# k-outer MFMA order in 32-MFMA phases (all k0 of both A blocks, then all k1; same-acc distance 16) on top of stack_i
# speedup vs baseline: 1.0025x; 1.0025x over previous
;     __host__ __device__ bool next(int i, Unit& u) const { const int t = i / 3, b = i - 3 * t; Unit v; if (!StaticOrder::next(t, v)) return false; u.pm = v.pm; u.pn = 8 * b + v.pn; return true; }
; #define PG8_LDA(dst, b, h) do { _Pragma("unroll") for (int m = 0; m < 4; ++m) _Pragma("unroll") for (int k = 0; k < 2; ++k) dst[m][k] = *(const PG8_LAS bf16x8*)(lds + PG8_SA(b, h) + aoff + m * 2048 + k * 1024); } while (0)
; template <class Epi, class Sched, bool ALIGN_EPI = false, bool SP2 = false>
; __device__ __forceinline__ void gemm_phase(PG8_LAS unsigned char* lds, const Gemm g, const Sched& S, const Epi& E, int tid_in) {
;     ...
;         const bool has_next = S.next(ui + 1, nxt);
;         const char* nA = has_next ? (const char*)g.A + (size_t)nxt.pm * tstepA + (g.grp ? (size_t)(nxt.pn / g.grp) * g.agrp : (size_t)0) : cA; const char* nB = has_next ? (const char*)g.Bt + (size_t)nxt.pn * tstepB : cB;
;         for (int t = 0; t < nt; t += 2) {
;             const bool last = (t == nt - 2);
;             const char* a1 = cA + (size_t)(t + 1) * kstep;
;             const char* a2 = last ? nA : cA + (size_t)(t + 2) * kstep; const char* b2 = last ? nB : cB + (size_t)(t + 2) * kstep;
;             const char* a3 = a2 + kstep; const char* b3 = b2 + kstep;
;             if (last && has_next) S.a_ready(nxt);
;             if constexpr (SP2) {
;             PG8_LDB(B0, 0, 0); PG8_LDB(B1, 0, 1); PG8_SCHED; PG8_LDA(At, 0, 0); PG8_STAGE(PG8_SA(1, 1), a1 + hstepA, voffA);
;             PG8_WAIT_V(8); PG8_WAIT_L(0); PG8_BAR; PG8_MMA(0, 0, At, B0); PG8_MMA(0, 1, At, B1); PG8_BAR; PG8_SCHED;
;             PG8_LDA(At, 0, 1); PG8_STAGE(PG8_SB(0, 0), b2, voffB); PG8_STAGE(PG8_SB(0, 1), b2 + hstepB, voffB); PG8_STAGE(PG8_SA(0, 0), a2, voffA);
;             PG8_WAIT_V(8); PG8_WAIT_L(0); PG8_BAR; PG8_MMA(1, 0, At, B0); PG8_MMA(1, 1, At, B1); PG8_BAR; PG8_SCHED;
;             PG8_LDB(B0, 1, 0); PG8_LDB(B1, 1, 1); PG8_SCHED; PG8_LDA(At, 1, 0); PG8_STAGE(PG8_SA(0, 1), a2 + hstepA, voffA);
;             PG8_WAIT_V(8); PG8_WAIT_L(0); PG8_BAR; PG8_MMA(0, 0, At, B0); PG8_MMA(0, 1, At, B1); PG8_BAR; PG8_SCHED;
;             PG8_LDA(At, 1, 1); PG8_STAGE(PG8_SB(1, 0), b3, voffB); PG8_STAGE(PG8_SB(1, 1), b3 + hstepB, voffB); PG8_STAGE(PG8_SA(1, 0), a3, voffA);
;             PG8_WAIT_V(8); PG8_WAIT_L(0); PG8_BAR; PG8_MMA(1, 0, At, B0); PG8_MMA(1, 1, At, B1); PG8_BAR; PG8_SCHED;
.LBB0_311:
	s_ashr_i32 s23, s22, 31
	s_lshl_b64 s[10:11], s[22:23], 20
	s_add_u32 s24, s4, s10
	s_addc_u32 s25, s26, s11
	s_and_b64 s[10:11], s[34:35], exec
	s_cselect_b32 s19, s24, s12
	s_ashr_i32 s15, s14, 31
	s_lshl_b64 s[10:11], s[14:15], 20
	s_add_u32 s10, s40, s10
	s_addc_u32 s11, s60, s11
	s_and_b64 s[20:21], s[34:35], exec
	s_cselect_b32 s15, s10, s16
	s_add_u32 s20, s16, 0x100
	v_mov_b32_e32 v2, 0
	s_addc_u32 s21, s17, 0
	s_mov_b32 s23, -2
	v_add_u32_e32 v0, 0x10000, v237
	ds_read_b128 v[130:133], v0
	ds_read_b128 v[134:137], v0 offset:1024
	ds_read_b128 v[138:141], v0 offset:2048
	ds_read_b128 v[142:145], v0 offset:3072
	v_add_u32_e32 v0, 0x14000, v237
	ds_read_b128 v[146:149], v0
	ds_read_b128 v[150:153], v0 offset:1024
	ds_read_b128 v[154:157], v0 offset:2048
	ds_read_b128 v[158:161], v0 offset:3072
	s_add_u32 s16, s12, 0x100
	s_addc_u32 s17, s13, 0
	s_sub_i32 s12, s12, s4
	s_add_i32 s12, s12, 0x80080
	s_sub_i32 s36, s12, 0x80000
	s_cmp_eq_u32 s23, 28
	s_cselect_b32 s13, s19, s16
	s_mov_b32 m0, s69
	ds_read_b128 v[162:165], v238
	ds_read_b128 v[166:169], v238 offset:1024
	ds_read_b128 v[170:173], v238 offset:2048
	ds_read_b128 v[174:177], v238 offset:3072
	ds_read_b128 v[178:181], v238 offset:4096
	ds_read_b128 v[182:185], v238 offset:5120
	ds_read_b128 v[186:189], v238 offset:6144
	ds_read_b128 v[190:193], v238 offset:7168
	s_mov_b32 m0, s78
	s_nop 0
	buffer_load_dwordx4 v211, s[4:7], s36 offen lds
	s_mov_b32 m0, s69
	s_nop 0
	buffer_load_dwordx4 v195, s[4:7], s12 offen lds
	s_mov_b32 m0, s67
	s_nop 0
	buffer_load_dwordx4 v211, s[4:7], s12 offen lds
	s_waitcnt vmcnt(8)
	s_waitcnt lgkmcnt(0)
	s_setprio 1
	s_barrier
	v_mfma_f32_16x16x32_bf16 v[126:129], v[130:133], v[162:165], 0
	v_mfma_f32_16x16x32_bf16 v[122:125], v[138:141], v[162:165], 0
	v_mfma_f32_16x16x32_bf16 v[106:109], v[138:141], v[170:173], 0
	v_mfma_f32_16x16x32_bf16 v[110:113], v[130:133], v[170:173], 0
	v_mfma_f32_16x16x32_bf16 v[94:97], v[130:133], v[178:181], 0
	v_mfma_f32_16x16x32_bf16 v[90:93], v[138:141], v[178:181], 0
	v_mfma_f32_16x16x32_bf16 v[74:77], v[138:141], v[186:189], 0
	v_mfma_f32_16x16x32_bf16 v[78:81], v[130:133], v[186:189], 0
	v_mfma_f32_16x16x32_bf16 v[126:129], v[134:137], v[166:169], v[126:129]
	v_mfma_f32_16x16x32_bf16 v[122:125], v[142:145], v[166:169], v[122:125]
	v_mfma_f32_16x16x32_bf16 v[106:109], v[142:145], v[174:177], v[106:109]
	v_mfma_f32_16x16x32_bf16 v[110:113], v[134:137], v[174:177], v[110:113]
	v_mfma_f32_16x16x32_bf16 v[94:97], v[134:137], v[182:185], v[94:97]
	v_mfma_f32_16x16x32_bf16 v[90:93], v[142:145], v[182:185], v[90:93]
	v_mfma_f32_16x16x32_bf16 v[74:77], v[142:145], v[190:193], v[74:77]
	v_mfma_f32_16x16x32_bf16 v[78:81], v[134:137], v[190:193], v[78:81]
	v_mfma_f32_16x16x32_bf16 v[118:121], v[146:149], v[162:165], 0
	v_mfma_f32_16x16x32_bf16 v[114:117], v[154:157], v[162:165], 0
	v_mfma_f32_16x16x32_bf16 v[98:101], v[154:157], v[170:173], 0
	v_mfma_f32_16x16x32_bf16 v[102:105], v[146:149], v[170:173], 0
	v_mfma_f32_16x16x32_bf16 v[86:89], v[146:149], v[178:181], 0
	v_mfma_f32_16x16x32_bf16 v[82:85], v[154:157], v[178:181], 0
	v_mfma_f32_16x16x32_bf16 v[66:69], v[154:157], v[186:189], 0
	v_mfma_f32_16x16x32_bf16 v[70:73], v[146:149], v[186:189], 0
	v_mfma_f32_16x16x32_bf16 v[118:121], v[150:153], v[166:169], v[118:121]
	v_mfma_f32_16x16x32_bf16 v[114:117], v[158:161], v[166:169], v[114:117]
	v_mfma_f32_16x16x32_bf16 v[98:101], v[158:161], v[174:177], v[98:101]
	v_mfma_f32_16x16x32_bf16 v[102:105], v[150:153], v[174:177], v[102:105]
	v_mfma_f32_16x16x32_bf16 v[86:89], v[150:153], v[182:185], v[86:89]
	v_mfma_f32_16x16x32_bf16 v[82:85], v[158:161], v[182:185], v[82:85]
	v_mfma_f32_16x16x32_bf16 v[66:69], v[158:161], v[190:193], v[66:69]
	v_mfma_f32_16x16x32_bf16 v[70:73], v[150:153], v[190:193], v[70:73]
	s_barrier
	s_setprio 0
	s_cselect_b32 s12, s15, s20
	s_mov_b32 m0, s61
	s_mov_b32 s42, s6
	s_mov_b32 s43, s7
	s_sub_i32 s12, s12, s40
	ds_read_b128 v[162:165], v238 offset:16384
	ds_read_b128 v[166:169], v238 offset:17408
	ds_read_b128 v[170:173], v238 offset:18432
	ds_read_b128 v[174:177], v238 offset:19456
	ds_read_b128 v[178:181], v238 offset:20480
	ds_read_b128 v[182:185], v238 offset:21504
	ds_read_b128 v[186:189], v238 offset:22528
	ds_read_b128 v[190:193], v238 offset:23552
	buffer_load_dwordx4 v207, s[40:43], s12 offen lds
	s_mov_b32 m0, s62
	s_add_i32 s36, s12, 0x80000
	buffer_load_dwordx4 v224, s[40:43], s12 offen lds
	s_mov_b32 m0, s63
	s_sub_i32 s13, s13, s4
	buffer_load_dwordx4 v207, s[40:43], s36 offen lds
	s_mov_b32 m0, s71
	s_nop 0
	buffer_load_dwordx4 v224, s[40:43], s36 offen lds
	s_mov_b32 m0, s53
	s_nop 0
	buffer_load_dwordx4 v195, s[4:7], s13 offen lds
	s_waitcnt vmcnt(7)
	s_waitcnt lgkmcnt(0)
	s_setprio 1
	s_barrier
; #define PG8_STAGE(bufoff, gbase, voff) do { const int so_ = (int)(unsigned)((const char*)(gbase) - base_##voff); _Pragma("unroll") for (int _i = 0; _i < 2; ++_i) \
;         __builtin_amdgcn_raw_ptr_buffer_load_lds(rs_##voff, (PG8_LAS unsigned*)(lds + (bufoff) + ldsw + _i * 8192), 16, (int)(voff)[_i], so_, 0, 0); } while (0)
; #define PG8_LDA(dst, b, h) do { _Pragma("unroll") for (int m = 0; m < 4; ++m) _Pragma("unroll") for (int k = 0; k < 2; ++k) dst[m][k] = *(const PG8_LAS bf16x8*)(lds + PG8_SA(b, h) + aoff + m * 2048 + k * 1024); } while (0)
; #define PG8_LDB(dst, b, h) do { _Pragma("unroll") for (int n = 0; n < 2; ++n) _Pragma("unroll") for (int k = 0; k < 2; ++k) dst[n][k] = *(const PG8_LAS bf16x8*)(lds + PG8_SB(b, h) + boff + n * 2048 + k * 1024); } while (0)
; #define PG8_MMA(ai, bj, At, Bt) do { __builtin_amdgcn_s_setprio(1); _Pragma("unroll") for (int m = 0; m < 4; ++m) _Pragma("unroll") for (int n = 0; n < 2; ++n) _Pragma("unroll") for (int k = 0; k < 2; ++k) \
;         acc[ai][bj][m][n] = __builtin_amdgcn_mfma_f32_16x16x32_bf16(Bt[n][k], At[m][k], acc[ai][bj][m][n], 0, 0, 0); __builtin_amdgcn_s_setprio(0); } while (0)
; template <class Epi, class Sched, bool ALIGN_EPI = false, bool SP2 = false>
; __device__ __forceinline__ void gemm_phase(PG8_LAS unsigned char* lds, const Gemm g, const Sched& S, const Epi& E, int tid_in) {
;     ...
;             PG8_LDB(B0, 0, 0); PG8_LDB(B1, 0, 1); PG8_SCHED; PG8_LDA(At, 0, 0); PG8_STAGE(PG8_SA(1, 1), a1 + hstepA, voffA);
;             PG8_WAIT_V(8); PG8_WAIT_L(0); PG8_BAR; PG8_MMA(0, 0, At, B0); PG8_MMA(0, 1, At, B1); PG8_BAR; PG8_SCHED;
;             PG8_LDA(At, 0, 1); PG8_STAGE(PG8_SB(0, 0), b2, voffB); PG8_STAGE(PG8_SB(0, 1), b2 + hstepB, voffB); PG8_STAGE(PG8_SA(0, 0), a2, voffA);
;             PG8_WAIT_V(8); PG8_WAIT_L(0); PG8_BAR; PG8_MMA(1, 0, At, B0); PG8_MMA(1, 1, At, B1); PG8_BAR; PG8_SCHED;
;             PG8_LDB(B0, 1, 0); PG8_LDB(B1, 1, 1); PG8_SCHED; PG8_LDA(At, 1, 0); PG8_STAGE(PG8_SA(0, 1), a2 + hstepA, voffA);
;             PG8_WAIT_V(8); PG8_WAIT_L(0); PG8_BAR; PG8_MMA(0, 0, At, B0); PG8_MMA(0, 1, At, B1); PG8_BAR; PG8_SCHED;
;             PG8_LDA(At, 1, 1); PG8_STAGE(PG8_SB(1, 0), b3, voffB); PG8_STAGE(PG8_SB(1, 1), b3 + hstepB, voffB); PG8_STAGE(PG8_SA(1, 0), a3, voffA);
;             PG8_WAIT_V(8); PG8_WAIT_L(0); PG8_BAR; PG8_MMA(1, 0, At, B0); PG8_MMA(1, 1, At, B1); PG8_BAR; PG8_SCHED;
	v_mfma_f32_16x16x32_bf16 v[62:65], v[130:133], v[162:165], 0
	v_mfma_f32_16x16x32_bf16 v[58:61], v[138:141], v[162:165], 0
	v_mfma_f32_16x16x32_bf16 v[42:45], v[138:141], v[170:173], 0
	v_mfma_f32_16x16x32_bf16 v[46:49], v[130:133], v[170:173], 0
	v_mfma_f32_16x16x32_bf16 v[30:33], v[130:133], v[178:181], 0
	v_mfma_f32_16x16x32_bf16 v[26:29], v[138:141], v[178:181], 0
	v_mfma_f32_16x16x32_bf16 v[10:13], v[138:141], v[186:189], 0
	v_mfma_f32_16x16x32_bf16 v[14:17], v[130:133], v[186:189], 0
	v_mfma_f32_16x16x32_bf16 v[62:65], v[134:137], v[166:169], v[62:65]
	v_mfma_f32_16x16x32_bf16 v[58:61], v[142:145], v[166:169], v[58:61]
	v_mfma_f32_16x16x32_bf16 v[42:45], v[142:145], v[174:177], v[42:45]
	v_mfma_f32_16x16x32_bf16 v[46:49], v[134:137], v[174:177], v[46:49]
	v_mfma_f32_16x16x32_bf16 v[30:33], v[134:137], v[182:185], v[30:33]
	v_mfma_f32_16x16x32_bf16 v[26:29], v[142:145], v[182:185], v[26:29]
	v_mfma_f32_16x16x32_bf16 v[10:13], v[142:145], v[190:193], v[10:13]
	v_mfma_f32_16x16x32_bf16 v[14:17], v[134:137], v[190:193], v[14:17]
	v_mfma_f32_16x16x32_bf16 v[54:57], v[146:149], v[162:165], 0
	v_mfma_f32_16x16x32_bf16 v[50:53], v[154:157], v[162:165], 0
	v_mfma_f32_16x16x32_bf16 v[34:37], v[154:157], v[170:173], 0
	v_mfma_f32_16x16x32_bf16 v[38:41], v[146:149], v[170:173], 0
	v_mfma_f32_16x16x32_bf16 v[22:25], v[146:149], v[178:181], 0
	v_mfma_f32_16x16x32_bf16 v[18:21], v[154:157], v[178:181], 0
	v_mfma_f32_16x16x32_bf16 v[2:5], v[154:157], v[186:189], 0
	v_mfma_f32_16x16x32_bf16 v[6:9], v[146:149], v[186:189], 0
	v_mfma_f32_16x16x32_bf16 v[54:57], v[150:153], v[166:169], v[54:57]
	v_mfma_f32_16x16x32_bf16 v[50:53], v[158:161], v[166:169], v[50:53]
	v_mfma_f32_16x16x32_bf16 v[34:37], v[158:161], v[174:177], v[34:37]
	v_mfma_f32_16x16x32_bf16 v[38:41], v[150:153], v[174:177], v[38:41]
	v_mfma_f32_16x16x32_bf16 v[22:25], v[150:153], v[182:185], v[22:25]
	v_mfma_f32_16x16x32_bf16 v[18:21], v[158:161], v[182:185], v[18:21]
	v_mfma_f32_16x16x32_bf16 v[2:5], v[158:161], v[190:193], v[2:5]
	v_mfma_f32_16x16x32_bf16 v[6:9], v[150:153], v[190:193], v[6:9]
	s_barrier
	s_setprio 0
	v_add_u32_e32 v0, 0x18000, v237
	ds_read_b128 v[130:133], v0
	ds_read_b128 v[134:137], v0 offset:1024
	ds_read_b128 v[138:141], v0 offset:2048
	ds_read_b128 v[142:145], v0 offset:3072
	v_add_u32_e32 v0, 0x1c000, v237
	ds_read_b128 v[146:149], v0
	ds_read_b128 v[150:153], v0 offset:1024
	ds_read_b128 v[154:157], v0 offset:2048
	ds_read_b128 v[158:161], v0 offset:3072
	s_add_i32 s36, s13, 0x80000
	s_mov_b32 m0, s73
	ds_read_b128 v[162:165], v238 offset:32768
	ds_read_b128 v[166:169], v238 offset:33792
	ds_read_b128 v[170:173], v238 offset:34816
	ds_read_b128 v[174:177], v238 offset:35840
	ds_read_b128 v[178:181], v238 offset:36864
	ds_read_b128 v[182:185], v238 offset:37888
	ds_read_b128 v[186:189], v238 offset:38912
	ds_read_b128 v[190:193], v238 offset:39936
	s_mov_b32 m0, s72
	s_nop 0
	buffer_load_dwordx4 v211, s[4:7], s13 offen lds
	s_mov_b32 m0, s73
	s_nop 0
	buffer_load_dwordx4 v195, s[4:7], s36 offen lds
	s_mov_b32 m0, s74
	s_nop 0
	buffer_load_dwordx4 v211, s[4:7], s36 offen lds
	s_waitcnt vmcnt(8)
	s_waitcnt lgkmcnt(0)
	s_setprio 1
	s_barrier
	v_mfma_f32_16x16x32_bf16 v[126:129], v[130:133], v[162:165], v[126:129]
	v_mfma_f32_16x16x32_bf16 v[122:125], v[138:141], v[162:165], v[122:125]
	v_mfma_f32_16x16x32_bf16 v[106:109], v[138:141], v[170:173], v[106:109]
	v_mfma_f32_16x16x32_bf16 v[110:113], v[130:133], v[170:173], v[110:113]
	v_mfma_f32_16x16x32_bf16 v[94:97], v[130:133], v[178:181], v[94:97]
	v_mfma_f32_16x16x32_bf16 v[90:93], v[138:141], v[178:181], v[90:93]
	v_mfma_f32_16x16x32_bf16 v[74:77], v[138:141], v[186:189], v[74:77]
	v_mfma_f32_16x16x32_bf16 v[78:81], v[130:133], v[186:189], v[78:81]
	v_mfma_f32_16x16x32_bf16 v[70:73], v[146:149], v[186:189], v[70:73]
	v_mfma_f32_16x16x32_bf16 v[66:69], v[154:157], v[186:189], v[66:69]
	v_mfma_f32_16x16x32_bf16 v[82:85], v[154:157], v[178:181], v[82:85]
	v_mfma_f32_16x16x32_bf16 v[86:89], v[146:149], v[178:181], v[86:89]
	v_mfma_f32_16x16x32_bf16 v[102:105], v[146:149], v[170:173], v[102:105]
	v_mfma_f32_16x16x32_bf16 v[98:101], v[154:157], v[170:173], v[98:101]
	v_mfma_f32_16x16x32_bf16 v[114:117], v[154:157], v[162:165], v[114:117]
	v_mfma_f32_16x16x32_bf16 v[118:121], v[146:149], v[162:165], v[118:121]
	v_mfma_f32_16x16x32_bf16 v[126:129], v[134:137], v[166:169], v[126:129]
	v_mfma_f32_16x16x32_bf16 v[122:125], v[142:145], v[166:169], v[122:125]
	v_mfma_f32_16x16x32_bf16 v[106:109], v[142:145], v[174:177], v[106:109]
	v_mfma_f32_16x16x32_bf16 v[110:113], v[134:137], v[174:177], v[110:113]
	v_mfma_f32_16x16x32_bf16 v[94:97], v[134:137], v[182:185], v[94:97]
	v_mfma_f32_16x16x32_bf16 v[90:93], v[142:145], v[182:185], v[90:93]
	v_mfma_f32_16x16x32_bf16 v[74:77], v[142:145], v[190:193], v[74:77]
	v_mfma_f32_16x16x32_bf16 v[78:81], v[134:137], v[190:193], v[78:81]
	v_mfma_f32_16x16x32_bf16 v[70:73], v[150:153], v[190:193], v[70:73]
	v_mfma_f32_16x16x32_bf16 v[66:69], v[158:161], v[190:193], v[66:69]
	v_mfma_f32_16x16x32_bf16 v[82:85], v[158:161], v[182:185], v[82:85]
	v_mfma_f32_16x16x32_bf16 v[86:89], v[150:153], v[182:185], v[86:89]
	v_mfma_f32_16x16x32_bf16 v[102:105], v[150:153], v[174:177], v[102:105]
	v_mfma_f32_16x16x32_bf16 v[98:101], v[158:161], v[174:177], v[98:101]
	v_mfma_f32_16x16x32_bf16 v[114:117], v[158:161], v[166:169], v[114:117]
	v_mfma_f32_16x16x32_bf16 v[118:121], v[150:153], v[166:169], v[118:121]
	s_barrier
; #define PG8_STAGE(bufoff, gbase, voff) do { const int so_ = (int)(unsigned)((const char*)(gbase) - base_##voff); _Pragma("unroll") for (int _i = 0; _i < 2; ++_i) \
;         __builtin_amdgcn_raw_ptr_buffer_load_lds(rs_##voff, (PG8_LAS unsigned*)(lds + (bufoff) + ldsw + _i * 8192), 16, (int)(voff)[_i], so_, 0, 0); } while (0)
; #define PG8_LDA(dst, b, h) do { _Pragma("unroll") for (int m = 0; m < 4; ++m) _Pragma("unroll") for (int k = 0; k < 2; ++k) dst[m][k] = *(const PG8_LAS bf16x8*)(lds + PG8_SA(b, h) + aoff + m * 2048 + k * 1024); } while (0)
; #define PG8_LDB(dst, b, h) do { _Pragma("unroll") for (int n = 0; n < 2; ++n) _Pragma("unroll") for (int k = 0; k < 2; ++k) dst[n][k] = *(const PG8_LAS bf16x8*)(lds + PG8_SB(b, h) + boff + n * 2048 + k * 1024); } while (0)
; #define PG8_MMA(ai, bj, At, Bt) do { __builtin_amdgcn_s_setprio(1); _Pragma("unroll") for (int m = 0; m < 4; ++m) _Pragma("unroll") for (int n = 0; n < 2; ++n) _Pragma("unroll") for (int k = 0; k < 2; ++k) \
;         acc[ai][bj][m][n] = __builtin_amdgcn_mfma_f32_16x16x32_bf16(Bt[n][k], At[m][k], acc[ai][bj][m][n], 0, 0, 0); __builtin_amdgcn_s_setprio(0); } while (0)
; template <class Epi, class Sched, bool ALIGN_EPI = false, bool SP2 = false>
; __device__ __forceinline__ void gemm_phase(PG8_LAS unsigned char* lds, const Gemm g, const Sched& S, const Epi& E, int tid_in) {
;     ...
;             PG8_LDB(B0, 0, 0); PG8_LDB(B1, 0, 1); PG8_SCHED; PG8_LDA(At, 0, 0); PG8_STAGE(PG8_SA(1, 1), a1 + hstepA, voffA);
;             PG8_WAIT_V(8); PG8_WAIT_L(0); PG8_BAR; PG8_MMA(0, 0, At, B0); PG8_MMA(0, 1, At, B1); PG8_BAR; PG8_SCHED;
;             PG8_LDA(At, 0, 1); PG8_STAGE(PG8_SB(0, 0), b2, voffB); PG8_STAGE(PG8_SB(0, 1), b2 + hstepB, voffB); PG8_STAGE(PG8_SA(0, 0), a2, voffA);
;             PG8_WAIT_V(8); PG8_WAIT_L(0); PG8_BAR; PG8_MMA(1, 0, At, B0); PG8_MMA(1, 1, At, B1); PG8_BAR; PG8_SCHED;
;             PG8_LDB(B0, 1, 0); PG8_LDB(B1, 1, 1); PG8_SCHED; PG8_LDA(At, 1, 0); PG8_STAGE(PG8_SA(0, 1), a2 + hstepA, voffA);
;             PG8_WAIT_V(8); PG8_WAIT_L(0); PG8_BAR; PG8_MMA(0, 0, At, B0); PG8_MMA(0, 1, At, B1); PG8_BAR; PG8_SCHED;
;             PG8_LDA(At, 1, 1); PG8_STAGE(PG8_SB(1, 0), b3, voffB); PG8_STAGE(PG8_SB(1, 1), b3 + hstepB, voffB); PG8_STAGE(PG8_SA(1, 0), a3, voffA);
;             PG8_WAIT_V(8); PG8_WAIT_L(0); PG8_BAR; PG8_MMA(1, 0, At, B0); PG8_MMA(1, 1, At, B1); PG8_BAR; PG8_SCHED;
	s_setprio 0
	s_mov_b32 m0, s75
	s_add_i32 s36, s12, 0x80
	ds_read_b128 v[162:165], v238 offset:49152
	ds_read_b128 v[166:169], v238 offset:50176
	ds_read_b128 v[170:173], v238 offset:51200
	ds_read_b128 v[174:177], v238 offset:52224
	ds_read_b128 v[178:181], v238 offset:53248
	ds_read_b128 v[182:185], v238 offset:54272
	ds_read_b128 v[186:189], v238 offset:55296
	ds_read_b128 v[190:193], v238 offset:56320
	buffer_load_dwordx4 v207, s[40:43], s36 offen lds
	s_mov_b32 m0, s76
	s_add_i32 s12, s12, 0x80080
	buffer_load_dwordx4 v224, s[40:43], s36 offen lds
	s_mov_b32 m0, s79
	s_addk_i32 s13, 0x80
	buffer_load_dwordx4 v207, s[40:43], s12 offen lds
	s_mov_b32 m0, s68
	s_nop 0
	buffer_load_dwordx4 v224, s[40:43], s12 offen lds
	s_mov_b32 m0, s77
	s_nop 0
	buffer_load_dwordx4 v195, s[4:7], s13 offen lds
	s_waitcnt vmcnt(7)
	s_waitcnt lgkmcnt(0)
	s_setprio 1
	s_barrier
	v_mfma_f32_16x16x32_bf16 v[62:65], v[130:133], v[162:165], v[62:65]
	v_mfma_f32_16x16x32_bf16 v[58:61], v[138:141], v[162:165], v[58:61]
	v_mfma_f32_16x16x32_bf16 v[42:45], v[138:141], v[170:173], v[42:45]
	v_mfma_f32_16x16x32_bf16 v[46:49], v[130:133], v[170:173], v[46:49]
	v_mfma_f32_16x16x32_bf16 v[30:33], v[130:133], v[178:181], v[30:33]
	v_mfma_f32_16x16x32_bf16 v[26:29], v[138:141], v[178:181], v[26:29]
	v_mfma_f32_16x16x32_bf16 v[10:13], v[138:141], v[186:189], v[10:13]
	v_mfma_f32_16x16x32_bf16 v[14:17], v[130:133], v[186:189], v[14:17]
	v_mfma_f32_16x16x32_bf16 v[6:9], v[146:149], v[186:189], v[6:9]
	v_mfma_f32_16x16x32_bf16 v[2:5], v[154:157], v[186:189], v[2:5]
	v_mfma_f32_16x16x32_bf16 v[18:21], v[154:157], v[178:181], v[18:21]
	v_mfma_f32_16x16x32_bf16 v[22:25], v[146:149], v[178:181], v[22:25]
	v_mfma_f32_16x16x32_bf16 v[38:41], v[146:149], v[170:173], v[38:41]
	v_mfma_f32_16x16x32_bf16 v[34:37], v[154:157], v[170:173], v[34:37]
	v_mfma_f32_16x16x32_bf16 v[50:53], v[154:157], v[162:165], v[50:53]
	v_mfma_f32_16x16x32_bf16 v[54:57], v[146:149], v[162:165], v[54:57]
	v_mfma_f32_16x16x32_bf16 v[62:65], v[134:137], v[166:169], v[62:65]
	v_mfma_f32_16x16x32_bf16 v[58:61], v[142:145], v[166:169], v[58:61]
	v_mfma_f32_16x16x32_bf16 v[42:45], v[142:145], v[174:177], v[42:45]
	v_mfma_f32_16x16x32_bf16 v[46:49], v[134:137], v[174:177], v[46:49]
	v_mfma_f32_16x16x32_bf16 v[30:33], v[134:137], v[182:185], v[30:33]
	v_mfma_f32_16x16x32_bf16 v[26:29], v[142:145], v[182:185], v[26:29]
	v_mfma_f32_16x16x32_bf16 v[10:13], v[142:145], v[190:193], v[10:13]
	v_mfma_f32_16x16x32_bf16 v[14:17], v[134:137], v[190:193], v[14:17]
	v_mfma_f32_16x16x32_bf16 v[6:9], v[150:153], v[190:193], v[6:9]
	v_mfma_f32_16x16x32_bf16 v[2:5], v[158:161], v[190:193], v[2:5]
	v_mfma_f32_16x16x32_bf16 v[18:21], v[158:161], v[182:185], v[18:21]
	v_mfma_f32_16x16x32_bf16 v[22:25], v[150:153], v[182:185], v[22:25]
	v_mfma_f32_16x16x32_bf16 v[38:41], v[150:153], v[174:177], v[38:41]
	v_mfma_f32_16x16x32_bf16 v[34:37], v[158:161], v[174:177], v[34:37]
	v_mfma_f32_16x16x32_bf16 v[50:53], v[158:161], v[166:169], v[50:53]
	v_mfma_f32_16x16x32_bf16 v[54:57], v[150:153], v[166:169], v[54:57]
	s_barrier
	s_setprio 0
	s_add_i32 s23, s23, 2
	s_add_u32 s20, s20, 0x100
	s_addc_u32 s21, s21, 0
	s_cmp_gt_u32 s23, 29
	s_mov_b64 s[12:13], s[16:17]
.LBB0_312:
	v_add_u32_e32 v0, 0x10000, v237
	ds_read_b128 v[130:133], v0
	ds_read_b128 v[134:137], v0 offset:1024
	ds_read_b128 v[138:141], v0 offset:2048
	ds_read_b128 v[142:145], v0 offset:3072
	v_add_u32_e32 v0, 0x14000, v237
	ds_read_b128 v[146:149], v0
	ds_read_b128 v[150:153], v0 offset:1024
	ds_read_b128 v[154:157], v0 offset:2048
	ds_read_b128 v[158:161], v0 offset:3072
	s_add_u32 s16, s12, 0x100
	s_addc_u32 s17, s13, 0
	s_sub_i32 s12, s12, s4
	s_add_i32 s12, s12, 0x80080
	s_sub_i32 s36, s12, 0x80000
	s_cmp_eq_u32 s23, 28
	s_cselect_b32 s13, s19, s16
	s_mov_b32 m0, s69
	ds_read_b128 v[162:165], v238
	ds_read_b128 v[166:169], v238 offset:1024
	ds_read_b128 v[170:173], v238 offset:2048
	ds_read_b128 v[174:177], v238 offset:3072
	ds_read_b128 v[178:181], v238 offset:4096
	ds_read_b128 v[182:185], v238 offset:5120
	ds_read_b128 v[186:189], v238 offset:6144
	ds_read_b128 v[190:193], v238 offset:7168
	s_mov_b32 m0, s78
	s_nop 0
	buffer_load_dwordx4 v211, s[4:7], s36 offen lds
	s_mov_b32 m0, s69
	s_nop 0
	buffer_load_dwordx4 v195, s[4:7], s12 offen lds
	s_mov_b32 m0, s67
	s_nop 0
	buffer_load_dwordx4 v211, s[4:7], s12 offen lds
	s_waitcnt vmcnt(8)
	s_waitcnt lgkmcnt(0)
	s_setprio 1
	s_barrier
	v_mfma_f32_16x16x32_bf16 v[126:129], v[130:133], v[162:165], v[126:129]
	v_mfma_f32_16x16x32_bf16 v[122:125], v[138:141], v[162:165], v[122:125]
	v_mfma_f32_16x16x32_bf16 v[106:109], v[138:141], v[170:173], v[106:109]
	v_mfma_f32_16x16x32_bf16 v[110:113], v[130:133], v[170:173], v[110:113]
	v_mfma_f32_16x16x32_bf16 v[94:97], v[130:133], v[178:181], v[94:97]
	v_mfma_f32_16x16x32_bf16 v[90:93], v[138:141], v[178:181], v[90:93]
	v_mfma_f32_16x16x32_bf16 v[74:77], v[138:141], v[186:189], v[74:77]
	v_mfma_f32_16x16x32_bf16 v[78:81], v[130:133], v[186:189], v[78:81]
	v_mfma_f32_16x16x32_bf16 v[70:73], v[146:149], v[186:189], v[70:73]
	v_mfma_f32_16x16x32_bf16 v[66:69], v[154:157], v[186:189], v[66:69]
	v_mfma_f32_16x16x32_bf16 v[82:85], v[154:157], v[178:181], v[82:85]
	v_mfma_f32_16x16x32_bf16 v[86:89], v[146:149], v[178:181], v[86:89]
	v_mfma_f32_16x16x32_bf16 v[102:105], v[146:149], v[170:173], v[102:105]
	v_mfma_f32_16x16x32_bf16 v[98:101], v[154:157], v[170:173], v[98:101]
	v_mfma_f32_16x16x32_bf16 v[114:117], v[154:157], v[162:165], v[114:117]
	v_mfma_f32_16x16x32_bf16 v[118:121], v[146:149], v[162:165], v[118:121]
	v_mfma_f32_16x16x32_bf16 v[126:129], v[134:137], v[166:169], v[126:129]
	v_mfma_f32_16x16x32_bf16 v[122:125], v[142:145], v[166:169], v[122:125]
	v_mfma_f32_16x16x32_bf16 v[106:109], v[142:145], v[174:177], v[106:109]
	v_mfma_f32_16x16x32_bf16 v[110:113], v[134:137], v[174:177], v[110:113]
	v_mfma_f32_16x16x32_bf16 v[94:97], v[134:137], v[182:185], v[94:97]
	v_mfma_f32_16x16x32_bf16 v[90:93], v[142:145], v[182:185], v[90:93]
	v_mfma_f32_16x16x32_bf16 v[74:77], v[142:145], v[190:193], v[74:77]
	v_mfma_f32_16x16x32_bf16 v[78:81], v[134:137], v[190:193], v[78:81]
	v_mfma_f32_16x16x32_bf16 v[70:73], v[150:153], v[190:193], v[70:73]
	v_mfma_f32_16x16x32_bf16 v[66:69], v[158:161], v[190:193], v[66:69]
	v_mfma_f32_16x16x32_bf16 v[82:85], v[158:161], v[182:185], v[82:85]
	v_mfma_f32_16x16x32_bf16 v[86:89], v[150:153], v[182:185], v[86:89]
	v_mfma_f32_16x16x32_bf16 v[102:105], v[150:153], v[174:177], v[102:105]
	v_mfma_f32_16x16x32_bf16 v[98:101], v[158:161], v[174:177], v[98:101]
	v_mfma_f32_16x16x32_bf16 v[114:117], v[158:161], v[166:169], v[114:117]
	v_mfma_f32_16x16x32_bf16 v[118:121], v[150:153], v[166:169], v[118:121]
	s_barrier
; #define PG8_STAGE(bufoff, gbase, voff) do { const int so_ = (int)(unsigned)((const char*)(gbase) - base_##voff); _Pragma("unroll") for (int _i = 0; _i < 2; ++_i) \
;         __builtin_amdgcn_raw_ptr_buffer_load_lds(rs_##voff, (PG8_LAS unsigned*)(lds + (bufoff) + ldsw + _i * 8192), 16, (int)(voff)[_i], so_, 0, 0); } while (0)
; #define PG8_LDA(dst, b, h) do { _Pragma("unroll") for (int m = 0; m < 4; ++m) _Pragma("unroll") for (int k = 0; k < 2; ++k) dst[m][k] = *(const PG8_LAS bf16x8*)(lds + PG8_SA(b, h) + aoff + m * 2048 + k * 1024); } while (0)
; #define PG8_LDB(dst, b, h) do { _Pragma("unroll") for (int n = 0; n < 2; ++n) _Pragma("unroll") for (int k = 0; k < 2; ++k) dst[n][k] = *(const PG8_LAS bf16x8*)(lds + PG8_SB(b, h) + boff + n * 2048 + k * 1024); } while (0)
; #define PG8_MMA(ai, bj, At, Bt) do { __builtin_amdgcn_s_setprio(1); _Pragma("unroll") for (int m = 0; m < 4; ++m) _Pragma("unroll") for (int n = 0; n < 2; ++n) _Pragma("unroll") for (int k = 0; k < 2; ++k) \
;         acc[ai][bj][m][n] = __builtin_amdgcn_mfma_f32_16x16x32_bf16(Bt[n][k], At[m][k], acc[ai][bj][m][n], 0, 0, 0); __builtin_amdgcn_s_setprio(0); } while (0)
; #define PG8_WAIT_V(n) asm volatile("s_waitcnt vmcnt(" #n ")" ::: "memory")
; #define PG8_WAIT_L(n) asm volatile("s_waitcnt lgkmcnt(" #n ")" ::: "memory")
; #define PG8_BAR __builtin_amdgcn_s_barrier()
; #define PG8_SCHED __builtin_amdgcn_sched_barrier(0)
; template <class Epi, class Sched, bool ALIGN_EPI = false, bool SP2 = false>
; __device__ __forceinline__ void gemm_phase(PG8_LAS unsigned char* lds, const Gemm g, const Sched& S, const Epi& E, int tid_in) {
;     ...
;             PG8_LDA(At, 0, 1); PG8_STAGE(PG8_SB(0, 0), b2, voffB); PG8_STAGE(PG8_SB(0, 1), b2 + hstepB, voffB); PG8_STAGE(PG8_SA(0, 0), a2, voffA);
;             PG8_WAIT_V(8); PG8_WAIT_L(0); PG8_BAR; PG8_MMA(1, 0, At, B0); PG8_MMA(1, 1, At, B1); PG8_BAR; PG8_SCHED;
;             PG8_LDB(B0, 1, 0); PG8_LDB(B1, 1, 1); PG8_SCHED; PG8_LDA(At, 1, 0); PG8_STAGE(PG8_SA(0, 1), a2 + hstepA, voffA);
;             PG8_WAIT_V(8); PG8_WAIT_L(0); PG8_BAR; PG8_MMA(0, 0, At, B0); PG8_MMA(0, 1, At, B1); PG8_BAR; PG8_SCHED;
	s_setprio 0
	s_cselect_b32 s12, s15, s20
	s_mov_b32 m0, s61
	s_mov_b32 s42, s6
	s_mov_b32 s43, s7
	s_sub_i32 s12, s12, s40
	ds_read_b128 v[162:165], v238 offset:16384
	ds_read_b128 v[166:169], v238 offset:17408
	ds_read_b128 v[170:173], v238 offset:18432
	ds_read_b128 v[174:177], v238 offset:19456
	ds_read_b128 v[178:181], v238 offset:20480
	ds_read_b128 v[182:185], v238 offset:21504
	ds_read_b128 v[186:189], v238 offset:22528
	ds_read_b128 v[190:193], v238 offset:23552
	buffer_load_dwordx4 v207, s[40:43], s12 offen lds
	s_mov_b32 m0, s62
	s_add_i32 s36, s12, 0x80000
	buffer_load_dwordx4 v224, s[40:43], s12 offen lds
	s_mov_b32 m0, s63
	s_sub_i32 s13, s13, s4
	buffer_load_dwordx4 v207, s[40:43], s36 offen lds
	s_mov_b32 m0, s71
	s_nop 0
	buffer_load_dwordx4 v224, s[40:43], s36 offen lds
	s_mov_b32 m0, s53
	s_nop 0
	buffer_load_dwordx4 v195, s[4:7], s13 offen lds
	s_waitcnt vmcnt(7)
	s_waitcnt lgkmcnt(0)
	s_setprio 1
	s_barrier
	v_mfma_f32_16x16x32_bf16 v[62:65], v[130:133], v[162:165], v[62:65]
	v_mfma_f32_16x16x32_bf16 v[58:61], v[138:141], v[162:165], v[58:61]
	v_mfma_f32_16x16x32_bf16 v[42:45], v[138:141], v[170:173], v[42:45]
	v_mfma_f32_16x16x32_bf16 v[46:49], v[130:133], v[170:173], v[46:49]
	v_mfma_f32_16x16x32_bf16 v[30:33], v[130:133], v[178:181], v[30:33]
	v_mfma_f32_16x16x32_bf16 v[26:29], v[138:141], v[178:181], v[26:29]
	v_mfma_f32_16x16x32_bf16 v[10:13], v[138:141], v[186:189], v[10:13]
	v_mfma_f32_16x16x32_bf16 v[14:17], v[130:133], v[186:189], v[14:17]
	v_mfma_f32_16x16x32_bf16 v[6:9], v[146:149], v[186:189], v[6:9]
	v_mfma_f32_16x16x32_bf16 v[2:5], v[154:157], v[186:189], v[2:5]
	v_mfma_f32_16x16x32_bf16 v[18:21], v[154:157], v[178:181], v[18:21]
	v_mfma_f32_16x16x32_bf16 v[22:25], v[146:149], v[178:181], v[22:25]
	v_mfma_f32_16x16x32_bf16 v[38:41], v[146:149], v[170:173], v[38:41]
	v_mfma_f32_16x16x32_bf16 v[34:37], v[154:157], v[170:173], v[34:37]
	v_mfma_f32_16x16x32_bf16 v[50:53], v[154:157], v[162:165], v[50:53]
	v_mfma_f32_16x16x32_bf16 v[54:57], v[146:149], v[162:165], v[54:57]
	v_mfma_f32_16x16x32_bf16 v[62:65], v[134:137], v[166:169], v[62:65]
	v_mfma_f32_16x16x32_bf16 v[58:61], v[142:145], v[166:169], v[58:61]
	v_mfma_f32_16x16x32_bf16 v[42:45], v[142:145], v[174:177], v[42:45]
	v_mfma_f32_16x16x32_bf16 v[46:49], v[134:137], v[174:177], v[46:49]
	v_mfma_f32_16x16x32_bf16 v[30:33], v[134:137], v[182:185], v[30:33]
	v_mfma_f32_16x16x32_bf16 v[26:29], v[142:145], v[182:185], v[26:29]
	v_mfma_f32_16x16x32_bf16 v[10:13], v[142:145], v[190:193], v[10:13]
	v_mfma_f32_16x16x32_bf16 v[14:17], v[134:137], v[190:193], v[14:17]
	v_mfma_f32_16x16x32_bf16 v[6:9], v[150:153], v[190:193], v[6:9]
	v_mfma_f32_16x16x32_bf16 v[2:5], v[158:161], v[190:193], v[2:5]
	v_mfma_f32_16x16x32_bf16 v[18:21], v[158:161], v[182:185], v[18:21]
	v_mfma_f32_16x16x32_bf16 v[22:25], v[150:153], v[182:185], v[22:25]
	v_mfma_f32_16x16x32_bf16 v[38:41], v[150:153], v[174:177], v[38:41]
	v_mfma_f32_16x16x32_bf16 v[34:37], v[158:161], v[174:177], v[34:37]
	v_mfma_f32_16x16x32_bf16 v[50:53], v[158:161], v[166:169], v[50:53]
	v_mfma_f32_16x16x32_bf16 v[54:57], v[150:153], v[166:169], v[54:57]
	s_barrier
	s_setprio 0
	v_add_u32_e32 v0, 0x18000, v237
	ds_read_b128 v[130:133], v0
	ds_read_b128 v[134:137], v0 offset:1024
	ds_read_b128 v[138:141], v0 offset:2048
	ds_read_b128 v[142:145], v0 offset:3072
	v_add_u32_e32 v0, 0x1c000, v237
	ds_read_b128 v[146:149], v0
	ds_read_b128 v[150:153], v0 offset:1024
	ds_read_b128 v[154:157], v0 offset:2048
	ds_read_b128 v[158:161], v0 offset:3072
	s_add_i32 s36, s13, 0x80000
	s_mov_b32 m0, s73
	ds_read_b128 v[162:165], v238 offset:32768
	ds_read_b128 v[166:169], v238 offset:33792
	ds_read_b128 v[170:173], v238 offset:34816
	ds_read_b128 v[174:177], v238 offset:35840
	ds_read_b128 v[178:181], v238 offset:36864
	ds_read_b128 v[182:185], v238 offset:37888
	ds_read_b128 v[186:189], v238 offset:38912
	ds_read_b128 v[190:193], v238 offset:39936
	s_mov_b32 m0, s72
	s_nop 0
	buffer_load_dwordx4 v211, s[4:7], s13 offen lds
	s_mov_b32 m0, s73
	s_nop 0
	buffer_load_dwordx4 v195, s[4:7], s36 offen lds
	s_mov_b32 m0, s74
	s_nop 0
	buffer_load_dwordx4 v211, s[4:7], s36 offen lds
	s_waitcnt vmcnt(8)
	s_waitcnt lgkmcnt(0)
	s_setprio 1
	s_barrier
; #define PG8_STAGE(bufoff, gbase, voff) do { const int so_ = (int)(unsigned)((const char*)(gbase) - base_##voff); _Pragma("unroll") for (int _i = 0; _i < 2; ++_i) \
;         __builtin_amdgcn_raw_ptr_buffer_load_lds(rs_##voff, (PG8_LAS unsigned*)(lds + (bufoff) + ldsw + _i * 8192), 16, (int)(voff)[_i], so_, 0, 0); } while (0)
; #define PG8_LDA(dst, b, h) do { _Pragma("unroll") for (int m = 0; m < 4; ++m) _Pragma("unroll") for (int k = 0; k < 2; ++k) dst[m][k] = *(const PG8_LAS bf16x8*)(lds + PG8_SA(b, h) + aoff + m * 2048 + k * 1024); } while (0)
; #define PG8_MMA(ai, bj, At, Bt) do { __builtin_amdgcn_s_setprio(1); _Pragma("unroll") for (int m = 0; m < 4; ++m) _Pragma("unroll") for (int n = 0; n < 2; ++n) _Pragma("unroll") for (int k = 0; k < 2; ++k) \
;         acc[ai][bj][m][n] = __builtin_amdgcn_mfma_f32_16x16x32_bf16(Bt[n][k], At[m][k], acc[ai][bj][m][n], 0, 0, 0); __builtin_amdgcn_s_setprio(0); } while (0)
; #define PG8_WAIT_V(n) asm volatile("s_waitcnt vmcnt(" #n ")" ::: "memory")
; #define PG8_WAIT_L(n) asm volatile("s_waitcnt lgkmcnt(" #n ")" ::: "memory")
; #define PG8_BAR __builtin_amdgcn_s_barrier()
; #define PG8_SCHED __builtin_amdgcn_sched_barrier(0)
; template <class Epi, class Sched, bool ALIGN_EPI = false, bool SP2 = false>
; __device__ __forceinline__ void gemm_phase(PG8_LAS unsigned char* lds, const Gemm g, const Sched& S, const Epi& E, int tid_in) {
;     ...
;             PG8_WAIT_V(8); PG8_WAIT_L(0); PG8_BAR; PG8_MMA(0, 0, At, B0); PG8_MMA(0, 1, At, B1); PG8_BAR; PG8_SCHED;
;             PG8_LDA(At, 1, 1); PG8_STAGE(PG8_SB(1, 0), b3, voffB); PG8_STAGE(PG8_SB(1, 1), b3 + hstepB, voffB); PG8_STAGE(PG8_SA(1, 0), a3, voffA);
;             PG8_WAIT_V(8); PG8_WAIT_L(0); PG8_BAR; PG8_MMA(1, 0, At, B0); PG8_MMA(1, 1, At, B1); PG8_BAR; PG8_SCHED;
;     ...
;         if constexpr (ALIGN_EPI) { if (wr == 0) PG8_BAR; }
	v_mfma_f32_16x16x32_bf16 v[126:129], v[130:133], v[162:165], v[126:129]
	v_mfma_f32_16x16x32_bf16 v[122:125], v[138:141], v[162:165], v[122:125]
	v_mfma_f32_16x16x32_bf16 v[106:109], v[138:141], v[170:173], v[106:109]
	v_mfma_f32_16x16x32_bf16 v[110:113], v[130:133], v[170:173], v[110:113]
	v_mfma_f32_16x16x32_bf16 v[94:97], v[130:133], v[178:181], v[94:97]
	v_mfma_f32_16x16x32_bf16 v[90:93], v[138:141], v[178:181], v[90:93]
	v_mfma_f32_16x16x32_bf16 v[74:77], v[138:141], v[186:189], v[74:77]
	v_mfma_f32_16x16x32_bf16 v[78:81], v[130:133], v[186:189], v[78:81]
	v_mfma_f32_16x16x32_bf16 v[70:73], v[146:149], v[186:189], v[70:73]
	v_mfma_f32_16x16x32_bf16 v[66:69], v[154:157], v[186:189], v[66:69]
	v_mfma_f32_16x16x32_bf16 v[82:85], v[154:157], v[178:181], v[82:85]
	v_mfma_f32_16x16x32_bf16 v[86:89], v[146:149], v[178:181], v[86:89]
	v_mfma_f32_16x16x32_bf16 v[102:105], v[146:149], v[170:173], v[102:105]
	v_mfma_f32_16x16x32_bf16 v[98:101], v[154:157], v[170:173], v[98:101]
	v_mfma_f32_16x16x32_bf16 v[114:117], v[154:157], v[162:165], v[114:117]
	v_mfma_f32_16x16x32_bf16 v[118:121], v[146:149], v[162:165], v[118:121]
	v_mfma_f32_16x16x32_bf16 v[126:129], v[134:137], v[166:169], v[126:129]
	v_mfma_f32_16x16x32_bf16 v[122:125], v[142:145], v[166:169], v[122:125]
	v_mfma_f32_16x16x32_bf16 v[106:109], v[142:145], v[174:177], v[106:109]
	v_mfma_f32_16x16x32_bf16 v[110:113], v[134:137], v[174:177], v[110:113]
	v_mfma_f32_16x16x32_bf16 v[94:97], v[134:137], v[182:185], v[94:97]
	v_mfma_f32_16x16x32_bf16 v[90:93], v[142:145], v[182:185], v[90:93]
	v_mfma_f32_16x16x32_bf16 v[74:77], v[142:145], v[190:193], v[74:77]
	v_mfma_f32_16x16x32_bf16 v[78:81], v[134:137], v[190:193], v[78:81]
	v_mfma_f32_16x16x32_bf16 v[70:73], v[150:153], v[190:193], v[70:73]
	v_mfma_f32_16x16x32_bf16 v[66:69], v[158:161], v[190:193], v[66:69]
	v_mfma_f32_16x16x32_bf16 v[82:85], v[158:161], v[182:185], v[82:85]
	v_mfma_f32_16x16x32_bf16 v[86:89], v[150:153], v[182:185], v[86:89]
	v_mfma_f32_16x16x32_bf16 v[102:105], v[150:153], v[174:177], v[102:105]
	v_mfma_f32_16x16x32_bf16 v[98:101], v[158:161], v[174:177], v[98:101]
	v_mfma_f32_16x16x32_bf16 v[114:117], v[158:161], v[166:169], v[114:117]
	v_mfma_f32_16x16x32_bf16 v[118:121], v[150:153], v[166:169], v[118:121]
	s_barrier
	s_setprio 0
	s_mov_b32 m0, s75
	s_add_i32 s36, s12, 0x80
	ds_read_b128 v[162:165], v238 offset:49152
	ds_read_b128 v[166:169], v238 offset:50176
	ds_read_b128 v[170:173], v238 offset:51200
	ds_read_b128 v[174:177], v238 offset:52224
	ds_read_b128 v[178:181], v238 offset:53248
	ds_read_b128 v[182:185], v238 offset:54272
	ds_read_b128 v[186:189], v238 offset:55296
	ds_read_b128 v[190:193], v238 offset:56320
	buffer_load_dwordx4 v207, s[40:43], s36 offen lds
	s_mov_b32 m0, s76
	s_add_i32 s12, s12, 0x80080
	buffer_load_dwordx4 v224, s[40:43], s36 offen lds
	s_mov_b32 m0, s79
	s_addk_i32 s13, 0x80
	buffer_load_dwordx4 v207, s[40:43], s12 offen lds
	s_mov_b32 m0, s68
	s_nop 0
	buffer_load_dwordx4 v224, s[40:43], s12 offen lds
	s_mov_b32 m0, s77
	s_nop 0
	buffer_load_dwordx4 v195, s[4:7], s13 offen lds
	s_waitcnt vmcnt(7)
	s_waitcnt lgkmcnt(0)
	s_setprio 1
	s_barrier
	v_mfma_f32_16x16x32_bf16 v[62:65], v[130:133], v[162:165], v[62:65]
	v_mfma_f32_16x16x32_bf16 v[58:61], v[138:141], v[162:165], v[58:61]
	v_mfma_f32_16x16x32_bf16 v[42:45], v[138:141], v[170:173], v[42:45]
	v_mfma_f32_16x16x32_bf16 v[46:49], v[130:133], v[170:173], v[46:49]
	v_mfma_f32_16x16x32_bf16 v[30:33], v[130:133], v[178:181], v[30:33]
	v_mfma_f32_16x16x32_bf16 v[26:29], v[138:141], v[178:181], v[26:29]
	v_mfma_f32_16x16x32_bf16 v[10:13], v[138:141], v[186:189], v[10:13]
	v_mfma_f32_16x16x32_bf16 v[14:17], v[130:133], v[186:189], v[14:17]
	v_mfma_f32_16x16x32_bf16 v[6:9], v[146:149], v[186:189], v[6:9]
	v_mfma_f32_16x16x32_bf16 v[2:5], v[154:157], v[186:189], v[2:5]
	v_mfma_f32_16x16x32_bf16 v[18:21], v[154:157], v[178:181], v[18:21]
	v_mfma_f32_16x16x32_bf16 v[22:25], v[146:149], v[178:181], v[22:25]
	v_mfma_f32_16x16x32_bf16 v[38:41], v[146:149], v[170:173], v[38:41]
	v_mfma_f32_16x16x32_bf16 v[34:37], v[154:157], v[170:173], v[34:37]
	v_mfma_f32_16x16x32_bf16 v[50:53], v[154:157], v[162:165], v[50:53]
	v_mfma_f32_16x16x32_bf16 v[54:57], v[146:149], v[162:165], v[54:57]
	v_mfma_f32_16x16x32_bf16 v[62:65], v[134:137], v[166:169], v[62:65]
	v_mfma_f32_16x16x32_bf16 v[58:61], v[142:145], v[166:169], v[58:61]
	v_mfma_f32_16x16x32_bf16 v[42:45], v[142:145], v[174:177], v[42:45]
	v_mfma_f32_16x16x32_bf16 v[46:49], v[134:137], v[174:177], v[46:49]
	v_mfma_f32_16x16x32_bf16 v[30:33], v[134:137], v[182:185], v[30:33]
	v_mfma_f32_16x16x32_bf16 v[26:29], v[142:145], v[182:185], v[26:29]
	v_mfma_f32_16x16x32_bf16 v[10:13], v[142:145], v[190:193], v[10:13]
	v_mfma_f32_16x16x32_bf16 v[14:17], v[134:137], v[190:193], v[14:17]
	v_mfma_f32_16x16x32_bf16 v[6:9], v[150:153], v[190:193], v[6:9]
	v_mfma_f32_16x16x32_bf16 v[2:5], v[158:161], v[190:193], v[2:5]
	v_mfma_f32_16x16x32_bf16 v[18:21], v[158:161], v[182:185], v[18:21]
	v_mfma_f32_16x16x32_bf16 v[22:25], v[150:153], v[182:185], v[22:25]
	v_mfma_f32_16x16x32_bf16 v[38:41], v[150:153], v[174:177], v[38:41]
	v_mfma_f32_16x16x32_bf16 v[34:37], v[158:161], v[174:177], v[34:37]
	v_mfma_f32_16x16x32_bf16 v[50:53], v[158:161], v[166:169], v[50:53]
	v_mfma_f32_16x16x32_bf16 v[54:57], v[150:153], v[166:169], v[54:57]
	s_barrier
	s_setprio 0
	s_add_i32 s23, s23, 2
	s_add_u32 s20, s20, 0x100
	s_addc_u32 s21, s21, 0
	s_cmp_gt_u32 s23, 29
	s_mov_b64 s[12:13], s[16:17]
	s_cbranch_scc0 .LBB0_312
	s_and_b64 vcc, exec, s[48:49]
	s_cbranch_vccz .LBB0_315
	s_barrier

; #define PG8_STAGE(bufoff, gbase, voff) do { const int so_ = (int)(unsigned)((const char*)(gbase) - base_##voff); _Pragma("unroll") for (int _i = 0; _i < 2; ++_i) \
;         __builtin_amdgcn_raw_ptr_buffer_load_lds(rs_##voff, (PG8_LAS unsigned*)(lds + (bufoff) + ldsw + _i * 8192), 16, (int)(voff)[_i], so_, 0, 0); } while (0)
; #define PG8_LDA(dst, b, h) do { _Pragma("unroll") for (int m = 0; m < 4; ++m) _Pragma("unroll") for (int k = 0; k < 2; ++k) dst[m][k] = *(const PG8_LAS bf16x8*)(lds + PG8_SA(b, h) + aoff + m * 2048 + k * 1024); } while (0)
; #define PG8_LDB(dst, b, h) do { _Pragma("unroll") for (int n = 0; n < 2; ++n) _Pragma("unroll") for (int k = 0; k < 2; ++k) dst[n][k] = *(const PG8_LAS bf16x8*)(lds + PG8_SB(b, h) + boff + n * 2048 + k * 1024); } while (0)
; #define PG8_MMA(ai, bj, At, Bt) do { __builtin_amdgcn_s_setprio(1); _Pragma("unroll") for (int m = 0; m < 4; ++m) _Pragma("unroll") for (int n = 0; n < 2; ++n) _Pragma("unroll") for (int k = 0; k < 2; ++k) \
;         acc[ai][bj][m][n] = __builtin_amdgcn_mfma_f32_16x16x32_bf16(Bt[n][k], At[m][k], acc[ai][bj][m][n], 0, 0, 0); __builtin_amdgcn_s_setprio(0); } while (0)
; #define PG8_WAIT_V(n) asm volatile("s_waitcnt vmcnt(" #n ")" ::: "memory")
; #define PG8_WAIT_L(n) asm volatile("s_waitcnt lgkmcnt(" #n ")" ::: "memory")
; #define PG8_BAR __builtin_amdgcn_s_barrier()
; #define PG8_SCHED __builtin_amdgcn_sched_barrier(0)
; template <class Epi, class Sched, bool ALIGN_EPI = false, bool SP2 = false>
; __device__ __forceinline__ void gemm_phase(PG8_LAS unsigned char* lds, const Gemm g, const Sched& S, const Epi& E, int tid_in) {
;     ...
;             PG8_LDB(B0, 0, 0); PG8_LDB(B1, 0, 1); PG8_SCHED; PG8_LDA(At, 0, 0); PG8_STAGE(PG8_SA(1, 1), a1 + hstepA, voffA);
;             PG8_WAIT_V(8); PG8_WAIT_L(0); PG8_BAR; PG8_MMA(0, 0, At, B0); PG8_MMA(0, 1, At, B1); PG8_BAR; PG8_SCHED;
;             PG8_LDA(At, 0, 1); PG8_STAGE(PG8_SB(0, 0), b2, voffB); PG8_STAGE(PG8_SB(0, 1), b2 + hstepB, voffB); PG8_STAGE(PG8_SA(0, 0), a2, voffA);
;             PG8_WAIT_V(8); PG8_WAIT_L(0); PG8_BAR; PG8_MMA(1, 0, At, B0); PG8_MMA(1, 1, At, B1); PG8_BAR; PG8_SCHED;
.LBB0_1037:
	v_add_u32_e32 v0, 0x10000, v236
	ds_read_b128 v[132:135], v0
	ds_read_b128 v[136:139], v0 offset:1024
	ds_read_b128 v[140:143], v0 offset:2048
	ds_read_b128 v[144:147], v0 offset:3072
	v_add_u32_e32 v0, 0x14000, v236
	ds_read_b128 v[148:151], v0
	ds_read_b128 v[152:155], v0 offset:1024
	ds_read_b128 v[156:159], v0 offset:2048
	ds_read_b128 v[160:163], v0 offset:3072
	s_add_u32 s16, s12, 0x100
	s_addc_u32 s17, s13, 0
	s_sub_i32 s12, s12, s4
	s_add_i32 s12, s12, 0xc0080
	s_sub_i32 s39, s12, 0xc0000
	s_cmp_eq_u32 s38, 12
	s_cselect_b32 s13, s24, s16
	s_mov_b32 m0, s76
	ds_read_b128 v[164:167], v237
	ds_read_b128 v[168:171], v237 offset:1024
	ds_read_b128 v[172:175], v237 offset:2048
	ds_read_b128 v[176:179], v237 offset:3072
	ds_read_b128 v[180:183], v237 offset:4096
	ds_read_b128 v[184:187], v237 offset:5120
	ds_read_b128 v[188:191], v237 offset:6144
	ds_read_b128 v[192:195], v237 offset:7168
	s_mov_b32 m0, s73
	s_nop 0
	buffer_load_dwordx4 v222, s[4:7], s39 offen lds
	s_mov_b32 m0, s76
	s_nop 0
	buffer_load_dwordx4 v220, s[4:7], s12 offen lds
	s_mov_b32 m0, s77
	s_nop 0
	buffer_load_dwordx4 v222, s[4:7], s12 offen lds
	s_waitcnt vmcnt(8)
	s_waitcnt lgkmcnt(0)
	s_setprio 1
	s_barrier
	v_mfma_f32_16x16x32_bf16 v[128:131], v[132:135], v[164:167], v[128:131]
	v_mfma_f32_16x16x32_bf16 v[124:127], v[140:143], v[164:167], v[124:127]
	v_mfma_f32_16x16x32_bf16 v[116:119], v[140:143], v[172:175], v[116:119]
	v_mfma_f32_16x16x32_bf16 v[120:123], v[132:135], v[172:175], v[120:123]
	v_mfma_f32_16x16x32_bf16 v[112:115], v[132:135], v[180:183], v[112:115]
	v_mfma_f32_16x16x32_bf16 v[108:111], v[140:143], v[180:183], v[108:111]
	v_mfma_f32_16x16x32_bf16 v[100:103], v[140:143], v[188:191], v[100:103]
	v_mfma_f32_16x16x32_bf16 v[104:107], v[132:135], v[188:191], v[104:107]
	v_mfma_f32_16x16x32_bf16 v[72:75], v[148:151], v[188:191], v[72:75]
	v_mfma_f32_16x16x32_bf16 v[68:71], v[156:159], v[188:191], v[68:71]
	v_mfma_f32_16x16x32_bf16 v[76:79], v[156:159], v[180:183], v[76:79]
	v_mfma_f32_16x16x32_bf16 v[80:83], v[148:151], v[180:183], v[80:83]
	v_mfma_f32_16x16x32_bf16 v[88:91], v[148:151], v[172:175], v[88:91]
	v_mfma_f32_16x16x32_bf16 v[84:87], v[156:159], v[172:175], v[84:87]
	v_mfma_f32_16x16x32_bf16 v[92:95], v[156:159], v[164:167], v[92:95]
	v_mfma_f32_16x16x32_bf16 v[96:99], v[148:151], v[164:167], v[96:99]
	v_mfma_f32_16x16x32_bf16 v[128:131], v[136:139], v[168:171], v[128:131]
	v_mfma_f32_16x16x32_bf16 v[124:127], v[144:147], v[168:171], v[124:127]
	v_mfma_f32_16x16x32_bf16 v[116:119], v[144:147], v[176:179], v[116:119]
	v_mfma_f32_16x16x32_bf16 v[120:123], v[136:139], v[176:179], v[120:123]
	v_mfma_f32_16x16x32_bf16 v[112:115], v[136:139], v[184:187], v[112:115]
	v_mfma_f32_16x16x32_bf16 v[108:111], v[144:147], v[184:187], v[108:111]
	v_mfma_f32_16x16x32_bf16 v[100:103], v[144:147], v[192:195], v[100:103]
	v_mfma_f32_16x16x32_bf16 v[104:107], v[136:139], v[192:195], v[104:107]
	v_mfma_f32_16x16x32_bf16 v[72:75], v[152:155], v[192:195], v[72:75]
	v_mfma_f32_16x16x32_bf16 v[68:71], v[160:163], v[192:195], v[68:71]
	v_mfma_f32_16x16x32_bf16 v[76:79], v[160:163], v[184:187], v[76:79]
	v_mfma_f32_16x16x32_bf16 v[80:83], v[152:155], v[184:187], v[80:83]
	v_mfma_f32_16x16x32_bf16 v[88:91], v[152:155], v[176:179], v[88:91]
	v_mfma_f32_16x16x32_bf16 v[84:87], v[160:163], v[176:179], v[84:87]
	v_mfma_f32_16x16x32_bf16 v[92:95], v[160:163], v[168:171], v[92:95]
	v_mfma_f32_16x16x32_bf16 v[96:99], v[152:155], v[168:171], v[96:99]
	s_barrier
	s_setprio 0
	s_cselect_b32 s12, s18, s19
	s_mov_b32 m0, s26
	s_mov_b32 s46, s6
	s_mov_b32 s47, s7
	s_sub_i32 s12, s12, s44
	ds_read_b128 v[164:167], v237 offset:16384
	ds_read_b128 v[168:171], v237 offset:17408
	ds_read_b128 v[172:175], v237 offset:18432
	ds_read_b128 v[176:179], v237 offset:19456
	ds_read_b128 v[180:183], v237 offset:20480
	ds_read_b128 v[184:187], v237 offset:21504
	ds_read_b128 v[188:191], v237 offset:22528
	ds_read_b128 v[192:195], v237 offset:23552
	buffer_load_dwordx4 v221, s[44:47], s12 offen lds
	s_mov_b32 m0, s53
	s_add_i32 s39, s12, 0x40000
	buffer_load_dwordx4 v223, s[44:47], s12 offen lds
	s_mov_b32 m0, s60
	s_sub_i32 s13, s13, s4
	buffer_load_dwordx4 v221, s[44:47], s39 offen lds
	s_mov_b32 m0, s61
	s_nop 0
	buffer_load_dwordx4 v223, s[44:47], s39 offen lds
	s_mov_b32 m0, s21
	s_nop 0
	buffer_load_dwordx4 v220, s[4:7], s13 offen lds
	s_waitcnt vmcnt(7)
	s_waitcnt lgkmcnt(0)
	s_setprio 1
	s_barrier
	v_mfma_f32_16x16x32_bf16 v[64:67], v[132:135], v[164:167], v[64:67]
	v_mfma_f32_16x16x32_bf16 v[60:63], v[140:143], v[164:167], v[60:63]
	v_mfma_f32_16x16x32_bf16 v[52:55], v[140:143], v[172:175], v[52:55]
	v_mfma_f32_16x16x32_bf16 v[56:59], v[132:135], v[172:175], v[56:59]
	v_mfma_f32_16x16x32_bf16 v[48:51], v[132:135], v[180:183], v[48:51]
	v_mfma_f32_16x16x32_bf16 v[44:47], v[140:143], v[180:183], v[44:47]
	v_mfma_f32_16x16x32_bf16 v[36:39], v[140:143], v[188:191], v[36:39]
	v_mfma_f32_16x16x32_bf16 v[40:43], v[132:135], v[188:191], v[40:43]
	v_mfma_f32_16x16x32_bf16 v[64:67], v[136:139], v[168:171], v[64:67]
	v_mfma_f32_16x16x32_bf16 v[60:63], v[144:147], v[168:171], v[60:63]
	v_mfma_f32_16x16x32_bf16 v[52:55], v[144:147], v[176:179], v[52:55]
	v_mfma_f32_16x16x32_bf16 v[56:59], v[136:139], v[176:179], v[56:59]
	v_mfma_f32_16x16x32_bf16 v[48:51], v[136:139], v[184:187], v[48:51]
	v_mfma_f32_16x16x32_bf16 v[44:47], v[144:147], v[184:187], v[44:47]
	v_mfma_f32_16x16x32_bf16 v[36:39], v[144:147], v[192:195], v[36:39]
	v_mfma_f32_16x16x32_bf16 v[40:43], v[136:139], v[192:195], v[40:43]
	v_mfma_f32_16x16x32_bf16 v[32:35], v[148:151], v[164:167], v[32:35]
	v_mfma_f32_16x16x32_bf16 v[28:31], v[156:159], v[164:167], v[28:31]
	v_mfma_f32_16x16x32_bf16 v[20:23], v[156:159], v[172:175], v[20:23]
	v_mfma_f32_16x16x32_bf16 v[24:27], v[148:151], v[172:175], v[24:27]
	v_mfma_f32_16x16x32_bf16 v[16:19], v[148:151], v[180:183], v[16:19]
	v_mfma_f32_16x16x32_bf16 v[12:15], v[156:159], v[180:183], v[12:15]
	v_mfma_f32_16x16x32_bf16 v[2:5], v[156:159], v[188:191], v[4:7]
	v_mfma_f32_16x16x32_bf16 v[8:11], v[148:151], v[188:191], v[8:11]
	v_mfma_f32_16x16x32_bf16 v[32:35], v[152:155], v[168:171], v[32:35]
	v_mfma_f32_16x16x32_bf16 v[28:31], v[160:163], v[168:171], v[28:31]
	v_mfma_f32_16x16x32_bf16 v[20:23], v[160:163], v[176:179], v[20:23]
	v_mfma_f32_16x16x32_bf16 v[24:27], v[152:155], v[176:179], v[24:27]
	v_mfma_f32_16x16x32_bf16 v[16:19], v[152:155], v[184:187], v[16:19]
	v_mfma_f32_16x16x32_bf16 v[12:15], v[160:163], v[184:187], v[12:15]
	v_mfma_f32_16x16x32_bf16 v[2:5], v[160:163], v[192:195], v[2:5]
	v_mfma_f32_16x16x32_bf16 v[8:11], v[152:155], v[192:195], v[8:11]
	s_barrier
; #define PG8_STAGE(bufoff, gbase, voff) do { const int so_ = (int)(unsigned)((const char*)(gbase) - base_##voff); _Pragma("unroll") for (int _i = 0; _i < 2; ++_i) \
;         __builtin_amdgcn_raw_ptr_buffer_load_lds(rs_##voff, (PG8_LAS unsigned*)(lds + (bufoff) + ldsw + _i * 8192), 16, (int)(voff)[_i], so_, 0, 0); } while (0)
; #define PG8_LDA(dst, b, h) do { _Pragma("unroll") for (int m = 0; m < 4; ++m) _Pragma("unroll") for (int k = 0; k < 2; ++k) dst[m][k] = *(const PG8_LAS bf16x8*)(lds + PG8_SA(b, h) + aoff + m * 2048 + k * 1024); } while (0)
; #define PG8_LDB(dst, b, h) do { _Pragma("unroll") for (int n = 0; n < 2; ++n) _Pragma("unroll") for (int k = 0; k < 2; ++k) dst[n][k] = *(const PG8_LAS bf16x8*)(lds + PG8_SB(b, h) + boff + n * 2048 + k * 1024); } while (0)
; #define PG8_MMA(ai, bj, At, Bt) do { __builtin_amdgcn_s_setprio(1); _Pragma("unroll") for (int m = 0; m < 4; ++m) _Pragma("unroll") for (int n = 0; n < 2; ++n) _Pragma("unroll") for (int k = 0; k < 2; ++k) \
;         acc[ai][bj][m][n] = __builtin_amdgcn_mfma_f32_16x16x32_bf16(Bt[n][k], At[m][k], acc[ai][bj][m][n], 0, 0, 0); __builtin_amdgcn_s_setprio(0); } while (0)
; #define PG8_WAIT_V(n) asm volatile("s_waitcnt vmcnt(" #n ")" ::: "memory")
; #define PG8_WAIT_L(n) asm volatile("s_waitcnt lgkmcnt(" #n ")" ::: "memory")
; #define PG8_BAR __builtin_amdgcn_s_barrier()
; #define PG8_SCHED __builtin_amdgcn_sched_barrier(0)
; template <class Epi, class Sched, bool ALIGN_EPI = false, bool SP2 = false>
; __device__ __forceinline__ void gemm_phase(PG8_LAS unsigned char* lds, const Gemm g, const Sched& S, const Epi& E, int tid_in) {
;     ...
;             PG8_LDB(B0, 1, 0); PG8_LDB(B1, 1, 1); PG8_SCHED; PG8_LDA(At, 1, 0); PG8_STAGE(PG8_SA(0, 1), a2 + hstepA, voffA);
;             PG8_WAIT_V(8); PG8_WAIT_L(0); PG8_BAR; PG8_MMA(0, 0, At, B0); PG8_MMA(0, 1, At, B1); PG8_BAR; PG8_SCHED;
;             PG8_LDA(At, 1, 1); PG8_STAGE(PG8_SB(1, 0), b3, voffB); PG8_STAGE(PG8_SB(1, 1), b3 + hstepB, voffB); PG8_STAGE(PG8_SA(1, 0), a3, voffA);
;             PG8_WAIT_V(8); PG8_WAIT_L(0); PG8_BAR; PG8_MMA(1, 0, At, B0); PG8_MMA(1, 1, At, B1); PG8_BAR; PG8_SCHED;
	s_setprio 0
	v_add_u32_e32 v0, 0x18000, v236
	ds_read_b128 v[132:135], v0
	ds_read_b128 v[136:139], v0 offset:1024
	ds_read_b128 v[140:143], v0 offset:2048
	ds_read_b128 v[144:147], v0 offset:3072
	v_add_u32_e32 v0, 0x1c000, v236
	ds_read_b128 v[148:151], v0
	ds_read_b128 v[152:155], v0 offset:1024
	ds_read_b128 v[156:159], v0 offset:2048
	ds_read_b128 v[160:163], v0 offset:3072
	s_add_i32 s39, s13, 0xc0000
	s_mov_b32 m0, s63
	ds_read_b128 v[164:167], v237 offset:32768
	ds_read_b128 v[168:171], v237 offset:33792
	ds_read_b128 v[172:175], v237 offset:34816
	ds_read_b128 v[176:179], v237 offset:35840
	ds_read_b128 v[180:183], v237 offset:36864
	ds_read_b128 v[184:187], v237 offset:37888
	ds_read_b128 v[188:191], v237 offset:38912
	ds_read_b128 v[192:195], v237 offset:39936
	s_mov_b32 m0, s62
	s_nop 0
	buffer_load_dwordx4 v222, s[4:7], s13 offen lds
	s_mov_b32 m0, s63
	s_nop 0
	buffer_load_dwordx4 v220, s[4:7], s39 offen lds
	s_mov_b32 m0, s66
	s_nop 0
	buffer_load_dwordx4 v222, s[4:7], s39 offen lds
	s_waitcnt vmcnt(8)
	s_waitcnt lgkmcnt(0)
	s_setprio 1
	s_barrier
	v_mfma_f32_16x16x32_bf16 v[128:131], v[132:135], v[164:167], v[128:131]
	v_mfma_f32_16x16x32_bf16 v[124:127], v[140:143], v[164:167], v[124:127]
	v_mfma_f32_16x16x32_bf16 v[116:119], v[140:143], v[172:175], v[116:119]
	v_mfma_f32_16x16x32_bf16 v[120:123], v[132:135], v[172:175], v[120:123]
	v_mfma_f32_16x16x32_bf16 v[112:115], v[132:135], v[180:183], v[112:115]
	v_mfma_f32_16x16x32_bf16 v[108:111], v[140:143], v[180:183], v[108:111]
	v_mfma_f32_16x16x32_bf16 v[100:103], v[140:143], v[188:191], v[100:103]
	v_mfma_f32_16x16x32_bf16 v[104:107], v[132:135], v[188:191], v[104:107]
	v_mfma_f32_16x16x32_bf16 v[72:75], v[148:151], v[188:191], v[72:75]
	v_mfma_f32_16x16x32_bf16 v[68:71], v[156:159], v[188:191], v[68:71]
	v_mfma_f32_16x16x32_bf16 v[76:79], v[156:159], v[180:183], v[76:79]
	v_mfma_f32_16x16x32_bf16 v[80:83], v[148:151], v[180:183], v[80:83]
	v_mfma_f32_16x16x32_bf16 v[88:91], v[148:151], v[172:175], v[88:91]
	v_mfma_f32_16x16x32_bf16 v[84:87], v[156:159], v[172:175], v[84:87]
	v_mfma_f32_16x16x32_bf16 v[92:95], v[156:159], v[164:167], v[92:95]
	v_mfma_f32_16x16x32_bf16 v[96:99], v[148:151], v[164:167], v[96:99]
	v_mfma_f32_16x16x32_bf16 v[128:131], v[136:139], v[168:171], v[128:131]
	v_mfma_f32_16x16x32_bf16 v[124:127], v[144:147], v[168:171], v[124:127]
	v_mfma_f32_16x16x32_bf16 v[116:119], v[144:147], v[176:179], v[116:119]
	v_mfma_f32_16x16x32_bf16 v[120:123], v[136:139], v[176:179], v[120:123]
	v_mfma_f32_16x16x32_bf16 v[112:115], v[136:139], v[184:187], v[112:115]
	v_mfma_f32_16x16x32_bf16 v[108:111], v[144:147], v[184:187], v[108:111]
	v_mfma_f32_16x16x32_bf16 v[100:103], v[144:147], v[192:195], v[100:103]
	v_mfma_f32_16x16x32_bf16 v[104:107], v[136:139], v[192:195], v[104:107]
	v_mfma_f32_16x16x32_bf16 v[72:75], v[152:155], v[192:195], v[72:75]
	v_mfma_f32_16x16x32_bf16 v[68:71], v[160:163], v[192:195], v[68:71]
	v_mfma_f32_16x16x32_bf16 v[76:79], v[160:163], v[184:187], v[76:79]
	v_mfma_f32_16x16x32_bf16 v[80:83], v[152:155], v[184:187], v[80:83]
	v_mfma_f32_16x16x32_bf16 v[88:91], v[152:155], v[176:179], v[88:91]
	v_mfma_f32_16x16x32_bf16 v[84:87], v[160:163], v[176:179], v[84:87]
	v_mfma_f32_16x16x32_bf16 v[92:95], v[160:163], v[168:171], v[92:95]
	v_mfma_f32_16x16x32_bf16 v[96:99], v[152:155], v[168:171], v[96:99]
	s_barrier
	s_setprio 0
	s_mov_b32 m0, s69
	s_add_i32 s39, s12, 0x80
	ds_read_b128 v[164:167], v237 offset:49152
	ds_read_b128 v[168:171], v237 offset:50176
	ds_read_b128 v[172:175], v237 offset:51200
	ds_read_b128 v[176:179], v237 offset:52224
	ds_read_b128 v[180:183], v237 offset:53248
	ds_read_b128 v[184:187], v237 offset:54272
	ds_read_b128 v[188:191], v237 offset:55296
	ds_read_b128 v[192:195], v237 offset:56320
	buffer_load_dwordx4 v221, s[44:47], s39 offen lds
	s_mov_b32 m0, s71
	s_add_i32 s12, s12, 0x40080
	buffer_load_dwordx4 v223, s[44:47], s39 offen lds
	s_mov_b32 m0, s74
	s_addk_i32 s13, 0x80
	buffer_load_dwordx4 v221, s[44:47], s12 offen lds
	s_mov_b32 m0, s75
	s_nop 0
	buffer_load_dwordx4 v223, s[44:47], s12 offen lds
	s_mov_b32 m0, s72
	s_nop 0
	buffer_load_dwordx4 v220, s[4:7], s13 offen lds
	s_waitcnt vmcnt(7)
	s_waitcnt lgkmcnt(0)
	s_setprio 1
	s_barrier
	v_mfma_f32_16x16x32_bf16 v[64:67], v[132:135], v[164:167], v[64:67]
	v_mfma_f32_16x16x32_bf16 v[60:63], v[140:143], v[164:167], v[60:63]
	v_mfma_f32_16x16x32_bf16 v[52:55], v[140:143], v[172:175], v[52:55]
	v_mfma_f32_16x16x32_bf16 v[56:59], v[132:135], v[172:175], v[56:59]
	v_mfma_f32_16x16x32_bf16 v[48:51], v[132:135], v[180:183], v[48:51]
	v_mfma_f32_16x16x32_bf16 v[44:47], v[140:143], v[180:183], v[44:47]
	v_mfma_f32_16x16x32_bf16 v[36:39], v[140:143], v[188:191], v[36:39]
	v_mfma_f32_16x16x32_bf16 v[40:43], v[132:135], v[188:191], v[40:43]
	v_mfma_f32_16x16x32_bf16 v[64:67], v[136:139], v[168:171], v[64:67]
	v_mfma_f32_16x16x32_bf16 v[60:63], v[144:147], v[168:171], v[60:63]
	v_mfma_f32_16x16x32_bf16 v[52:55], v[144:147], v[176:179], v[52:55]
	v_mfma_f32_16x16x32_bf16 v[56:59], v[136:139], v[176:179], v[56:59]
	v_mfma_f32_16x16x32_bf16 v[48:51], v[136:139], v[184:187], v[48:51]
	v_mfma_f32_16x16x32_bf16 v[44:47], v[144:147], v[184:187], v[44:47]
	v_mfma_f32_16x16x32_bf16 v[36:39], v[144:147], v[192:195], v[36:39]
	v_mfma_f32_16x16x32_bf16 v[40:43], v[136:139], v[192:195], v[40:43]
	v_mfma_f32_16x16x32_bf16 v[32:35], v[148:151], v[164:167], v[32:35]
	v_mfma_f32_16x16x32_bf16 v[28:31], v[156:159], v[164:167], v[28:31]
	v_mfma_f32_16x16x32_bf16 v[20:23], v[156:159], v[172:175], v[20:23]
	v_mfma_f32_16x16x32_bf16 v[24:27], v[148:151], v[172:175], v[24:27]
	v_mfma_f32_16x16x32_bf16 v[16:19], v[148:151], v[180:183], v[16:19]
	v_mfma_f32_16x16x32_bf16 v[12:15], v[156:159], v[180:183], v[12:15]
	v_mfma_f32_16x16x32_bf16 v[2:5], v[156:159], v[188:191], v[2:5]
	v_mfma_f32_16x16x32_bf16 v[6:9], v[148:151], v[188:191], v[8:11]
	v_mfma_f32_16x16x32_bf16 v[32:35], v[152:155], v[168:171], v[32:35]
	v_mfma_f32_16x16x32_bf16 v[28:31], v[160:163], v[168:171], v[28:31]
	v_mfma_f32_16x16x32_bf16 v[20:23], v[160:163], v[176:179], v[20:23]
	v_mfma_f32_16x16x32_bf16 v[24:27], v[152:155], v[176:179], v[24:27]
	v_mfma_f32_16x16x32_bf16 v[16:19], v[152:155], v[184:187], v[16:19]
	v_mfma_f32_16x16x32_bf16 v[12:15], v[160:163], v[184:187], v[12:15]
	v_mfma_f32_16x16x32_bf16 v[8:11], v[152:155], v[192:195], v[6:9]
	v_mfma_f32_16x16x32_bf16 v[4:7], v[160:163], v[192:195], v[2:5]
	s_barrier
	s_setprio 0
	s_add_i32 s38, s38, 2
	s_add_u32 s19, s19, 0x100
	s_addc_u32 s23, s23, 0
	s_cmp_gt_u32 s38, 13
	s_mov_b64 s[12:13], s[16:17]
	s_cbranch_scc0 .LBB0_1037
	s_and_b64 vcc, exec, s[14:15]
	s_cbranch_vccz .LBB0_1040
	s_barrier

; #define PG8_STAGE(bufoff, gbase, voff) do { const int so_ = (int)(unsigned)((const char*)(gbase) - base_##voff); _Pragma("unroll") for (int _i = 0; _i < 2; ++_i) \
;         __builtin_amdgcn_raw_ptr_buffer_load_lds(rs_##voff, (PG8_LAS unsigned*)(lds + (bufoff) + ldsw + _i * 8192), 16, (int)(voff)[_i], so_, 0, 0); } while (0)
; #define PG8_LDA(dst, b, h) do { _Pragma("unroll") for (int m = 0; m < 4; ++m) _Pragma("unroll") for (int k = 0; k < 2; ++k) dst[m][k] = *(const PG8_LAS bf16x8*)(lds + PG8_SA(b, h) + aoff + m * 2048 + k * 1024); } while (0)
; #define PG8_LDB(dst, b, h) do { _Pragma("unroll") for (int n = 0; n < 2; ++n) _Pragma("unroll") for (int k = 0; k < 2; ++k) dst[n][k] = *(const PG8_LAS bf16x8*)(lds + PG8_SB(b, h) + boff + n * 2048 + k * 1024); } while (0)
; #define PG8_MMA(ai, bj, At, Bt) do { __builtin_amdgcn_s_setprio(1); _Pragma("unroll") for (int m = 0; m < 4; ++m) _Pragma("unroll") for (int n = 0; n < 2; ++n) _Pragma("unroll") for (int k = 0; k < 2; ++k) \
;         acc[ai][bj][m][n] = __builtin_amdgcn_mfma_f32_16x16x32_bf16(Bt[n][k], At[m][k], acc[ai][bj][m][n], 0, 0, 0); __builtin_amdgcn_s_setprio(0); } while (0)
; #define PG8_WAIT_V(n) asm volatile("s_waitcnt vmcnt(" #n ")" ::: "memory")
; #define PG8_WAIT_L(n) asm volatile("s_waitcnt lgkmcnt(" #n ")" ::: "memory")
; #define PG8_BAR __builtin_amdgcn_s_barrier()
; #define PG8_SCHED __builtin_amdgcn_sched_barrier(0)
; template <class Epi, class Sched, bool ALIGN_EPI = false, bool SP2 = false>
; __device__ __forceinline__ void gemm_phase(PG8_LAS unsigned char* lds, const Gemm g, const Sched& S, const Epi& E, int tid_in) {
;     ...
;             PG8_LDB(B0, 0, 0); PG8_LDB(B1, 0, 1); PG8_SCHED; PG8_LDA(At, 0, 0); PG8_STAGE(PG8_SA(1, 1), a1 + hstepA, voffA);
;             PG8_WAIT_V(8); PG8_WAIT_L(0); PG8_BAR; PG8_MMA(0, 0, At, B0); PG8_MMA(0, 1, At, B1); PG8_BAR; PG8_SCHED;
;             PG8_LDA(At, 0, 1); PG8_STAGE(PG8_SB(0, 0), b2, voffB); PG8_STAGE(PG8_SB(0, 1), b2 + hstepB, voffB); PG8_STAGE(PG8_SA(0, 0), a2, voffA);
;             PG8_WAIT_V(8); PG8_WAIT_L(0); PG8_BAR; PG8_MMA(1, 0, At, B0); PG8_MMA(1, 1, At, B1); PG8_BAR; PG8_SCHED;
.LBB0_1265:
	v_add_u32_e32 v133, 0x10000, v131
	ds_read_b128 v[134:137], v133
	ds_read_b128 v[138:141], v133 offset:1024
	ds_read_b128 v[142:145], v133 offset:2048
	ds_read_b128 v[146:149], v133 offset:3072
	v_add_u32_e32 v133, 0x14000, v131
	ds_read_b128 v[150:153], v133
	ds_read_b128 v[154:157], v133 offset:1024
	ds_read_b128 v[158:161], v133 offset:2048
	ds_read_b128 v[166:169], v133 offset:3072
	s_add_i32 s42, s18, s44
	s_add_i32 s21, s14, s44
	s_add_i32 s79, s12, s44
	s_addk_i32 s42, 0xff80
	s_sub_i32 vcc_lo, s42, 0x80000
	s_cmp_eq_u32 s19, 28
	s_cselect_b32 s21, s15, s21
	s_mov_b32 m0, s75
	ds_read_b128 v[170:173], v132
	ds_read_b128 v[174:177], v132 offset:1024
	ds_read_b128 v[178:181], v132 offset:2048
	ds_read_b128 v[182:185], v132 offset:3072
	ds_read_b128 v[186:189], v132 offset:4096
	ds_read_b128 v[190:193], v132 offset:5120
	ds_read_b128 v[200:203], v132 offset:6144
	ds_read_b128 v[206:209], v132 offset:7168
	s_mov_b32 m0, s72
	s_nop 0
	buffer_load_dwordx4 v130, s[4:7], vcc_lo offen lds
	s_mov_b32 m0, s75
	s_nop 0
	buffer_load_dwordx4 v0, s[4:7], s42 offen lds
	s_mov_b32 m0, s76
	s_nop 0
	buffer_load_dwordx4 v130, s[4:7], s42 offen lds
	s_waitcnt vmcnt(8)
	s_waitcnt lgkmcnt(0)
	s_setprio 1
	s_barrier
	v_mfma_f32_16x16x32_bf16 v[34:37], v[134:137], v[170:173], v[34:37]
	v_mfma_f32_16x16x32_bf16 v[18:21], v[142:145], v[170:173], v[18:21]
	v_mfma_f32_16x16x32_bf16 v[78:81], v[142:145], v[178:181], v[78:81]
	v_mfma_f32_16x16x32_bf16 v[86:89], v[134:137], v[178:181], v[86:89]
	v_mfma_f32_16x16x32_bf16 v[106:109], v[134:137], v[186:189], v[106:109]
	v_mfma_f32_16x16x32_bf16 v[102:105], v[142:145], v[186:189], v[102:105]
	v_mfma_f32_16x16x32_bf16 v[122:125], v[142:145], v[200:203], v[122:125]
	v_mfma_f32_16x16x32_bf16 v[126:129], v[134:137], v[200:203], v[126:129]
	v_mfma_f32_16x16x32_bf16 v[118:121], v[150:153], v[200:203], v[118:121]
	v_mfma_f32_16x16x32_bf16 v[114:117], v[158:161], v[200:203], v[114:117]
	v_mfma_f32_16x16x32_bf16 v[110:113], v[158:161], v[186:189], v[110:113]
	v_mfma_f32_16x16x32_bf16 v[98:101], v[150:153], v[186:189], v[98:101]
	v_mfma_f32_16x16x32_bf16 v[74:77], v[150:153], v[178:181], v[74:77]
	v_mfma_f32_16x16x32_bf16 v[90:93], v[158:161], v[178:181], v[90:93]
	v_mfma_f32_16x16x32_bf16 v[38:41], v[158:161], v[170:173], v[38:41]
	v_mfma_f32_16x16x32_bf16 v[14:17], v[150:153], v[170:173], v[14:17]
	v_mfma_f32_16x16x32_bf16 v[34:37], v[138:141], v[174:177], v[34:37]
	v_mfma_f32_16x16x32_bf16 v[18:21], v[146:149], v[174:177], v[18:21]
	v_mfma_f32_16x16x32_bf16 v[78:81], v[146:149], v[182:185], v[78:81]
	v_mfma_f32_16x16x32_bf16 v[86:89], v[138:141], v[182:185], v[86:89]
	v_mfma_f32_16x16x32_bf16 v[106:109], v[138:141], v[190:193], v[106:109]
	v_mfma_f32_16x16x32_bf16 v[102:105], v[146:149], v[190:193], v[102:105]
	v_mfma_f32_16x16x32_bf16 v[122:125], v[146:149], v[206:209], v[122:125]
	v_mfma_f32_16x16x32_bf16 v[126:129], v[138:141], v[206:209], v[126:129]
	v_mfma_f32_16x16x32_bf16 v[118:121], v[154:157], v[206:209], v[118:121]
	v_mfma_f32_16x16x32_bf16 v[114:117], v[166:169], v[206:209], v[114:117]
	v_mfma_f32_16x16x32_bf16 v[110:113], v[166:169], v[190:193], v[110:113]
	v_mfma_f32_16x16x32_bf16 v[98:101], v[154:157], v[190:193], v[98:101]
	v_mfma_f32_16x16x32_bf16 v[74:77], v[154:157], v[182:185], v[74:77]
	v_mfma_f32_16x16x32_bf16 v[90:93], v[166:169], v[182:185], v[90:93]
	v_mfma_f32_16x16x32_bf16 v[38:41], v[166:169], v[174:177], v[38:41]
	v_mfma_f32_16x16x32_bf16 v[14:17], v[154:157], v[174:177], v[14:17]
	s_barrier
	s_setprio 0
	s_cselect_b32 s79, s17, s79
	s_mov_b32 m0, s49
	s_mov_b32 s42, s6
	s_mov_b32 s43, s7
	s_sub_i32 s79, s79, s40
	ds_read_b128 v[170:173], v132 offset:16384
	ds_read_b128 v[174:177], v132 offset:17408
	ds_read_b128 v[178:181], v132 offset:18432
	ds_read_b128 v[182:185], v132 offset:19456
	ds_read_b128 v[186:189], v132 offset:20480
	ds_read_b128 v[190:193], v132 offset:21504
	ds_read_b128 v[200:203], v132 offset:22528
	ds_read_b128 v[206:209], v132 offset:23552
	buffer_load_dwordx4 v0, s[40:43], s79 offen lds
	s_mov_b32 m0, s60
	s_add_i32 vcc_lo, s79, 0x80000
	buffer_load_dwordx4 v130, s[40:43], s79 offen lds
	s_mov_b32 m0, s61
	s_sub_i32 s21, s21, s4
	buffer_load_dwordx4 v0, s[40:43], vcc_lo offen lds
	s_mov_b32 m0, s62
	s_nop 0
	buffer_load_dwordx4 v130, s[40:43], vcc_lo offen lds
	s_mov_b32 m0, s35
	s_nop 0
	buffer_load_dwordx4 v0, s[4:7], s21 offen lds
	s_waitcnt vmcnt(7)
	s_waitcnt lgkmcnt(0)
	s_setprio 1
	s_barrier
	v_mfma_f32_16x16x32_bf16 v[50:53], v[134:137], v[170:173], v[50:53]
	v_mfma_f32_16x16x32_bf16 v[30:33], v[142:145], v[170:173], v[30:33]
	v_mfma_f32_16x16x32_bf16 v[58:61], v[142:145], v[178:181], v[58:61]
	v_mfma_f32_16x16x32_bf16 v[62:65], v[134:137], v[178:181], v[62:65]
	v_mfma_f32_16x16x32_bf16 v[94:97], v[134:137], v[186:189], v[94:97]
	v_mfma_f32_16x16x32_bf16 v[82:85], v[142:145], v[186:189], v[82:85]
	v_mfma_f32_16x16x32_bf16 v[26:29], v[142:145], v[200:203], v[26:29]
	v_mfma_f32_16x16x32_bf16 v[46:49], v[134:137], v[200:203], v[46:49]
	v_mfma_f32_16x16x32_bf16 v[6:9], v[150:153], v[200:203], v[6:9]
	v_mfma_f32_16x16x32_bf16 v[2:5], v[158:161], v[200:203], v[2:5]
	v_mfma_f32_16x16x32_bf16 v[42:45], v[158:161], v[186:189], v[42:45]
	v_mfma_f32_16x16x32_bf16 v[70:73], v[150:153], v[186:189], v[70:73]
	v_mfma_f32_16x16x32_bf16 v[54:57], v[150:153], v[178:181], v[54:57]
	v_mfma_f32_16x16x32_bf16 v[66:69], v[158:161], v[178:181], v[66:69]
	v_mfma_f32_16x16x32_bf16 v[10:13], v[158:161], v[170:173], v[10:13]
	v_mfma_f32_16x16x32_bf16 v[22:25], v[150:153], v[170:173], v[22:25]
	v_mfma_f32_16x16x32_bf16 v[50:53], v[138:141], v[174:177], v[50:53]
	v_mfma_f32_16x16x32_bf16 v[30:33], v[146:149], v[174:177], v[30:33]
	v_mfma_f32_16x16x32_bf16 v[58:61], v[146:149], v[182:185], v[58:61]
	v_mfma_f32_16x16x32_bf16 v[62:65], v[138:141], v[182:185], v[62:65]
	v_mfma_f32_16x16x32_bf16 v[94:97], v[138:141], v[190:193], v[94:97]
	v_mfma_f32_16x16x32_bf16 v[82:85], v[146:149], v[190:193], v[82:85]
	v_mfma_f32_16x16x32_bf16 v[26:29], v[146:149], v[206:209], v[26:29]
	v_mfma_f32_16x16x32_bf16 v[46:49], v[138:141], v[206:209], v[46:49]
	v_mfma_f32_16x16x32_bf16 v[6:9], v[154:157], v[206:209], v[6:9]
	v_mfma_f32_16x16x32_bf16 v[2:5], v[166:169], v[206:209], v[2:5]
	v_mfma_f32_16x16x32_bf16 v[42:45], v[166:169], v[190:193], v[42:45]
	v_mfma_f32_16x16x32_bf16 v[70:73], v[154:157], v[190:193], v[70:73]
	v_mfma_f32_16x16x32_bf16 v[54:57], v[154:157], v[182:185], v[54:57]
	v_mfma_f32_16x16x32_bf16 v[66:69], v[166:169], v[182:185], v[66:69]
	v_mfma_f32_16x16x32_bf16 v[10:13], v[166:169], v[174:177], v[10:13]
	v_mfma_f32_16x16x32_bf16 v[22:25], v[154:157], v[174:177], v[22:25]
	s_barrier
; #define PG8_STAGE(bufoff, gbase, voff) do { const int so_ = (int)(unsigned)((const char*)(gbase) - base_##voff); _Pragma("unroll") for (int _i = 0; _i < 2; ++_i) \
;         __builtin_amdgcn_raw_ptr_buffer_load_lds(rs_##voff, (PG8_LAS unsigned*)(lds + (bufoff) + ldsw + _i * 8192), 16, (int)(voff)[_i], so_, 0, 0); } while (0)
; #define PG8_LDA(dst, b, h) do { _Pragma("unroll") for (int m = 0; m < 4; ++m) _Pragma("unroll") for (int k = 0; k < 2; ++k) dst[m][k] = *(const PG8_LAS bf16x8*)(lds + PG8_SA(b, h) + aoff + m * 2048 + k * 1024); } while (0)
; #define PG8_LDB(dst, b, h) do { _Pragma("unroll") for (int n = 0; n < 2; ++n) _Pragma("unroll") for (int k = 0; k < 2; ++k) dst[n][k] = *(const PG8_LAS bf16x8*)(lds + PG8_SB(b, h) + boff + n * 2048 + k * 1024); } while (0)
; #define PG8_MMA(ai, bj, At, Bt) do { __builtin_amdgcn_s_setprio(1); _Pragma("unroll") for (int m = 0; m < 4; ++m) _Pragma("unroll") for (int n = 0; n < 2; ++n) _Pragma("unroll") for (int k = 0; k < 2; ++k) \
;         acc[ai][bj][m][n] = __builtin_amdgcn_mfma_f32_16x16x32_bf16(Bt[n][k], At[m][k], acc[ai][bj][m][n], 0, 0, 0); __builtin_amdgcn_s_setprio(0); } while (0)
; #define PG8_WAIT_V(n) asm volatile("s_waitcnt vmcnt(" #n ")" ::: "memory")
; #define PG8_WAIT_L(n) asm volatile("s_waitcnt lgkmcnt(" #n ")" ::: "memory")
; #define PG8_BAR __builtin_amdgcn_s_barrier()
; #define PG8_SCHED __builtin_amdgcn_sched_barrier(0)
; template <class Epi, class Sched, bool ALIGN_EPI = false, bool SP2 = false>
; __device__ __forceinline__ void gemm_phase(PG8_LAS unsigned char* lds, const Gemm g, const Sched& S, const Epi& E, int tid_in) {
;     ...
;             PG8_LDB(B0, 1, 0); PG8_LDB(B1, 1, 1); PG8_SCHED; PG8_LDA(At, 1, 0); PG8_STAGE(PG8_SA(0, 1), a2 + hstepA, voffA);
;             PG8_WAIT_V(8); PG8_WAIT_L(0); PG8_BAR; PG8_MMA(0, 0, At, B0); PG8_MMA(0, 1, At, B1); PG8_BAR; PG8_SCHED;
;             PG8_LDA(At, 1, 1); PG8_STAGE(PG8_SB(1, 0), b3, voffB); PG8_STAGE(PG8_SB(1, 1), b3 + hstepB, voffB); PG8_STAGE(PG8_SA(1, 0), a3, voffA);
	s_setprio 0
	v_add_u32_e32 v133, 0x18000, v131
	ds_read_b128 v[134:137], v133
	ds_read_b128 v[138:141], v133 offset:1024
	ds_read_b128 v[142:145], v133 offset:2048
	ds_read_b128 v[146:149], v133 offset:3072
	v_add_u32_e32 v133, 0x1c000, v131
	ds_read_b128 v[150:153], v133
	ds_read_b128 v[154:157], v133 offset:1024
	ds_read_b128 v[158:161], v133 offset:2048
	ds_read_b128 v[166:169], v133 offset:3072
	s_add_i32 vcc_lo, s21, 0x80000
	s_mov_b32 m0, s66
	ds_read_b128 v[170:173], v132 offset:32768
	ds_read_b128 v[174:177], v132 offset:33792
	ds_read_b128 v[178:181], v132 offset:34816
	ds_read_b128 v[182:185], v132 offset:35840
	ds_read_b128 v[186:189], v132 offset:36864
	ds_read_b128 v[190:193], v132 offset:37888
	ds_read_b128 v[200:203], v132 offset:38912
	ds_read_b128 v[206:209], v132 offset:39936
	s_mov_b32 m0, s63
	s_nop 0
	buffer_load_dwordx4 v130, s[4:7], s21 offen lds
	s_mov_b32 m0, s66
	s_nop 0
	buffer_load_dwordx4 v0, s[4:7], vcc_lo offen lds
	s_mov_b32 m0, s67
	s_nop 0
	buffer_load_dwordx4 v130, s[4:7], vcc_lo offen lds
	s_waitcnt vmcnt(8)
	s_waitcnt lgkmcnt(0)
	s_setprio 1
	s_barrier
	v_mfma_f32_16x16x32_bf16 v[34:37], v[134:137], v[170:173], v[34:37]
	v_mfma_f32_16x16x32_bf16 v[18:21], v[142:145], v[170:173], v[18:21]
	v_mfma_f32_16x16x32_bf16 v[78:81], v[142:145], v[178:181], v[78:81]
	v_mfma_f32_16x16x32_bf16 v[86:89], v[134:137], v[178:181], v[86:89]
	v_mfma_f32_16x16x32_bf16 v[106:109], v[134:137], v[186:189], v[106:109]
	v_mfma_f32_16x16x32_bf16 v[102:105], v[142:145], v[186:189], v[102:105]
	v_mfma_f32_16x16x32_bf16 v[122:125], v[142:145], v[200:203], v[122:125]
	v_mfma_f32_16x16x32_bf16 v[126:129], v[134:137], v[200:203], v[126:129]
	v_mfma_f32_16x16x32_bf16 v[118:121], v[150:153], v[200:203], v[118:121]
	v_mfma_f32_16x16x32_bf16 v[114:117], v[158:161], v[200:203], v[114:117]
	v_mfma_f32_16x16x32_bf16 v[110:113], v[158:161], v[186:189], v[110:113]
	v_mfma_f32_16x16x32_bf16 v[98:101], v[150:153], v[186:189], v[98:101]
	v_mfma_f32_16x16x32_bf16 v[74:77], v[150:153], v[178:181], v[74:77]
	v_mfma_f32_16x16x32_bf16 v[90:93], v[158:161], v[178:181], v[90:93]
	v_mfma_f32_16x16x32_bf16 v[38:41], v[158:161], v[170:173], v[38:41]
	v_mfma_f32_16x16x32_bf16 v[14:17], v[150:153], v[170:173], v[14:17]
	v_mfma_f32_16x16x32_bf16 v[34:37], v[138:141], v[174:177], v[34:37]
	v_mfma_f32_16x16x32_bf16 v[18:21], v[146:149], v[174:177], v[18:21]
	v_mfma_f32_16x16x32_bf16 v[78:81], v[146:149], v[182:185], v[78:81]
	v_mfma_f32_16x16x32_bf16 v[86:89], v[138:141], v[182:185], v[86:89]
	v_mfma_f32_16x16x32_bf16 v[106:109], v[138:141], v[190:193], v[106:109]
	v_mfma_f32_16x16x32_bf16 v[102:105], v[146:149], v[190:193], v[102:105]
	v_mfma_f32_16x16x32_bf16 v[122:125], v[146:149], v[206:209], v[122:125]
	v_mfma_f32_16x16x32_bf16 v[126:129], v[138:141], v[206:209], v[126:129]
	v_mfma_f32_16x16x32_bf16 v[118:121], v[154:157], v[206:209], v[118:121]
	v_mfma_f32_16x16x32_bf16 v[114:117], v[166:169], v[206:209], v[114:117]
	v_mfma_f32_16x16x32_bf16 v[110:113], v[166:169], v[190:193], v[110:113]
	v_mfma_f32_16x16x32_bf16 v[98:101], v[154:157], v[190:193], v[98:101]
	v_mfma_f32_16x16x32_bf16 v[74:77], v[154:157], v[182:185], v[74:77]
	v_mfma_f32_16x16x32_bf16 v[90:93], v[166:169], v[182:185], v[90:93]
	v_mfma_f32_16x16x32_bf16 v[38:41], v[166:169], v[174:177], v[38:41]
	v_mfma_f32_16x16x32_bf16 v[14:17], v[154:157], v[174:177], v[14:17]
	s_barrier
	s_setprio 0
	s_mov_b32 m0, s68
	s_add_i32 vcc_lo, s79, 0x80
	ds_read_b128 v[170:173], v132 offset:49152
	ds_read_b128 v[174:177], v132 offset:50176
	ds_read_b128 v[178:181], v132 offset:51200
	ds_read_b128 v[182:185], v132 offset:52224
	ds_read_b128 v[186:189], v132 offset:53248
	ds_read_b128 v[190:193], v132 offset:54272
	ds_read_b128 v[200:203], v132 offset:55296
	ds_read_b128 v[206:209], v132 offset:56320
	buffer_load_dwordx4 v0, s[40:43], vcc_lo offen lds
	s_mov_b32 m0, s69
	s_add_i32 s79, s79, 0x80080
	buffer_load_dwordx4 v130, s[40:43], vcc_lo offen lds
	s_mov_b32 m0, s73
	s_addk_i32 s21, 0x80
	buffer_load_dwordx4 v0, s[40:43], s79 offen lds
	s_mov_b32 m0, s74
	s_nop 0
	buffer_load_dwordx4 v130, s[40:43], s79 offen lds
	s_mov_b32 m0, s71
	s_nop 0
	buffer_load_dwordx4 v0, s[4:7], s21 offen lds
	s_waitcnt vmcnt(7)
	s_waitcnt lgkmcnt(0)
	s_setprio 1
	s_barrier
;     static __device__ __forceinline__ bool last_of_chain(const Unit& u) { return (u.pn >> 3) == 2; }
; #define PG8_STAGE(bufoff, gbase, voff) do { const int so_ = (int)(unsigned)((const char*)(gbase) - base_##voff); _Pragma("unroll") for (int _i = 0; _i < 2; ++_i) \
;         __builtin_amdgcn_raw_ptr_buffer_load_lds(rs_##voff, (PG8_LAS unsigned*)(lds + (bufoff) + ldsw + _i * 8192), 16, (int)(voff)[_i], so_, 0, 0); } while (0)
; #define PG8_LDA(dst, b, h) do { _Pragma("unroll") for (int m = 0; m < 4; ++m) _Pragma("unroll") for (int k = 0; k < 2; ++k) dst[m][k] = *(const PG8_LAS bf16x8*)(lds + PG8_SA(b, h) + aoff + m * 2048 + k * 1024); } while (0)
; #define PG8_MMA(ai, bj, At, Bt) do { __builtin_amdgcn_s_setprio(1); _Pragma("unroll") for (int m = 0; m < 4; ++m) _Pragma("unroll") for (int n = 0; n < 2; ++n) _Pragma("unroll") for (int k = 0; k < 2; ++k) \
;         acc[ai][bj][m][n] = __builtin_amdgcn_mfma_f32_16x16x32_bf16(Bt[n][k], At[m][k], acc[ai][bj][m][n], 0, 0, 0); __builtin_amdgcn_s_setprio(0); } while (0)
; #define PG8_WAIT_V(n) asm volatile("s_waitcnt vmcnt(" #n ")" ::: "memory")
; #define PG8_WAIT_L(n) asm volatile("s_waitcnt lgkmcnt(" #n ")" ::: "memory")
; #define PG8_BAR __builtin_amdgcn_s_barrier()
; #define PG8_SCHED __builtin_amdgcn_sched_barrier(0)
; template <class Epi, class Sched, bool ALIGN_EPI = false, bool SP2 = false>
; __device__ __forceinline__ void gemm_phase(PG8_LAS unsigned char* lds, const Gemm g, const Sched& S, const Epi& E, int tid_in) {
;     ...
;             PG8_LDA(At, 1, 1); PG8_STAGE(PG8_SB(1, 0), b3, voffB); PG8_STAGE(PG8_SB(1, 1), b3 + hstepB, voffB); PG8_STAGE(PG8_SA(1, 0), a3, voffA);
;             PG8_WAIT_V(8); PG8_WAIT_L(0); PG8_BAR; PG8_MMA(1, 0, At, B0); PG8_MMA(1, 1, At, B1); PG8_BAR; PG8_SCHED;
;     ...
;         bool zero_acc = true; if constexpr (Epi::CHAIN) zero_acc = Epi::last_of_chain(cur);
;         if (zero_acc) {
; #pragma unroll
;         for (int a = 0; a < 2; ++a)
; #pragma unroll
;             for (int b = 0; b < 2; ++b)
; #pragma unroll
;                 for (int m = 0; m < 4; ++m)
; #pragma unroll
;                     for (int n = 0; n < 2; ++n) acc[a][b][m][n] = (f32x4){0.f, 0.f, 0.f, 0.f};
;         }
;         cur = nxt; cA = nA; cB = nB; ++ui;
	v_mfma_f32_16x16x32_bf16 v[50:53], v[134:137], v[170:173], v[50:53]
	v_mfma_f32_16x16x32_bf16 v[30:33], v[142:145], v[170:173], v[30:33]
	v_mfma_f32_16x16x32_bf16 v[58:61], v[142:145], v[178:181], v[58:61]
	v_mfma_f32_16x16x32_bf16 v[62:65], v[134:137], v[178:181], v[62:65]
	v_mfma_f32_16x16x32_bf16 v[94:97], v[134:137], v[186:189], v[94:97]
	v_mfma_f32_16x16x32_bf16 v[82:85], v[142:145], v[186:189], v[82:85]
	v_mfma_f32_16x16x32_bf16 v[26:29], v[142:145], v[200:203], v[26:29]
	v_mfma_f32_16x16x32_bf16 v[46:49], v[134:137], v[200:203], v[46:49]
	v_mfma_f32_16x16x32_bf16 v[6:9], v[150:153], v[200:203], v[6:9]
	v_mfma_f32_16x16x32_bf16 v[2:5], v[158:161], v[200:203], v[2:5]
	v_mfma_f32_16x16x32_bf16 v[42:45], v[158:161], v[186:189], v[42:45]
	v_mfma_f32_16x16x32_bf16 v[70:73], v[150:153], v[186:189], v[70:73]
	v_mfma_f32_16x16x32_bf16 v[54:57], v[150:153], v[178:181], v[54:57]
	v_mfma_f32_16x16x32_bf16 v[66:69], v[158:161], v[178:181], v[66:69]
	v_mfma_f32_16x16x32_bf16 v[10:13], v[158:161], v[170:173], v[10:13]
	v_mfma_f32_16x16x32_bf16 v[22:25], v[150:153], v[170:173], v[22:25]
	v_mfma_f32_16x16x32_bf16 v[50:53], v[138:141], v[174:177], v[50:53]
	v_mfma_f32_16x16x32_bf16 v[30:33], v[146:149], v[174:177], v[30:33]
	v_mfma_f32_16x16x32_bf16 v[58:61], v[146:149], v[182:185], v[58:61]
	v_mfma_f32_16x16x32_bf16 v[62:65], v[138:141], v[182:185], v[62:65]
	v_mfma_f32_16x16x32_bf16 v[94:97], v[138:141], v[190:193], v[94:97]
	v_mfma_f32_16x16x32_bf16 v[82:85], v[146:149], v[190:193], v[82:85]
	v_mfma_f32_16x16x32_bf16 v[26:29], v[146:149], v[206:209], v[26:29]
	v_mfma_f32_16x16x32_bf16 v[46:49], v[138:141], v[206:209], v[46:49]
	v_mfma_f32_16x16x32_bf16 v[6:9], v[154:157], v[206:209], v[6:9]
	v_mfma_f32_16x16x32_bf16 v[2:5], v[166:169], v[206:209], v[2:5]
	v_mfma_f32_16x16x32_bf16 v[42:45], v[166:169], v[190:193], v[42:45]
	v_mfma_f32_16x16x32_bf16 v[70:73], v[154:157], v[190:193], v[70:73]
	v_mfma_f32_16x16x32_bf16 v[54:57], v[154:157], v[182:185], v[54:57]
	v_mfma_f32_16x16x32_bf16 v[66:69], v[166:169], v[182:185], v[66:69]
	v_mfma_f32_16x16x32_bf16 v[10:13], v[166:169], v[174:177], v[10:13]
	v_mfma_f32_16x16x32_bf16 v[22:25], v[154:157], v[174:177], v[22:25]
	s_barrier
	s_setprio 0
	s_add_i32 s19, s19, 2
	s_add_u32 s44, s44, 0x100
	s_addc_u32 s45, s45, 0
	s_cmp_gt_u32 s19, 29
	s_cbranch_scc0 .LBB0_1265
	s_andn2_b64 vcc, exec, s[38:39]
	s_cbranch_vccnz .LBB0_1257
	v_mov_b32_e32 v2, 0
	s_mov_b64 s[12:13], s[24:25]
	s_mov_b32 s10, s16
	s_mov_b32 s48, s20
	s_mov_b64 s[14:15], s[22:23]
	s_mov_b32 s13, s78
	v_mov_b32_e32 v3, v2
	v_mov_b32_e32 v4, v2
	v_mov_b32_e32 v5, v2
	v_mov_b32_e32 v6, v2
	v_mov_b32_e32 v7, v2
	v_mov_b32_e32 v8, v2
	v_mov_b32_e32 v9, v2
	v_mov_b32_e32 v42, v2
	v_mov_b32_e32 v43, v2
	v_mov_b32_e32 v44, v2
	v_mov_b32_e32 v45, v2
	v_mov_b32_e32 v70, v2
	v_mov_b32_e32 v71, v2
	v_mov_b32_e32 v72, v2
	v_mov_b32_e32 v73, v2
	v_mov_b32_e32 v66, v2
	v_mov_b32_e32 v67, v2
	v_mov_b32_e32 v68, v2
	v_mov_b32_e32 v69, v2
	v_mov_b32_e32 v54, v2
	v_mov_b32_e32 v55, v2
	v_mov_b32_e32 v56, v2
	v_mov_b32_e32 v57, v2
	v_mov_b32_e32 v10, v2
	v_mov_b32_e32 v11, v2
	v_mov_b32_e32 v12, v2
	v_mov_b32_e32 v13, v2
	v_mov_b32_e32 v22, v2
	v_mov_b32_e32 v23, v2
	v_mov_b32_e32 v24, v2
	v_mov_b32_e32 v25, v2
	v_mov_b32_e32 v26, v2
	v_mov_b32_e32 v27, v2
	v_mov_b32_e32 v28, v2
	v_mov_b32_e32 v29, v2
	v_mov_b32_e32 v46, v2
	v_mov_b32_e32 v47, v2
	v_mov_b32_e32 v48, v2
	v_mov_b32_e32 v49, v2
	v_mov_b32_e32 v82, v2
	v_mov_b32_e32 v83, v2
	v_mov_b32_e32 v84, v2
	v_mov_b32_e32 v85, v2
	v_mov_b32_e32 v94, v2
	v_mov_b32_e32 v95, v2
	v_mov_b32_e32 v96, v2
	v_mov_b32_e32 v97, v2
	v_mov_b32_e32 v58, v2
	v_mov_b32_e32 v59, v2
	v_mov_b32_e32 v60, v2
	v_mov_b32_e32 v61, v2
	v_mov_b32_e32 v62, v2
	v_mov_b32_e32 v63, v2
	v_mov_b32_e32 v64, v2
	v_mov_b32_e32 v65, v2
	v_mov_b32_e32 v30, v2
	v_mov_b32_e32 v31, v2
	v_mov_b32_e32 v32, v2
	v_mov_b32_e32 v33, v2
	v_mov_b32_e32 v50, v2
	v_mov_b32_e32 v51, v2
	v_mov_b32_e32 v52, v2
	v_mov_b32_e32 v53, v2
	v_mov_b32_e32 v114, v2
	v_mov_b32_e32 v115, v2
	v_mov_b32_e32 v116, v2
	v_mov_b32_e32 v117, v2
	v_mov_b32_e32 v118, v2
	v_mov_b32_e32 v119, v2
	v_mov_b32_e32 v120, v2
	v_mov_b32_e32 v121, v2
	v_mov_b32_e32 v110, v2
	v_mov_b32_e32 v111, v2
	v_mov_b32_e32 v112, v2
	v_mov_b32_e32 v113, v2
	v_mov_b32_e32 v98, v2
	v_mov_b32_e32 v99, v2
	v_mov_b32_e32 v100, v2
	v_mov_b32_e32 v101, v2
	v_mov_b32_e32 v90, v2
	v_mov_b32_e32 v91, v2
	v_mov_b32_e32 v92, v2
	v_mov_b32_e32 v93, v2
	v_mov_b32_e32 v74, v2
	v_mov_b32_e32 v75, v2
	v_mov_b32_e32 v76, v2
	v_mov_b32_e32 v77, v2
	v_mov_b32_e32 v38, v2
	v_mov_b32_e32 v39, v2
	v_mov_b32_e32 v40, v2
	v_mov_b32_e32 v41, v2
	v_mov_b32_e32 v14, v2
	v_mov_b32_e32 v15, v2
	v_mov_b32_e32 v16, v2
	v_mov_b32_e32 v17, v2
	v_mov_b32_e32 v122, v2
	v_mov_b32_e32 v123, v2
	v_mov_b32_e32 v124, v2
	v_mov_b32_e32 v125, v2
	v_mov_b32_e32 v126, v2
	v_mov_b32_e32 v127, v2
	v_mov_b32_e32 v128, v2
	v_mov_b32_e32 v129, v2
	v_mov_b32_e32 v102, v2
	v_mov_b32_e32 v103, v2
	v_mov_b32_e32 v104, v2
	v_mov_b32_e32 v105, v2
	v_mov_b32_e32 v106, v2
	v_mov_b32_e32 v107, v2
	v_mov_b32_e32 v108, v2
	v_mov_b32_e32 v109, v2
	v_mov_b32_e32 v78, v2
	v_mov_b32_e32 v79, v2
	v_mov_b32_e32 v80, v2
	v_mov_b32_e32 v81, v2
	v_mov_b32_e32 v86, v2
	v_mov_b32_e32 v87, v2
	v_mov_b32_e32 v88, v2
	v_mov_b32_e32 v89, v2
	v_mov_b32_e32 v18, v2
	v_mov_b32_e32 v19, v2
	v_mov_b32_e32 v20, v2
	v_mov_b32_e32 v21, v2
	v_mov_b32_e32 v34, v2
	v_mov_b32_e32 v35, v2
	v_mov_b32_e32 v36, v2
	v_mov_b32_e32 v37, v2
	s_branch .LBB0_1257

; #define PG8_STAGE(bufoff, gbase, voff) do { const int so_ = (int)(unsigned)((const char*)(gbase) - base_##voff); _Pragma("unroll") for (int _i = 0; _i < 2; ++_i) \
;         __builtin_amdgcn_raw_ptr_buffer_load_lds(rs_##voff, (PG8_LAS unsigned*)(lds + (bufoff) + ldsw + _i * 8192), 16, (int)(voff)[_i], so_, 0, 0); } while (0)
; #define PG8_LDA(dst, b, h) do { _Pragma("unroll") for (int m = 0; m < 4; ++m) _Pragma("unroll") for (int k = 0; k < 2; ++k) dst[m][k] = *(const PG8_LAS bf16x8*)(lds + PG8_SA(b, h) + aoff + m * 2048 + k * 1024); } while (0)
; #define PG8_LDB(dst, b, h) do { _Pragma("unroll") for (int n = 0; n < 2; ++n) _Pragma("unroll") for (int k = 0; k < 2; ++k) dst[n][k] = *(const PG8_LAS bf16x8*)(lds + PG8_SB(b, h) + boff + n * 2048 + k * 1024); } while (0)
; #define PG8_WAIT_V(n) asm volatile("s_waitcnt vmcnt(" #n ")" ::: "memory")
; #define PG8_WAIT_L(n) asm volatile("s_waitcnt lgkmcnt(" #n ")" ::: "memory")
; #define PG8_BAR __builtin_amdgcn_s_barrier()
; #define PG8_SCHED __builtin_amdgcn_sched_barrier(0)
; template <class Epi, class Sched, bool ALIGN_EPI = false, bool SP2 = false>
; __device__ __forceinline__ void gemm_phase(PG8_LAS unsigned char* lds, const Gemm g, const Sched& S, const Epi& E, int tid_in) {
;     ...
;         const char* nA = has_next ? (const char*)g.A + (size_t)nxt.pm * tstepA + (g.grp ? (size_t)(nxt.pn / g.grp) * g.agrp : (size_t)0) : cA; const char* nB = has_next ? (const char*)g.Bt + (size_t)nxt.pn * tstepB : cB;
;         for (int t = 0; t < nt; t += 2) {
;             const bool last = (t == nt - 2);
;             const char* a1 = cA + (size_t)(t + 1) * kstep;
;             const char* a2 = last ? nA : cA + (size_t)(t + 2) * kstep; const char* b2 = last ? nB : cB + (size_t)(t + 2) * kstep;
;             const char* a3 = a2 + kstep; const char* b3 = b2 + kstep;
;             if (last && has_next) S.a_ready(nxt);
;             if constexpr (SP2) {
;             PG8_LDB(B0, 0, 0); PG8_LDB(B1, 0, 1); PG8_SCHED; PG8_LDA(At, 0, 0); PG8_STAGE(PG8_SA(1, 1), a1 + hstepA, voffA);
;             PG8_WAIT_V(8); PG8_WAIT_L(0); PG8_BAR; PG8_MMA(0, 0, At, B0); PG8_MMA(0, 1, At, B1); PG8_BAR; PG8_SCHED;
;             PG8_LDA(At, 0, 1); PG8_STAGE(PG8_SB(0, 0), b2, voffB); PG8_STAGE(PG8_SB(0, 1), b2 + hstepB, voffB); PG8_STAGE(PG8_SA(0, 0), a2, voffA);
.LBB0_1513:
	s_ashr_i32 s21, s20, 31
	s_lshl_b64 s[18:19], s[20:21], 20
	s_add_u32 s22, s4, s18
	s_addc_u32 s23, s9, s19
	s_and_b64 s[18:19], s[36:37], exec
	s_cselect_b32 s18, s22, s16
	s_ashr_i32 s15, s14, 31
	s_lshl_b64 s[24:25], s[14:15], 20
	s_add_u32 s24, s40, s24
	s_addc_u32 s25, s26, s25
	s_and_b64 s[42:43], s[36:37], exec
	s_cselect_b32 s15, s24, s38
	s_add_u32 s19, s38, 0x100
	v_mov_b32_e32 v2, 0
	s_addc_u32 s21, s39, 0
	s_mov_b32 s73, -2
	v_add_u32_e32 v141, 0x10000, v139
	ds_read_b128 v[130:133], v141
	ds_read_b128 v[142:145], v141 offset:1024
	ds_read_b128 v[146:149], v141 offset:2048
	ds_read_b128 v[150:153], v141 offset:3072
	v_add_u32_e32 v141, 0x14000, v139
	ds_read_b128 v[154:157], v141
	ds_read_b128 v[158:161], v141 offset:1024
	ds_read_b128 v[162:165], v141 offset:2048
	ds_read_b128 v[166:169], v141 offset:3072
	s_add_u32 s38, s16, 0x100
	s_addc_u32 s39, s17, 0
	s_sub_i32 s16, s16, s4
	s_add_i32 s16, s16, 0x80080
	s_sub_i32 s74, s16, 0x80000
	s_cmp_eq_u32 s73, 28
	s_cselect_b32 s17, s18, s38
	s_mov_b32 m0, s67
	ds_read_b128 v[170:173], v140
	ds_read_b128 v[174:177], v140 offset:1024
	ds_read_b128 v[178:181], v140 offset:2048
	ds_read_b128 v[182:185], v140 offset:3072
	ds_read_b128 v[186:189], v140 offset:4096
	ds_read_b128 v[190:193], v140 offset:5120
	ds_read_b128 v[200:203], v140 offset:6144
	ds_read_b128 v[206:209], v140 offset:7168
	s_mov_b32 m0, s62
	s_nop 0
	buffer_load_dwordx4 v135, s[4:7], s74 offen lds
	s_mov_b32 m0, s67
	s_nop 0
	buffer_load_dwordx4 v0, s[4:7], s16 offen lds
	s_mov_b32 m0, s68
	s_nop 0
	buffer_load_dwordx4 v135, s[4:7], s16 offen lds
	s_waitcnt vmcnt(8)
	s_waitcnt lgkmcnt(0)
	s_setprio 1
	s_barrier
	v_mfma_f32_16x16x32_bf16 v[126:129], v[130:133], v[170:173], 0
	v_mfma_f32_16x16x32_bf16 v[122:125], v[146:149], v[170:173], 0
	v_mfma_f32_16x16x32_bf16 v[106:109], v[146:149], v[178:181], 0
	v_mfma_f32_16x16x32_bf16 v[110:113], v[130:133], v[178:181], 0
	v_mfma_f32_16x16x32_bf16 v[94:97], v[130:133], v[186:189], 0
	v_mfma_f32_16x16x32_bf16 v[90:93], v[146:149], v[186:189], 0
	v_mfma_f32_16x16x32_bf16 v[74:77], v[146:149], v[200:203], 0
	v_mfma_f32_16x16x32_bf16 v[78:81], v[130:133], v[200:203], 0
	v_mfma_f32_16x16x32_bf16 v[126:129], v[142:145], v[174:177], v[126:129]
	v_mfma_f32_16x16x32_bf16 v[122:125], v[150:153], v[174:177], v[122:125]
	v_mfma_f32_16x16x32_bf16 v[106:109], v[150:153], v[182:185], v[106:109]
	v_mfma_f32_16x16x32_bf16 v[110:113], v[142:145], v[182:185], v[110:113]
	v_mfma_f32_16x16x32_bf16 v[94:97], v[142:145], v[190:193], v[94:97]
	v_mfma_f32_16x16x32_bf16 v[90:93], v[150:153], v[190:193], v[90:93]
	v_mfma_f32_16x16x32_bf16 v[74:77], v[150:153], v[206:209], v[74:77]
	v_mfma_f32_16x16x32_bf16 v[78:81], v[142:145], v[206:209], v[78:81]
	v_mfma_f32_16x16x32_bf16 v[118:121], v[154:157], v[170:173], 0
	v_mfma_f32_16x16x32_bf16 v[114:117], v[162:165], v[170:173], 0
	v_mfma_f32_16x16x32_bf16 v[98:101], v[162:165], v[178:181], 0
	v_mfma_f32_16x16x32_bf16 v[102:105], v[154:157], v[178:181], 0
	v_mfma_f32_16x16x32_bf16 v[86:89], v[154:157], v[186:189], 0
	v_mfma_f32_16x16x32_bf16 v[82:85], v[162:165], v[186:189], 0
	v_mfma_f32_16x16x32_bf16 v[66:69], v[162:165], v[200:203], 0
	v_mfma_f32_16x16x32_bf16 v[70:73], v[154:157], v[200:203], 0
	v_mfma_f32_16x16x32_bf16 v[118:121], v[158:161], v[174:177], v[118:121]
	v_mfma_f32_16x16x32_bf16 v[114:117], v[166:169], v[174:177], v[114:117]
	v_mfma_f32_16x16x32_bf16 v[98:101], v[166:169], v[182:185], v[98:101]
	v_mfma_f32_16x16x32_bf16 v[102:105], v[158:161], v[182:185], v[102:105]
	v_mfma_f32_16x16x32_bf16 v[86:89], v[158:161], v[190:193], v[86:89]
	v_mfma_f32_16x16x32_bf16 v[82:85], v[166:169], v[190:193], v[82:85]
	v_mfma_f32_16x16x32_bf16 v[66:69], v[166:169], v[206:209], v[66:69]
	v_mfma_f32_16x16x32_bf16 v[70:73], v[158:161], v[206:209], v[70:73]
	s_barrier
	s_setprio 0
	s_cselect_b32 s16, s15, s19
	s_mov_b32 m0, s35
	s_mov_b32 s42, s6
	s_mov_b32 s43, s7
	s_sub_i32 s16, s16, s40
	ds_read_b128 v[170:173], v140 offset:16384
	ds_read_b128 v[174:177], v140 offset:17408
	ds_read_b128 v[178:181], v140 offset:18432
	ds_read_b128 v[182:185], v140 offset:19456
	ds_read_b128 v[186:189], v140 offset:20480
	ds_read_b128 v[190:193], v140 offset:21504
	ds_read_b128 v[200:203], v140 offset:22528
	ds_read_b128 v[206:209], v140 offset:23552
	buffer_load_dwordx4 v134, s[40:43], s16 offen lds
	s_mov_b32 m0, s44
	s_add_i32 s74, s16, 0x80000
	buffer_load_dwordx4 v136, s[40:43], s16 offen lds
	s_mov_b32 m0, s45
	s_sub_i32 s17, s17, s4
	buffer_load_dwordx4 v134, s[40:43], s74 offen lds
	s_mov_b32 m0, s46
	s_nop 0
	buffer_load_dwordx4 v136, s[40:43], s74 offen lds
	s_mov_b32 m0, s34
	s_nop 0
	buffer_load_dwordx4 v0, s[4:7], s17 offen lds
	s_waitcnt vmcnt(7)
	s_waitcnt lgkmcnt(0)
	s_setprio 1
	s_barrier
; #define PG8_STAGE(bufoff, gbase, voff) do { const int so_ = (int)(unsigned)((const char*)(gbase) - base_##voff); _Pragma("unroll") for (int _i = 0; _i < 2; ++_i) \
;         __builtin_amdgcn_raw_ptr_buffer_load_lds(rs_##voff, (PG8_LAS unsigned*)(lds + (bufoff) + ldsw + _i * 8192), 16, (int)(voff)[_i], so_, 0, 0); } while (0)
; #define PG8_LDA(dst, b, h) do { _Pragma("unroll") for (int m = 0; m < 4; ++m) _Pragma("unroll") for (int k = 0; k < 2; ++k) dst[m][k] = *(const PG8_LAS bf16x8*)(lds + PG8_SA(b, h) + aoff + m * 2048 + k * 1024); } while (0)
; #define PG8_LDB(dst, b, h) do { _Pragma("unroll") for (int n = 0; n < 2; ++n) _Pragma("unroll") for (int k = 0; k < 2; ++k) dst[n][k] = *(const PG8_LAS bf16x8*)(lds + PG8_SB(b, h) + boff + n * 2048 + k * 1024); } while (0)
; #define PG8_MMA(ai, bj, At, Bt) do { __builtin_amdgcn_s_setprio(1); _Pragma("unroll") for (int m = 0; m < 4; ++m) _Pragma("unroll") for (int n = 0; n < 2; ++n) _Pragma("unroll") for (int k = 0; k < 2; ++k) \
;         acc[ai][bj][m][n] = __builtin_amdgcn_mfma_f32_16x16x32_bf16(Bt[n][k], At[m][k], acc[ai][bj][m][n], 0, 0, 0); __builtin_amdgcn_s_setprio(0); } while (0)
; #define PG8_WAIT_V(n) asm volatile("s_waitcnt vmcnt(" #n ")" ::: "memory")
; #define PG8_WAIT_L(n) asm volatile("s_waitcnt lgkmcnt(" #n ")" ::: "memory")
; #define PG8_BAR __builtin_amdgcn_s_barrier()
; #define PG8_SCHED __builtin_amdgcn_sched_barrier(0)
; template <class Epi, class Sched, bool ALIGN_EPI = false, bool SP2 = false>
; __device__ __forceinline__ void gemm_phase(PG8_LAS unsigned char* lds, const Gemm g, const Sched& S, const Epi& E, int tid_in) {
;     ...
;             PG8_WAIT_V(8); PG8_WAIT_L(0); PG8_BAR; PG8_MMA(1, 0, At, B0); PG8_MMA(1, 1, At, B1); PG8_BAR; PG8_SCHED;
;             PG8_LDB(B0, 1, 0); PG8_LDB(B1, 1, 1); PG8_SCHED; PG8_LDA(At, 1, 0); PG8_STAGE(PG8_SA(0, 1), a2 + hstepA, voffA);
;             PG8_WAIT_V(8); PG8_WAIT_L(0); PG8_BAR; PG8_MMA(0, 0, At, B0); PG8_MMA(0, 1, At, B1); PG8_BAR; PG8_SCHED;
	v_mfma_f32_16x16x32_bf16 v[62:65], v[130:133], v[170:173], 0
	v_mfma_f32_16x16x32_bf16 v[58:61], v[146:149], v[170:173], 0
	v_mfma_f32_16x16x32_bf16 v[42:45], v[146:149], v[178:181], 0
	v_mfma_f32_16x16x32_bf16 v[46:49], v[130:133], v[178:181], 0
	v_mfma_f32_16x16x32_bf16 v[30:33], v[130:133], v[186:189], 0
	v_mfma_f32_16x16x32_bf16 v[26:29], v[146:149], v[186:189], 0
	v_mfma_f32_16x16x32_bf16 v[10:13], v[146:149], v[200:203], 0
	v_mfma_f32_16x16x32_bf16 v[14:17], v[130:133], v[200:203], 0
	v_mfma_f32_16x16x32_bf16 v[62:65], v[142:145], v[174:177], v[62:65]
	v_mfma_f32_16x16x32_bf16 v[58:61], v[150:153], v[174:177], v[58:61]
	v_mfma_f32_16x16x32_bf16 v[42:45], v[150:153], v[182:185], v[42:45]
	v_mfma_f32_16x16x32_bf16 v[46:49], v[142:145], v[182:185], v[46:49]
	v_mfma_f32_16x16x32_bf16 v[30:33], v[142:145], v[190:193], v[30:33]
	v_mfma_f32_16x16x32_bf16 v[26:29], v[150:153], v[190:193], v[26:29]
	v_mfma_f32_16x16x32_bf16 v[10:13], v[150:153], v[206:209], v[10:13]
	v_mfma_f32_16x16x32_bf16 v[14:17], v[142:145], v[206:209], v[14:17]
	v_mfma_f32_16x16x32_bf16 v[54:57], v[154:157], v[170:173], 0
	v_mfma_f32_16x16x32_bf16 v[50:53], v[162:165], v[170:173], 0
	v_mfma_f32_16x16x32_bf16 v[34:37], v[162:165], v[178:181], 0
	v_mfma_f32_16x16x32_bf16 v[38:41], v[154:157], v[178:181], 0
	v_mfma_f32_16x16x32_bf16 v[22:25], v[154:157], v[186:189], 0
	v_mfma_f32_16x16x32_bf16 v[18:21], v[162:165], v[186:189], 0
	v_mfma_f32_16x16x32_bf16 v[2:5], v[162:165], v[200:203], 0
	v_mfma_f32_16x16x32_bf16 v[6:9], v[154:157], v[200:203], 0
	v_mfma_f32_16x16x32_bf16 v[54:57], v[158:161], v[174:177], v[54:57]
	v_mfma_f32_16x16x32_bf16 v[50:53], v[166:169], v[174:177], v[50:53]
	v_mfma_f32_16x16x32_bf16 v[34:37], v[166:169], v[182:185], v[34:37]
	v_mfma_f32_16x16x32_bf16 v[38:41], v[158:161], v[182:185], v[38:41]
	v_mfma_f32_16x16x32_bf16 v[22:25], v[158:161], v[190:193], v[22:25]
	v_mfma_f32_16x16x32_bf16 v[18:21], v[166:169], v[190:193], v[18:21]
	v_mfma_f32_16x16x32_bf16 v[2:5], v[166:169], v[206:209], v[2:5]
	v_mfma_f32_16x16x32_bf16 v[6:9], v[158:161], v[206:209], v[6:9]
	s_barrier
	s_setprio 0
	v_add_u32_e32 v141, 0x18000, v139
	ds_read_b128 v[130:133], v141
	ds_read_b128 v[142:145], v141 offset:1024
	ds_read_b128 v[146:149], v141 offset:2048
	ds_read_b128 v[150:153], v141 offset:3072
	v_add_u32_e32 v141, 0x1c000, v139
	ds_read_b128 v[154:157], v141
	ds_read_b128 v[158:161], v141 offset:1024
	ds_read_b128 v[162:165], v141 offset:2048
	ds_read_b128 v[166:169], v141 offset:3072
	s_add_i32 s74, s17, 0x80000
	s_mov_b32 m0, s48
	ds_read_b128 v[170:173], v140 offset:32768
	ds_read_b128 v[174:177], v140 offset:33792
	ds_read_b128 v[178:181], v140 offset:34816
	ds_read_b128 v[182:185], v140 offset:35840
	ds_read_b128 v[186:189], v140 offset:36864
	ds_read_b128 v[190:193], v140 offset:37888
	ds_read_b128 v[200:203], v140 offset:38912
	ds_read_b128 v[206:209], v140 offset:39936
	s_mov_b32 m0, s47
	s_nop 0
	buffer_load_dwordx4 v135, s[4:7], s17 offen lds
	s_mov_b32 m0, s48
	s_nop 0
	buffer_load_dwordx4 v0, s[4:7], s74 offen lds
	s_mov_b32 m0, s49
	s_nop 0
	buffer_load_dwordx4 v135, s[4:7], s74 offen lds
	s_waitcnt vmcnt(8)
	s_waitcnt lgkmcnt(0)
	s_setprio 1
	s_barrier
	v_mfma_f32_16x16x32_bf16 v[126:129], v[130:133], v[170:173], v[126:129]
	v_mfma_f32_16x16x32_bf16 v[122:125], v[146:149], v[170:173], v[122:125]
	v_mfma_f32_16x16x32_bf16 v[106:109], v[146:149], v[178:181], v[106:109]
	v_mfma_f32_16x16x32_bf16 v[110:113], v[130:133], v[178:181], v[110:113]
	v_mfma_f32_16x16x32_bf16 v[94:97], v[130:133], v[186:189], v[94:97]
	v_mfma_f32_16x16x32_bf16 v[90:93], v[146:149], v[186:189], v[90:93]
	v_mfma_f32_16x16x32_bf16 v[74:77], v[146:149], v[200:203], v[74:77]
	v_mfma_f32_16x16x32_bf16 v[78:81], v[130:133], v[200:203], v[78:81]
	v_mfma_f32_16x16x32_bf16 v[70:73], v[154:157], v[200:203], v[70:73]
	v_mfma_f32_16x16x32_bf16 v[66:69], v[162:165], v[200:203], v[66:69]
	v_mfma_f32_16x16x32_bf16 v[82:85], v[162:165], v[186:189], v[82:85]
	v_mfma_f32_16x16x32_bf16 v[86:89], v[154:157], v[186:189], v[86:89]
	v_mfma_f32_16x16x32_bf16 v[102:105], v[154:157], v[178:181], v[102:105]
	v_mfma_f32_16x16x32_bf16 v[98:101], v[162:165], v[178:181], v[98:101]
	v_mfma_f32_16x16x32_bf16 v[114:117], v[162:165], v[170:173], v[114:117]
	v_mfma_f32_16x16x32_bf16 v[118:121], v[154:157], v[170:173], v[118:121]
	v_mfma_f32_16x16x32_bf16 v[126:129], v[142:145], v[174:177], v[126:129]
	v_mfma_f32_16x16x32_bf16 v[122:125], v[150:153], v[174:177], v[122:125]
	v_mfma_f32_16x16x32_bf16 v[106:109], v[150:153], v[182:185], v[106:109]
	v_mfma_f32_16x16x32_bf16 v[110:113], v[142:145], v[182:185], v[110:113]
	v_mfma_f32_16x16x32_bf16 v[94:97], v[142:145], v[190:193], v[94:97]
	v_mfma_f32_16x16x32_bf16 v[90:93], v[150:153], v[190:193], v[90:93]
	v_mfma_f32_16x16x32_bf16 v[74:77], v[150:153], v[206:209], v[74:77]
	v_mfma_f32_16x16x32_bf16 v[78:81], v[142:145], v[206:209], v[78:81]
	v_mfma_f32_16x16x32_bf16 v[70:73], v[158:161], v[206:209], v[70:73]
	v_mfma_f32_16x16x32_bf16 v[66:69], v[166:169], v[206:209], v[66:69]
	v_mfma_f32_16x16x32_bf16 v[82:85], v[166:169], v[190:193], v[82:85]
	v_mfma_f32_16x16x32_bf16 v[86:89], v[158:161], v[190:193], v[86:89]
	v_mfma_f32_16x16x32_bf16 v[102:105], v[158:161], v[182:185], v[102:105]
	v_mfma_f32_16x16x32_bf16 v[98:101], v[166:169], v[182:185], v[98:101]
	v_mfma_f32_16x16x32_bf16 v[114:117], v[166:169], v[174:177], v[114:117]
	v_mfma_f32_16x16x32_bf16 v[118:121], v[158:161], v[174:177], v[118:121]
	s_barrier
; #define PG8_STAGE(bufoff, gbase, voff) do { const int so_ = (int)(unsigned)((const char*)(gbase) - base_##voff); _Pragma("unroll") for (int _i = 0; _i < 2; ++_i) \
;         __builtin_amdgcn_raw_ptr_buffer_load_lds(rs_##voff, (PG8_LAS unsigned*)(lds + (bufoff) + ldsw + _i * 8192), 16, (int)(voff)[_i], so_, 0, 0); } while (0)
; #define PG8_LDA(dst, b, h) do { _Pragma("unroll") for (int m = 0; m < 4; ++m) _Pragma("unroll") for (int k = 0; k < 2; ++k) dst[m][k] = *(const PG8_LAS bf16x8*)(lds + PG8_SA(b, h) + aoff + m * 2048 + k * 1024); } while (0)
; #define PG8_LDB(dst, b, h) do { _Pragma("unroll") for (int n = 0; n < 2; ++n) _Pragma("unroll") for (int k = 0; k < 2; ++k) dst[n][k] = *(const PG8_LAS bf16x8*)(lds + PG8_SB(b, h) + boff + n * 2048 + k * 1024); } while (0)
; #define PG8_MMA(ai, bj, At, Bt) do { __builtin_amdgcn_s_setprio(1); _Pragma("unroll") for (int m = 0; m < 4; ++m) _Pragma("unroll") for (int n = 0; n < 2; ++n) _Pragma("unroll") for (int k = 0; k < 2; ++k) \
;         acc[ai][bj][m][n] = __builtin_amdgcn_mfma_f32_16x16x32_bf16(Bt[n][k], At[m][k], acc[ai][bj][m][n], 0, 0, 0); __builtin_amdgcn_s_setprio(0); } while (0)
; template <class Epi, class Sched, bool ALIGN_EPI = false, bool SP2 = false>
; __device__ __forceinline__ void gemm_phase(PG8_LAS unsigned char* lds, const Gemm g, const Sched& S, const Epi& E, int tid_in) {
;     ...
;             PG8_LDB(B0, 0, 0); PG8_LDB(B1, 0, 1); PG8_SCHED; PG8_LDA(At, 0, 0); PG8_STAGE(PG8_SA(1, 1), a1 + hstepA, voffA);
;             PG8_WAIT_V(8); PG8_WAIT_L(0); PG8_BAR; PG8_MMA(0, 0, At, B0); PG8_MMA(0, 1, At, B1); PG8_BAR; PG8_SCHED;
;             PG8_LDA(At, 0, 1); PG8_STAGE(PG8_SB(0, 0), b2, voffB); PG8_STAGE(PG8_SB(0, 1), b2 + hstepB, voffB); PG8_STAGE(PG8_SA(0, 0), a2, voffA);
;             PG8_WAIT_V(8); PG8_WAIT_L(0); PG8_BAR; PG8_MMA(1, 0, At, B0); PG8_MMA(1, 1, At, B1); PG8_BAR; PG8_SCHED;
;             PG8_LDB(B0, 1, 0); PG8_LDB(B1, 1, 1); PG8_SCHED; PG8_LDA(At, 1, 0); PG8_STAGE(PG8_SA(0, 1), a2 + hstepA, voffA);
;             PG8_WAIT_V(8); PG8_WAIT_L(0); PG8_BAR; PG8_MMA(0, 0, At, B0); PG8_MMA(0, 1, At, B1); PG8_BAR; PG8_SCHED;
;             PG8_LDA(At, 1, 1); PG8_STAGE(PG8_SB(1, 0), b3, voffB); PG8_STAGE(PG8_SB(1, 1), b3 + hstepB, voffB); PG8_STAGE(PG8_SA(1, 0), a3, voffA);
;             PG8_WAIT_V(8); PG8_WAIT_L(0); PG8_BAR; PG8_MMA(1, 0, At, B0); PG8_MMA(1, 1, At, B1); PG8_BAR; PG8_SCHED;
	s_setprio 0
	s_mov_b32 m0, s53
	s_add_i32 s74, s16, 0x80
	ds_read_b128 v[170:173], v140 offset:49152
	ds_read_b128 v[174:177], v140 offset:50176
	ds_read_b128 v[178:181], v140 offset:51200
	ds_read_b128 v[182:185], v140 offset:52224
	ds_read_b128 v[186:189], v140 offset:53248
	ds_read_b128 v[190:193], v140 offset:54272
	ds_read_b128 v[200:203], v140 offset:55296
	ds_read_b128 v[206:209], v140 offset:56320
	buffer_load_dwordx4 v134, s[40:43], s74 offen lds
	s_mov_b32 m0, s60
	s_add_i32 s16, s16, 0x80080
	buffer_load_dwordx4 v136, s[40:43], s74 offen lds
	s_mov_b32 m0, s63
	s_addk_i32 s17, 0x80
	buffer_load_dwordx4 v134, s[40:43], s16 offen lds
	s_mov_b32 m0, s66
	s_nop 0
	buffer_load_dwordx4 v136, s[40:43], s16 offen lds
	s_mov_b32 m0, s61
	s_nop 0
	buffer_load_dwordx4 v0, s[4:7], s17 offen lds
	s_waitcnt vmcnt(7)
	s_waitcnt lgkmcnt(0)
	s_setprio 1
	s_barrier
	v_mfma_f32_16x16x32_bf16 v[62:65], v[130:133], v[170:173], v[62:65]
	v_mfma_f32_16x16x32_bf16 v[58:61], v[146:149], v[170:173], v[58:61]
	v_mfma_f32_16x16x32_bf16 v[42:45], v[146:149], v[178:181], v[42:45]
	v_mfma_f32_16x16x32_bf16 v[46:49], v[130:133], v[178:181], v[46:49]
	v_mfma_f32_16x16x32_bf16 v[30:33], v[130:133], v[186:189], v[30:33]
	v_mfma_f32_16x16x32_bf16 v[26:29], v[146:149], v[186:189], v[26:29]
	v_mfma_f32_16x16x32_bf16 v[10:13], v[146:149], v[200:203], v[10:13]
	v_mfma_f32_16x16x32_bf16 v[14:17], v[130:133], v[200:203], v[14:17]
	v_mfma_f32_16x16x32_bf16 v[6:9], v[154:157], v[200:203], v[6:9]
	v_mfma_f32_16x16x32_bf16 v[2:5], v[162:165], v[200:203], v[2:5]
	v_mfma_f32_16x16x32_bf16 v[18:21], v[162:165], v[186:189], v[18:21]
	v_mfma_f32_16x16x32_bf16 v[22:25], v[154:157], v[186:189], v[22:25]
	v_mfma_f32_16x16x32_bf16 v[38:41], v[154:157], v[178:181], v[38:41]
	v_mfma_f32_16x16x32_bf16 v[34:37], v[162:165], v[178:181], v[34:37]
	v_mfma_f32_16x16x32_bf16 v[50:53], v[162:165], v[170:173], v[50:53]
	v_mfma_f32_16x16x32_bf16 v[54:57], v[154:157], v[170:173], v[54:57]
	v_mfma_f32_16x16x32_bf16 v[62:65], v[142:145], v[174:177], v[62:65]
	v_mfma_f32_16x16x32_bf16 v[58:61], v[150:153], v[174:177], v[58:61]
	v_mfma_f32_16x16x32_bf16 v[42:45], v[150:153], v[182:185], v[42:45]
	v_mfma_f32_16x16x32_bf16 v[46:49], v[142:145], v[182:185], v[46:49]
	v_mfma_f32_16x16x32_bf16 v[30:33], v[142:145], v[190:193], v[30:33]
	v_mfma_f32_16x16x32_bf16 v[26:29], v[150:153], v[190:193], v[26:29]
	v_mfma_f32_16x16x32_bf16 v[10:13], v[150:153], v[206:209], v[10:13]
	v_mfma_f32_16x16x32_bf16 v[14:17], v[142:145], v[206:209], v[14:17]
	v_mfma_f32_16x16x32_bf16 v[6:9], v[158:161], v[206:209], v[6:9]
	v_mfma_f32_16x16x32_bf16 v[2:5], v[166:169], v[206:209], v[2:5]
	v_mfma_f32_16x16x32_bf16 v[18:21], v[166:169], v[190:193], v[18:21]
	v_mfma_f32_16x16x32_bf16 v[22:25], v[158:161], v[190:193], v[22:25]
	v_mfma_f32_16x16x32_bf16 v[38:41], v[158:161], v[182:185], v[38:41]
	v_mfma_f32_16x16x32_bf16 v[34:37], v[166:169], v[182:185], v[34:37]
	v_mfma_f32_16x16x32_bf16 v[50:53], v[166:169], v[174:177], v[50:53]
	v_mfma_f32_16x16x32_bf16 v[54:57], v[158:161], v[174:177], v[54:57]
	s_barrier
	s_setprio 0
	s_add_i32 s73, s73, 2
	s_add_u32 s19, s19, 0x100
	s_addc_u32 s21, s21, 0
	s_cmp_gt_u32 s73, 29
	s_mov_b64 s[16:17], s[38:39]
.LBB0_1514:
	v_add_u32_e32 v141, 0x10000, v139
	ds_read_b128 v[130:133], v141
	ds_read_b128 v[142:145], v141 offset:1024
	ds_read_b128 v[146:149], v141 offset:2048
	ds_read_b128 v[150:153], v141 offset:3072
	v_add_u32_e32 v141, 0x14000, v139
	ds_read_b128 v[154:157], v141
	ds_read_b128 v[158:161], v141 offset:1024
	ds_read_b128 v[162:165], v141 offset:2048
	ds_read_b128 v[166:169], v141 offset:3072
	s_add_u32 s38, s16, 0x100
	s_addc_u32 s39, s17, 0
	s_sub_i32 s16, s16, s4
	s_add_i32 s16, s16, 0x80080
	s_sub_i32 s74, s16, 0x80000
	s_cmp_eq_u32 s73, 28
	s_cselect_b32 s17, s18, s38
	s_mov_b32 m0, s67
	ds_read_b128 v[170:173], v140
	ds_read_b128 v[174:177], v140 offset:1024
	ds_read_b128 v[178:181], v140 offset:2048
	ds_read_b128 v[182:185], v140 offset:3072
	ds_read_b128 v[186:189], v140 offset:4096
	ds_read_b128 v[190:193], v140 offset:5120
	ds_read_b128 v[200:203], v140 offset:6144
	ds_read_b128 v[206:209], v140 offset:7168
	s_mov_b32 m0, s62
	s_nop 0
	buffer_load_dwordx4 v135, s[4:7], s74 offen lds
	s_mov_b32 m0, s67
	s_nop 0
	buffer_load_dwordx4 v0, s[4:7], s16 offen lds
	s_mov_b32 m0, s68
	s_nop 0
	buffer_load_dwordx4 v135, s[4:7], s16 offen lds
	s_waitcnt vmcnt(8)
	s_waitcnt lgkmcnt(0)
	s_setprio 1
	s_barrier
	v_mfma_f32_16x16x32_bf16 v[126:129], v[130:133], v[170:173], v[126:129]
	v_mfma_f32_16x16x32_bf16 v[122:125], v[146:149], v[170:173], v[122:125]
	v_mfma_f32_16x16x32_bf16 v[106:109], v[146:149], v[178:181], v[106:109]
	v_mfma_f32_16x16x32_bf16 v[110:113], v[130:133], v[178:181], v[110:113]
	v_mfma_f32_16x16x32_bf16 v[94:97], v[130:133], v[186:189], v[94:97]
	v_mfma_f32_16x16x32_bf16 v[90:93], v[146:149], v[186:189], v[90:93]
	v_mfma_f32_16x16x32_bf16 v[74:77], v[146:149], v[200:203], v[74:77]
	v_mfma_f32_16x16x32_bf16 v[78:81], v[130:133], v[200:203], v[78:81]
	v_mfma_f32_16x16x32_bf16 v[70:73], v[154:157], v[200:203], v[70:73]
	v_mfma_f32_16x16x32_bf16 v[66:69], v[162:165], v[200:203], v[66:69]
	v_mfma_f32_16x16x32_bf16 v[82:85], v[162:165], v[186:189], v[82:85]
	v_mfma_f32_16x16x32_bf16 v[86:89], v[154:157], v[186:189], v[86:89]
	v_mfma_f32_16x16x32_bf16 v[102:105], v[154:157], v[178:181], v[102:105]
	v_mfma_f32_16x16x32_bf16 v[98:101], v[162:165], v[178:181], v[98:101]
	v_mfma_f32_16x16x32_bf16 v[114:117], v[162:165], v[170:173], v[114:117]
	v_mfma_f32_16x16x32_bf16 v[118:121], v[154:157], v[170:173], v[118:121]
	v_mfma_f32_16x16x32_bf16 v[126:129], v[142:145], v[174:177], v[126:129]
	v_mfma_f32_16x16x32_bf16 v[122:125], v[150:153], v[174:177], v[122:125]
	v_mfma_f32_16x16x32_bf16 v[106:109], v[150:153], v[182:185], v[106:109]
	v_mfma_f32_16x16x32_bf16 v[110:113], v[142:145], v[182:185], v[110:113]
	v_mfma_f32_16x16x32_bf16 v[94:97], v[142:145], v[190:193], v[94:97]
	v_mfma_f32_16x16x32_bf16 v[90:93], v[150:153], v[190:193], v[90:93]
	v_mfma_f32_16x16x32_bf16 v[74:77], v[150:153], v[206:209], v[74:77]
	v_mfma_f32_16x16x32_bf16 v[78:81], v[142:145], v[206:209], v[78:81]
	v_mfma_f32_16x16x32_bf16 v[70:73], v[158:161], v[206:209], v[70:73]
	v_mfma_f32_16x16x32_bf16 v[66:69], v[166:169], v[206:209], v[66:69]
	v_mfma_f32_16x16x32_bf16 v[82:85], v[166:169], v[190:193], v[82:85]
	v_mfma_f32_16x16x32_bf16 v[86:89], v[158:161], v[190:193], v[86:89]
	v_mfma_f32_16x16x32_bf16 v[102:105], v[158:161], v[182:185], v[102:105]
	v_mfma_f32_16x16x32_bf16 v[98:101], v[166:169], v[182:185], v[98:101]
	v_mfma_f32_16x16x32_bf16 v[114:117], v[166:169], v[174:177], v[114:117]
	v_mfma_f32_16x16x32_bf16 v[118:121], v[158:161], v[174:177], v[118:121]
	s_barrier
; #define PG8_STAGE(bufoff, gbase, voff) do { const int so_ = (int)(unsigned)((const char*)(gbase) - base_##voff); _Pragma("unroll") for (int _i = 0; _i < 2; ++_i) \
;         __builtin_amdgcn_raw_ptr_buffer_load_lds(rs_##voff, (PG8_LAS unsigned*)(lds + (bufoff) + ldsw + _i * 8192), 16, (int)(voff)[_i], so_, 0, 0); } while (0)
; #define PG8_LDA(dst, b, h) do { _Pragma("unroll") for (int m = 0; m < 4; ++m) _Pragma("unroll") for (int k = 0; k < 2; ++k) dst[m][k] = *(const PG8_LAS bf16x8*)(lds + PG8_SA(b, h) + aoff + m * 2048 + k * 1024); } while (0)
; #define PG8_LDB(dst, b, h) do { _Pragma("unroll") for (int n = 0; n < 2; ++n) _Pragma("unroll") for (int k = 0; k < 2; ++k) dst[n][k] = *(const PG8_LAS bf16x8*)(lds + PG8_SB(b, h) + boff + n * 2048 + k * 1024); } while (0)
; #define PG8_MMA(ai, bj, At, Bt) do { __builtin_amdgcn_s_setprio(1); _Pragma("unroll") for (int m = 0; m < 4; ++m) _Pragma("unroll") for (int n = 0; n < 2; ++n) _Pragma("unroll") for (int k = 0; k < 2; ++k) \
;         acc[ai][bj][m][n] = __builtin_amdgcn_mfma_f32_16x16x32_bf16(Bt[n][k], At[m][k], acc[ai][bj][m][n], 0, 0, 0); __builtin_amdgcn_s_setprio(0); } while (0)
; #define PG8_WAIT_V(n) asm volatile("s_waitcnt vmcnt(" #n ")" ::: "memory")
; #define PG8_WAIT_L(n) asm volatile("s_waitcnt lgkmcnt(" #n ")" ::: "memory")
; #define PG8_BAR __builtin_amdgcn_s_barrier()
; #define PG8_SCHED __builtin_amdgcn_sched_barrier(0)
; template <class Epi, class Sched, bool ALIGN_EPI = false, bool SP2 = false>
; __device__ __forceinline__ void gemm_phase(PG8_LAS unsigned char* lds, const Gemm g, const Sched& S, const Epi& E, int tid_in) {
;     ...
;             PG8_LDA(At, 0, 1); PG8_STAGE(PG8_SB(0, 0), b2, voffB); PG8_STAGE(PG8_SB(0, 1), b2 + hstepB, voffB); PG8_STAGE(PG8_SA(0, 0), a2, voffA);
;             PG8_WAIT_V(8); PG8_WAIT_L(0); PG8_BAR; PG8_MMA(1, 0, At, B0); PG8_MMA(1, 1, At, B1); PG8_BAR; PG8_SCHED;
;             PG8_LDB(B0, 1, 0); PG8_LDB(B1, 1, 1); PG8_SCHED; PG8_LDA(At, 1, 0); PG8_STAGE(PG8_SA(0, 1), a2 + hstepA, voffA);
	s_setprio 0
	s_cselect_b32 s16, s15, s19
	s_mov_b32 m0, s35
	s_mov_b32 s42, s6
	s_mov_b32 s43, s7
	s_sub_i32 s16, s16, s40
	ds_read_b128 v[170:173], v140 offset:16384
	ds_read_b128 v[174:177], v140 offset:17408
	ds_read_b128 v[178:181], v140 offset:18432
	ds_read_b128 v[182:185], v140 offset:19456
	ds_read_b128 v[186:189], v140 offset:20480
	ds_read_b128 v[190:193], v140 offset:21504
	ds_read_b128 v[200:203], v140 offset:22528
	ds_read_b128 v[206:209], v140 offset:23552
	buffer_load_dwordx4 v134, s[40:43], s16 offen lds
	s_mov_b32 m0, s44
	s_add_i32 s74, s16, 0x80000
	buffer_load_dwordx4 v136, s[40:43], s16 offen lds
	s_mov_b32 m0, s45
	s_sub_i32 s17, s17, s4
	buffer_load_dwordx4 v134, s[40:43], s74 offen lds
	s_mov_b32 m0, s46
	s_nop 0
	buffer_load_dwordx4 v136, s[40:43], s74 offen lds
	s_mov_b32 m0, s34
	s_nop 0
	buffer_load_dwordx4 v0, s[4:7], s17 offen lds
	s_waitcnt vmcnt(7)
	s_waitcnt lgkmcnt(0)
	s_setprio 1
	s_barrier
	v_mfma_f32_16x16x32_bf16 v[62:65], v[130:133], v[170:173], v[62:65]
	v_mfma_f32_16x16x32_bf16 v[58:61], v[146:149], v[170:173], v[58:61]
	v_mfma_f32_16x16x32_bf16 v[42:45], v[146:149], v[178:181], v[42:45]
	v_mfma_f32_16x16x32_bf16 v[46:49], v[130:133], v[178:181], v[46:49]
	v_mfma_f32_16x16x32_bf16 v[30:33], v[130:133], v[186:189], v[30:33]
	v_mfma_f32_16x16x32_bf16 v[26:29], v[146:149], v[186:189], v[26:29]
	v_mfma_f32_16x16x32_bf16 v[10:13], v[146:149], v[200:203], v[10:13]
	v_mfma_f32_16x16x32_bf16 v[14:17], v[130:133], v[200:203], v[14:17]
	v_mfma_f32_16x16x32_bf16 v[6:9], v[154:157], v[200:203], v[6:9]
	v_mfma_f32_16x16x32_bf16 v[2:5], v[162:165], v[200:203], v[2:5]
	v_mfma_f32_16x16x32_bf16 v[18:21], v[162:165], v[186:189], v[18:21]
	v_mfma_f32_16x16x32_bf16 v[22:25], v[154:157], v[186:189], v[22:25]
	v_mfma_f32_16x16x32_bf16 v[38:41], v[154:157], v[178:181], v[38:41]
	v_mfma_f32_16x16x32_bf16 v[34:37], v[162:165], v[178:181], v[34:37]
	v_mfma_f32_16x16x32_bf16 v[50:53], v[162:165], v[170:173], v[50:53]
	v_mfma_f32_16x16x32_bf16 v[54:57], v[154:157], v[170:173], v[54:57]
	v_mfma_f32_16x16x32_bf16 v[62:65], v[142:145], v[174:177], v[62:65]
	v_mfma_f32_16x16x32_bf16 v[58:61], v[150:153], v[174:177], v[58:61]
	v_mfma_f32_16x16x32_bf16 v[42:45], v[150:153], v[182:185], v[42:45]
	v_mfma_f32_16x16x32_bf16 v[46:49], v[142:145], v[182:185], v[46:49]
	v_mfma_f32_16x16x32_bf16 v[30:33], v[142:145], v[190:193], v[30:33]
	v_mfma_f32_16x16x32_bf16 v[26:29], v[150:153], v[190:193], v[26:29]
	v_mfma_f32_16x16x32_bf16 v[10:13], v[150:153], v[206:209], v[10:13]
	v_mfma_f32_16x16x32_bf16 v[14:17], v[142:145], v[206:209], v[14:17]
	v_mfma_f32_16x16x32_bf16 v[6:9], v[158:161], v[206:209], v[6:9]
	v_mfma_f32_16x16x32_bf16 v[2:5], v[166:169], v[206:209], v[2:5]
	v_mfma_f32_16x16x32_bf16 v[18:21], v[166:169], v[190:193], v[18:21]
	v_mfma_f32_16x16x32_bf16 v[22:25], v[158:161], v[190:193], v[22:25]
	v_mfma_f32_16x16x32_bf16 v[38:41], v[158:161], v[182:185], v[38:41]
	v_mfma_f32_16x16x32_bf16 v[34:37], v[166:169], v[182:185], v[34:37]
	v_mfma_f32_16x16x32_bf16 v[50:53], v[166:169], v[174:177], v[50:53]
	v_mfma_f32_16x16x32_bf16 v[54:57], v[158:161], v[174:177], v[54:57]
	s_barrier
	s_setprio 0
	v_add_u32_e32 v141, 0x18000, v139
	ds_read_b128 v[130:133], v141
	ds_read_b128 v[142:145], v141 offset:1024
	ds_read_b128 v[146:149], v141 offset:2048
	ds_read_b128 v[150:153], v141 offset:3072
	v_add_u32_e32 v141, 0x1c000, v139
	ds_read_b128 v[154:157], v141
	ds_read_b128 v[158:161], v141 offset:1024
	ds_read_b128 v[162:165], v141 offset:2048
	ds_read_b128 v[166:169], v141 offset:3072
	s_add_i32 s74, s17, 0x80000
	s_mov_b32 m0, s48
	ds_read_b128 v[170:173], v140 offset:32768
	ds_read_b128 v[174:177], v140 offset:33792
	ds_read_b128 v[178:181], v140 offset:34816
	ds_read_b128 v[182:185], v140 offset:35840
	ds_read_b128 v[186:189], v140 offset:36864
	ds_read_b128 v[190:193], v140 offset:37888
	ds_read_b128 v[200:203], v140 offset:38912
	ds_read_b128 v[206:209], v140 offset:39936
	s_mov_b32 m0, s47
	s_nop 0
	buffer_load_dwordx4 v135, s[4:7], s17 offen lds
	s_mov_b32 m0, s48
	s_nop 0
	buffer_load_dwordx4 v0, s[4:7], s74 offen lds
	s_mov_b32 m0, s49
	s_nop 0
	buffer_load_dwordx4 v135, s[4:7], s74 offen lds
	s_waitcnt vmcnt(8)
	s_waitcnt lgkmcnt(0)
	s_setprio 1
	s_barrier
; #define PG8_STAGE(bufoff, gbase, voff) do { const int so_ = (int)(unsigned)((const char*)(gbase) - base_##voff); _Pragma("unroll") for (int _i = 0; _i < 2; ++_i) \
;         __builtin_amdgcn_raw_ptr_buffer_load_lds(rs_##voff, (PG8_LAS unsigned*)(lds + (bufoff) + ldsw + _i * 8192), 16, (int)(voff)[_i], so_, 0, 0); } while (0)
; #define PG8_LDA(dst, b, h) do { _Pragma("unroll") for (int m = 0; m < 4; ++m) _Pragma("unroll") for (int k = 0; k < 2; ++k) dst[m][k] = *(const PG8_LAS bf16x8*)(lds + PG8_SA(b, h) + aoff + m * 2048 + k * 1024); } while (0)
; #define PG8_MMA(ai, bj, At, Bt) do { __builtin_amdgcn_s_setprio(1); _Pragma("unroll") for (int m = 0; m < 4; ++m) _Pragma("unroll") for (int n = 0; n < 2; ++n) _Pragma("unroll") for (int k = 0; k < 2; ++k) \
;         acc[ai][bj][m][n] = __builtin_amdgcn_mfma_f32_16x16x32_bf16(Bt[n][k], At[m][k], acc[ai][bj][m][n], 0, 0, 0); __builtin_amdgcn_s_setprio(0); } while (0)
; #define PG8_WAIT_V(n) asm volatile("s_waitcnt vmcnt(" #n ")" ::: "memory")
; #define PG8_WAIT_L(n) asm volatile("s_waitcnt lgkmcnt(" #n ")" ::: "memory")
; #define PG8_BAR __builtin_amdgcn_s_barrier()
; #define PG8_SCHED __builtin_amdgcn_sched_barrier(0)
; template <class Epi, class Sched, bool ALIGN_EPI = false, bool SP2 = false>
; __device__ __forceinline__ void gemm_phase(PG8_LAS unsigned char* lds, const Gemm g, const Sched& S, const Epi& E, int tid_in) {
;     ...
;             PG8_WAIT_V(8); PG8_WAIT_L(0); PG8_BAR; PG8_MMA(0, 0, At, B0); PG8_MMA(0, 1, At, B1); PG8_BAR; PG8_SCHED;
;             PG8_LDA(At, 1, 1); PG8_STAGE(PG8_SB(1, 0), b3, voffB); PG8_STAGE(PG8_SB(1, 1), b3 + hstepB, voffB); PG8_STAGE(PG8_SA(1, 0), a3, voffA);
;             PG8_WAIT_V(8); PG8_WAIT_L(0); PG8_BAR; PG8_MMA(1, 0, At, B0); PG8_MMA(1, 1, At, B1); PG8_BAR; PG8_SCHED;
;     ...
;         if constexpr (ALIGN_EPI) { if (wr == 0) PG8_BAR; }
	v_mfma_f32_16x16x32_bf16 v[126:129], v[130:133], v[170:173], v[126:129]
	v_mfma_f32_16x16x32_bf16 v[122:125], v[146:149], v[170:173], v[122:125]
	v_mfma_f32_16x16x32_bf16 v[106:109], v[146:149], v[178:181], v[106:109]
	v_mfma_f32_16x16x32_bf16 v[110:113], v[130:133], v[178:181], v[110:113]
	v_mfma_f32_16x16x32_bf16 v[94:97], v[130:133], v[186:189], v[94:97]
	v_mfma_f32_16x16x32_bf16 v[90:93], v[146:149], v[186:189], v[90:93]
	v_mfma_f32_16x16x32_bf16 v[74:77], v[146:149], v[200:203], v[74:77]
	v_mfma_f32_16x16x32_bf16 v[78:81], v[130:133], v[200:203], v[78:81]
	v_mfma_f32_16x16x32_bf16 v[70:73], v[154:157], v[200:203], v[70:73]
	v_mfma_f32_16x16x32_bf16 v[66:69], v[162:165], v[200:203], v[66:69]
	v_mfma_f32_16x16x32_bf16 v[82:85], v[162:165], v[186:189], v[82:85]
	v_mfma_f32_16x16x32_bf16 v[86:89], v[154:157], v[186:189], v[86:89]
	v_mfma_f32_16x16x32_bf16 v[102:105], v[154:157], v[178:181], v[102:105]
	v_mfma_f32_16x16x32_bf16 v[98:101], v[162:165], v[178:181], v[98:101]
	v_mfma_f32_16x16x32_bf16 v[114:117], v[162:165], v[170:173], v[114:117]
	v_mfma_f32_16x16x32_bf16 v[118:121], v[154:157], v[170:173], v[118:121]
	v_mfma_f32_16x16x32_bf16 v[126:129], v[142:145], v[174:177], v[126:129]
	v_mfma_f32_16x16x32_bf16 v[122:125], v[150:153], v[174:177], v[122:125]
	v_mfma_f32_16x16x32_bf16 v[106:109], v[150:153], v[182:185], v[106:109]
	v_mfma_f32_16x16x32_bf16 v[110:113], v[142:145], v[182:185], v[110:113]
	v_mfma_f32_16x16x32_bf16 v[94:97], v[142:145], v[190:193], v[94:97]
	v_mfma_f32_16x16x32_bf16 v[90:93], v[150:153], v[190:193], v[90:93]
	v_mfma_f32_16x16x32_bf16 v[74:77], v[150:153], v[206:209], v[74:77]
	v_mfma_f32_16x16x32_bf16 v[78:81], v[142:145], v[206:209], v[78:81]
	v_mfma_f32_16x16x32_bf16 v[70:73], v[158:161], v[206:209], v[70:73]
	v_mfma_f32_16x16x32_bf16 v[66:69], v[166:169], v[206:209], v[66:69]
	v_mfma_f32_16x16x32_bf16 v[82:85], v[166:169], v[190:193], v[82:85]
	v_mfma_f32_16x16x32_bf16 v[86:89], v[158:161], v[190:193], v[86:89]
	v_mfma_f32_16x16x32_bf16 v[102:105], v[158:161], v[182:185], v[102:105]
	v_mfma_f32_16x16x32_bf16 v[98:101], v[166:169], v[182:185], v[98:101]
	v_mfma_f32_16x16x32_bf16 v[114:117], v[166:169], v[174:177], v[114:117]
	v_mfma_f32_16x16x32_bf16 v[118:121], v[158:161], v[174:177], v[118:121]
	s_barrier
	s_setprio 0
	s_mov_b32 m0, s53
	s_add_i32 s74, s16, 0x80
	ds_read_b128 v[170:173], v140 offset:49152
	ds_read_b128 v[174:177], v140 offset:50176
	ds_read_b128 v[178:181], v140 offset:51200
	ds_read_b128 v[182:185], v140 offset:52224
	ds_read_b128 v[186:189], v140 offset:53248
	ds_read_b128 v[190:193], v140 offset:54272
	ds_read_b128 v[200:203], v140 offset:55296
	ds_read_b128 v[206:209], v140 offset:56320
	buffer_load_dwordx4 v134, s[40:43], s74 offen lds
	s_mov_b32 m0, s60
	s_add_i32 s16, s16, 0x80080
	buffer_load_dwordx4 v136, s[40:43], s74 offen lds
	s_mov_b32 m0, s63
	s_addk_i32 s17, 0x80
	buffer_load_dwordx4 v134, s[40:43], s16 offen lds
	s_mov_b32 m0, s66
	s_nop 0
	buffer_load_dwordx4 v136, s[40:43], s16 offen lds
	s_mov_b32 m0, s61
	s_nop 0
	buffer_load_dwordx4 v0, s[4:7], s17 offen lds
	s_waitcnt vmcnt(7)
	s_waitcnt lgkmcnt(0)
	s_setprio 1
	s_barrier
	v_mfma_f32_16x16x32_bf16 v[62:65], v[130:133], v[170:173], v[62:65]
	v_mfma_f32_16x16x32_bf16 v[58:61], v[146:149], v[170:173], v[58:61]
	v_mfma_f32_16x16x32_bf16 v[42:45], v[146:149], v[178:181], v[42:45]
	v_mfma_f32_16x16x32_bf16 v[46:49], v[130:133], v[178:181], v[46:49]
	v_mfma_f32_16x16x32_bf16 v[30:33], v[130:133], v[186:189], v[30:33]
	v_mfma_f32_16x16x32_bf16 v[26:29], v[146:149], v[186:189], v[26:29]
	v_mfma_f32_16x16x32_bf16 v[10:13], v[146:149], v[200:203], v[10:13]
	v_mfma_f32_16x16x32_bf16 v[14:17], v[130:133], v[200:203], v[14:17]
	v_mfma_f32_16x16x32_bf16 v[6:9], v[154:157], v[200:203], v[6:9]
	v_mfma_f32_16x16x32_bf16 v[2:5], v[162:165], v[200:203], v[2:5]
	v_mfma_f32_16x16x32_bf16 v[18:21], v[162:165], v[186:189], v[18:21]
	v_mfma_f32_16x16x32_bf16 v[22:25], v[154:157], v[186:189], v[22:25]
	v_mfma_f32_16x16x32_bf16 v[38:41], v[154:157], v[178:181], v[38:41]
	v_mfma_f32_16x16x32_bf16 v[34:37], v[162:165], v[178:181], v[34:37]
	v_mfma_f32_16x16x32_bf16 v[50:53], v[162:165], v[170:173], v[50:53]
	v_mfma_f32_16x16x32_bf16 v[54:57], v[154:157], v[170:173], v[54:57]
	v_mfma_f32_16x16x32_bf16 v[62:65], v[142:145], v[174:177], v[62:65]
	v_mfma_f32_16x16x32_bf16 v[58:61], v[150:153], v[174:177], v[58:61]
	v_mfma_f32_16x16x32_bf16 v[42:45], v[150:153], v[182:185], v[42:45]
	v_mfma_f32_16x16x32_bf16 v[46:49], v[142:145], v[182:185], v[46:49]
	v_mfma_f32_16x16x32_bf16 v[30:33], v[142:145], v[190:193], v[30:33]
	v_mfma_f32_16x16x32_bf16 v[26:29], v[150:153], v[190:193], v[26:29]
	v_mfma_f32_16x16x32_bf16 v[10:13], v[150:153], v[206:209], v[10:13]
	v_mfma_f32_16x16x32_bf16 v[14:17], v[142:145], v[206:209], v[14:17]
	v_mfma_f32_16x16x32_bf16 v[6:9], v[158:161], v[206:209], v[6:9]
	v_mfma_f32_16x16x32_bf16 v[2:5], v[166:169], v[206:209], v[2:5]
	v_mfma_f32_16x16x32_bf16 v[18:21], v[166:169], v[190:193], v[18:21]
	v_mfma_f32_16x16x32_bf16 v[22:25], v[158:161], v[190:193], v[22:25]
	v_mfma_f32_16x16x32_bf16 v[38:41], v[158:161], v[182:185], v[38:41]
	v_mfma_f32_16x16x32_bf16 v[34:37], v[166:169], v[182:185], v[34:37]
	v_mfma_f32_16x16x32_bf16 v[50:53], v[166:169], v[174:177], v[50:53]
	v_mfma_f32_16x16x32_bf16 v[54:57], v[158:161], v[174:177], v[54:57]
	s_barrier
	s_setprio 0
	s_add_i32 s73, s73, 2
	s_add_u32 s19, s19, 0x100
	s_addc_u32 s21, s21, 0
	s_cmp_gt_u32 s73, 29
	s_mov_b64 s[16:17], s[38:39]
	s_cbranch_scc0 .LBB0_1514
	s_and_b64 vcc, exec, s[12:13]
	s_cbranch_vccz .LBB0_1517
	s_barrier

; #define PG8_STAGE(bufoff, gbase, voff) do { const int so_ = (int)(unsigned)((const char*)(gbase) - base_##voff); _Pragma("unroll") for (int _i = 0; _i < 2; ++_i) \
;         __builtin_amdgcn_raw_ptr_buffer_load_lds(rs_##voff, (PG8_LAS unsigned*)(lds + (bufoff) + ldsw + _i * 8192), 16, (int)(voff)[_i], so_, 0, 0); } while (0)
; #define PG8_LDA(dst, b, h) do { _Pragma("unroll") for (int m = 0; m < 4; ++m) _Pragma("unroll") for (int k = 0; k < 2; ++k) dst[m][k] = *(const PG8_LAS bf16x8*)(lds + PG8_SA(b, h) + aoff + m * 2048 + k * 1024); } while (0)
; #define PG8_LDB(dst, b, h) do { _Pragma("unroll") for (int n = 0; n < 2; ++n) _Pragma("unroll") for (int k = 0; k < 2; ++k) dst[n][k] = *(const PG8_LAS bf16x8*)(lds + PG8_SB(b, h) + boff + n * 2048 + k * 1024); } while (0)
; #define PG8_MMA(ai, bj, At, Bt) do { __builtin_amdgcn_s_setprio(1); _Pragma("unroll") for (int m = 0; m < 4; ++m) _Pragma("unroll") for (int n = 0; n < 2; ++n) _Pragma("unroll") for (int k = 0; k < 2; ++k) \
;         acc[ai][bj][m][n] = __builtin_amdgcn_mfma_f32_16x16x32_bf16(Bt[n][k], At[m][k], acc[ai][bj][m][n], 0, 0, 0); __builtin_amdgcn_s_setprio(0); } while (0)
; #define PG8_WAIT_V(n) asm volatile("s_waitcnt vmcnt(" #n ")" ::: "memory")
; #define PG8_WAIT_L(n) asm volatile("s_waitcnt lgkmcnt(" #n ")" ::: "memory")
; #define PG8_BAR __builtin_amdgcn_s_barrier()
; #define PG8_SCHED __builtin_amdgcn_sched_barrier(0)
; template <class Epi, class Sched, bool ALIGN_EPI = false, bool SP2 = false>
; __device__ __forceinline__ void gemm_phase(PG8_LAS unsigned char* lds, const Gemm g, const Sched& S, const Epi& E, int tid_in) {
;     ...
;             PG8_LDB(B0, 0, 0); PG8_LDB(B1, 0, 1); PG8_SCHED; PG8_LDA(At, 0, 0); PG8_STAGE(PG8_SA(1, 1), a1 + hstepA, voffA);
;             PG8_WAIT_V(8); PG8_WAIT_L(0); PG8_BAR; PG8_MMA(0, 0, At, B0); PG8_MMA(0, 1, At, B1); PG8_BAR; PG8_SCHED;
;             PG8_LDA(At, 0, 1); PG8_STAGE(PG8_SB(0, 0), b2, voffB); PG8_STAGE(PG8_SB(0, 1), b2 + hstepB, voffB); PG8_STAGE(PG8_SA(0, 0), a2, voffA);
;             PG8_WAIT_V(8); PG8_WAIT_L(0); PG8_BAR; PG8_MMA(1, 0, At, B0); PG8_MMA(1, 1, At, B1); PG8_BAR; PG8_SCHED;
.LBB0_1584:
	v_add_u32_e32 v133, 0x10000, v131
	ds_read_b128 v[134:137], v133
	ds_read_b128 v[138:141], v133 offset:1024
	ds_read_b128 v[142:145], v133 offset:2048
	ds_read_b128 v[146:149], v133 offset:3072
	v_add_u32_e32 v133, 0x14000, v131
	ds_read_b128 v[150:153], v133
	ds_read_b128 v[154:157], v133 offset:1024
	ds_read_b128 v[158:161], v133 offset:2048
	ds_read_b128 v[166:169], v133 offset:3072
	s_add_i32 s43, s38, s22
	s_add_i32 s42, s14, s22
	s_add_i32 s76, s12, s22
	s_addk_i32 s43, 0xff80
	s_sub_i32 s78, s43, 0x160000
	s_cmpk_eq_i32 s39, 0x54
	s_cselect_b32 s77, s16, s42
	s_mov_b32 m0, s68
	ds_read_b128 v[170:173], v132
	ds_read_b128 v[174:177], v132 offset:1024
	ds_read_b128 v[178:181], v132 offset:2048
	ds_read_b128 v[182:185], v132 offset:3072
	ds_read_b128 v[186:189], v132 offset:4096
	ds_read_b128 v[190:193], v132 offset:5120
	ds_read_b128 v[200:203], v132 offset:6144
	ds_read_b128 v[206:209], v132 offset:7168
	s_mov_b32 m0, s63
	s_nop 0
	buffer_load_dwordx4 v130, s[4:7], s78 offen lds
	s_mov_b32 m0, s68
	s_nop 0
	buffer_load_dwordx4 v0, s[4:7], s43 offen lds
	s_mov_b32 m0, s69
	s_nop 0
	buffer_load_dwordx4 v130, s[4:7], s43 offen lds
	s_waitcnt vmcnt(8)
	s_waitcnt lgkmcnt(0)
	s_setprio 1
	s_barrier
	v_mfma_f32_16x16x32_bf16 v[22:25], v[134:137], v[170:173], v[22:25]
	v_mfma_f32_16x16x32_bf16 v[14:17], v[142:145], v[170:173], v[14:17]
	v_mfma_f32_16x16x32_bf16 v[54:57], v[142:145], v[178:181], v[54:57]
	v_mfma_f32_16x16x32_bf16 v[74:77], v[134:137], v[178:181], v[74:77]
	v_mfma_f32_16x16x32_bf16 v[106:109], v[134:137], v[186:189], v[106:109]
	v_mfma_f32_16x16x32_bf16 v[102:105], v[142:145], v[186:189], v[102:105]
	v_mfma_f32_16x16x32_bf16 v[118:121], v[142:145], v[200:203], v[118:121]
	v_mfma_f32_16x16x32_bf16 v[122:125], v[134:137], v[200:203], v[122:125]
	v_mfma_f32_16x16x32_bf16 v[114:117], v[150:153], v[200:203], v[114:117]
	v_mfma_f32_16x16x32_bf16 v[126:129], v[158:161], v[200:203], v[126:129]
	v_mfma_f32_16x16x32_bf16 v[110:113], v[158:161], v[186:189], v[110:113]
	v_mfma_f32_16x16x32_bf16 v[98:101], v[150:153], v[186:189], v[98:101]
	v_mfma_f32_16x16x32_bf16 v[50:53], v[150:153], v[178:181], v[50:53]
	v_mfma_f32_16x16x32_bf16 v[78:81], v[158:161], v[178:181], v[78:81]
	v_mfma_f32_16x16x32_bf16 v[18:21], v[158:161], v[170:173], v[18:21]
	v_mfma_f32_16x16x32_bf16 v[6:9], v[150:153], v[170:173], v[6:9]
	v_mfma_f32_16x16x32_bf16 v[22:25], v[138:141], v[174:177], v[22:25]
	v_mfma_f32_16x16x32_bf16 v[14:17], v[146:149], v[174:177], v[14:17]
	v_mfma_f32_16x16x32_bf16 v[54:57], v[146:149], v[182:185], v[54:57]
	v_mfma_f32_16x16x32_bf16 v[74:77], v[138:141], v[182:185], v[74:77]
	v_mfma_f32_16x16x32_bf16 v[106:109], v[138:141], v[190:193], v[106:109]
	v_mfma_f32_16x16x32_bf16 v[102:105], v[146:149], v[190:193], v[102:105]
	v_mfma_f32_16x16x32_bf16 v[118:121], v[146:149], v[206:209], v[118:121]
	v_mfma_f32_16x16x32_bf16 v[122:125], v[138:141], v[206:209], v[122:125]
	v_mfma_f32_16x16x32_bf16 v[114:117], v[154:157], v[206:209], v[114:117]
	v_mfma_f32_16x16x32_bf16 v[126:129], v[166:169], v[206:209], v[126:129]
	v_mfma_f32_16x16x32_bf16 v[110:113], v[166:169], v[190:193], v[110:113]
	v_mfma_f32_16x16x32_bf16 v[98:101], v[154:157], v[190:193], v[98:101]
	v_mfma_f32_16x16x32_bf16 v[50:53], v[154:157], v[182:185], v[50:53]
	v_mfma_f32_16x16x32_bf16 v[78:81], v[166:169], v[182:185], v[78:81]
	v_mfma_f32_16x16x32_bf16 v[18:21], v[166:169], v[174:177], v[18:21]
	v_mfma_f32_16x16x32_bf16 v[6:9], v[154:157], v[174:177], v[6:9]
	s_barrier
	s_setprio 0
	s_cselect_b32 s76, s20, s76
	s_mov_b32 m0, s26
	s_mov_b32 s42, s6
	s_mov_b32 s43, s7
	s_sub_i32 s76, s76, s40
	ds_read_b128 v[170:173], v132 offset:16384
	ds_read_b128 v[174:177], v132 offset:17408
	ds_read_b128 v[178:181], v132 offset:18432
	ds_read_b128 v[182:185], v132 offset:19456
	ds_read_b128 v[186:189], v132 offset:20480
	ds_read_b128 v[190:193], v132 offset:21504
	ds_read_b128 v[200:203], v132 offset:22528
	ds_read_b128 v[206:209], v132 offset:23552
	buffer_load_dwordx4 v0, s[40:43], s76 offen lds
	s_mov_b32 m0, s44
	s_add_i32 s78, s76, 0x160000
	buffer_load_dwordx4 v130, s[40:43], s76 offen lds
	s_mov_b32 m0, s45
	s_sub_i32 s77, s77, s4
	buffer_load_dwordx4 v0, s[40:43], s78 offen lds
	s_mov_b32 m0, s46
	s_nop 0
	buffer_load_dwordx4 v130, s[40:43], s78 offen lds
	s_mov_b32 m0, s19
	s_nop 0
	buffer_load_dwordx4 v0, s[4:7], s77 offen lds
	s_waitcnt vmcnt(7)
	s_waitcnt lgkmcnt(0)
	s_setprio 1
	s_barrier
	v_mfma_f32_16x16x32_bf16 v[62:65], v[134:137], v[170:173], v[62:65]
	v_mfma_f32_16x16x32_bf16 v[46:49], v[142:145], v[170:173], v[46:49]
	v_mfma_f32_16x16x32_bf16 v[70:73], v[142:145], v[178:181], v[70:73]
	v_mfma_f32_16x16x32_bf16 v[82:85], v[134:137], v[178:181], v[82:85]
	v_mfma_f32_16x16x32_bf16 v[94:97], v[134:137], v[186:189], v[94:97]
	v_mfma_f32_16x16x32_bf16 v[90:93], v[142:145], v[186:189], v[90:93]
	v_mfma_f32_16x16x32_bf16 v[26:29], v[142:145], v[200:203], v[26:29]
	v_mfma_f32_16x16x32_bf16 v[38:41], v[134:137], v[200:203], v[38:41]
	v_mfma_f32_16x16x32_bf16 v[10:13], v[150:153], v[200:203], v[10:13]
	v_mfma_f32_16x16x32_bf16 v[2:5], v[158:161], v[200:203], v[2:5]
	v_mfma_f32_16x16x32_bf16 v[34:37], v[158:161], v[186:189], v[34:37]
	v_mfma_f32_16x16x32_bf16 v[58:61], v[150:153], v[186:189], v[58:61]
	v_mfma_f32_16x16x32_bf16 v[66:69], v[150:153], v[178:181], v[66:69]
	v_mfma_f32_16x16x32_bf16 v[86:89], v[158:161], v[178:181], v[86:89]
	v_mfma_f32_16x16x32_bf16 v[30:33], v[158:161], v[170:173], v[30:33]
	v_mfma_f32_16x16x32_bf16 v[42:45], v[150:153], v[170:173], v[42:45]
	v_mfma_f32_16x16x32_bf16 v[62:65], v[138:141], v[174:177], v[62:65]
	v_mfma_f32_16x16x32_bf16 v[46:49], v[146:149], v[174:177], v[46:49]
	v_mfma_f32_16x16x32_bf16 v[70:73], v[146:149], v[182:185], v[70:73]
	v_mfma_f32_16x16x32_bf16 v[82:85], v[138:141], v[182:185], v[82:85]
	v_mfma_f32_16x16x32_bf16 v[94:97], v[138:141], v[190:193], v[94:97]
	v_mfma_f32_16x16x32_bf16 v[90:93], v[146:149], v[190:193], v[90:93]
	v_mfma_f32_16x16x32_bf16 v[26:29], v[146:149], v[206:209], v[26:29]
	v_mfma_f32_16x16x32_bf16 v[38:41], v[138:141], v[206:209], v[38:41]
	v_mfma_f32_16x16x32_bf16 v[10:13], v[154:157], v[206:209], v[10:13]
	v_mfma_f32_16x16x32_bf16 v[2:5], v[166:169], v[206:209], v[2:5]
	v_mfma_f32_16x16x32_bf16 v[34:37], v[166:169], v[190:193], v[34:37]
	v_mfma_f32_16x16x32_bf16 v[58:61], v[154:157], v[190:193], v[58:61]
	v_mfma_f32_16x16x32_bf16 v[66:69], v[154:157], v[182:185], v[66:69]
	v_mfma_f32_16x16x32_bf16 v[86:89], v[166:169], v[182:185], v[86:89]
	v_mfma_f32_16x16x32_bf16 v[30:33], v[166:169], v[174:177], v[30:33]
	v_mfma_f32_16x16x32_bf16 v[42:45], v[154:157], v[174:177], v[42:45]
	s_barrier
; #define PG8_STAGE(bufoff, gbase, voff) do { const int so_ = (int)(unsigned)((const char*)(gbase) - base_##voff); _Pragma("unroll") for (int _i = 0; _i < 2; ++_i) \
;         __builtin_amdgcn_raw_ptr_buffer_load_lds(rs_##voff, (PG8_LAS unsigned*)(lds + (bufoff) + ldsw + _i * 8192), 16, (int)(voff)[_i], so_, 0, 0); } while (0)
; #define PG8_LDA(dst, b, h) do { _Pragma("unroll") for (int m = 0; m < 4; ++m) _Pragma("unroll") for (int k = 0; k < 2; ++k) dst[m][k] = *(const PG8_LAS bf16x8*)(lds + PG8_SA(b, h) + aoff + m * 2048 + k * 1024); } while (0)
; #define PG8_LDB(dst, b, h) do { _Pragma("unroll") for (int n = 0; n < 2; ++n) _Pragma("unroll") for (int k = 0; k < 2; ++k) dst[n][k] = *(const PG8_LAS bf16x8*)(lds + PG8_SB(b, h) + boff + n * 2048 + k * 1024); } while (0)
; #define PG8_MMA(ai, bj, At, Bt) do { __builtin_amdgcn_s_setprio(1); _Pragma("unroll") for (int m = 0; m < 4; ++m) _Pragma("unroll") for (int n = 0; n < 2; ++n) _Pragma("unroll") for (int k = 0; k < 2; ++k) \
;         acc[ai][bj][m][n] = __builtin_amdgcn_mfma_f32_16x16x32_bf16(Bt[n][k], At[m][k], acc[ai][bj][m][n], 0, 0, 0); __builtin_amdgcn_s_setprio(0); } while (0)
; #define PG8_WAIT_V(n) asm volatile("s_waitcnt vmcnt(" #n ")" ::: "memory")
; #define PG8_WAIT_L(n) asm volatile("s_waitcnt lgkmcnt(" #n ")" ::: "memory")
; #define PG8_BAR __builtin_amdgcn_s_barrier()
; #define PG8_SCHED __builtin_amdgcn_sched_barrier(0)
; template <class Epi, class Sched, bool ALIGN_EPI = false, bool SP2 = false>
; __device__ __forceinline__ void gemm_phase(PG8_LAS unsigned char* lds, const Gemm g, const Sched& S, const Epi& E, int tid_in) {
;     ...
;             PG8_LDB(B0, 1, 0); PG8_LDB(B1, 1, 1); PG8_SCHED; PG8_LDA(At, 1, 0); PG8_STAGE(PG8_SA(0, 1), a2 + hstepA, voffA);
;             PG8_WAIT_V(8); PG8_WAIT_L(0); PG8_BAR; PG8_MMA(0, 0, At, B0); PG8_MMA(0, 1, At, B1); PG8_BAR; PG8_SCHED;
;             PG8_LDA(At, 1, 1); PG8_STAGE(PG8_SB(1, 0), b3, voffB); PG8_STAGE(PG8_SB(1, 1), b3 + hstepB, voffB); PG8_STAGE(PG8_SA(1, 0), a3, voffA);
	s_setprio 0
	v_add_u32_e32 v133, 0x18000, v131
	ds_read_b128 v[134:137], v133
	ds_read_b128 v[138:141], v133 offset:1024
	ds_read_b128 v[142:145], v133 offset:2048
	ds_read_b128 v[146:149], v133 offset:3072
	v_add_u32_e32 v133, 0x1c000, v131
	ds_read_b128 v[150:153], v133
	ds_read_b128 v[154:157], v133 offset:1024
	ds_read_b128 v[158:161], v133 offset:2048
	ds_read_b128 v[166:169], v133 offset:3072
	s_add_i32 s78, s77, 0x160000
	s_mov_b32 m0, s48
	ds_read_b128 v[170:173], v132 offset:32768
	ds_read_b128 v[174:177], v132 offset:33792
	ds_read_b128 v[178:181], v132 offset:34816
	ds_read_b128 v[182:185], v132 offset:35840
	ds_read_b128 v[186:189], v132 offset:36864
	ds_read_b128 v[190:193], v132 offset:37888
	ds_read_b128 v[200:203], v132 offset:38912
	ds_read_b128 v[206:209], v132 offset:39936
	s_mov_b32 m0, s47
	s_nop 0
	buffer_load_dwordx4 v130, s[4:7], s77 offen lds
	s_mov_b32 m0, s48
	s_nop 0
	buffer_load_dwordx4 v0, s[4:7], s78 offen lds
	s_mov_b32 m0, s49
	s_nop 0
	buffer_load_dwordx4 v130, s[4:7], s78 offen lds
	s_waitcnt vmcnt(8)
	s_waitcnt lgkmcnt(0)
	s_setprio 1
	s_barrier
	v_mfma_f32_16x16x32_bf16 v[22:25], v[134:137], v[170:173], v[22:25]
	v_mfma_f32_16x16x32_bf16 v[14:17], v[142:145], v[170:173], v[14:17]
	v_mfma_f32_16x16x32_bf16 v[54:57], v[142:145], v[178:181], v[54:57]
	v_mfma_f32_16x16x32_bf16 v[74:77], v[134:137], v[178:181], v[74:77]
	v_mfma_f32_16x16x32_bf16 v[106:109], v[134:137], v[186:189], v[106:109]
	v_mfma_f32_16x16x32_bf16 v[102:105], v[142:145], v[186:189], v[102:105]
	v_mfma_f32_16x16x32_bf16 v[118:121], v[142:145], v[200:203], v[118:121]
	v_mfma_f32_16x16x32_bf16 v[122:125], v[134:137], v[200:203], v[122:125]
	v_mfma_f32_16x16x32_bf16 v[114:117], v[150:153], v[200:203], v[114:117]
	v_mfma_f32_16x16x32_bf16 v[126:129], v[158:161], v[200:203], v[126:129]
	v_mfma_f32_16x16x32_bf16 v[110:113], v[158:161], v[186:189], v[110:113]
	v_mfma_f32_16x16x32_bf16 v[98:101], v[150:153], v[186:189], v[98:101]
	v_mfma_f32_16x16x32_bf16 v[50:53], v[150:153], v[178:181], v[50:53]
	v_mfma_f32_16x16x32_bf16 v[78:81], v[158:161], v[178:181], v[78:81]
	v_mfma_f32_16x16x32_bf16 v[18:21], v[158:161], v[170:173], v[18:21]
	v_mfma_f32_16x16x32_bf16 v[6:9], v[150:153], v[170:173], v[6:9]
	v_mfma_f32_16x16x32_bf16 v[22:25], v[138:141], v[174:177], v[22:25]
	v_mfma_f32_16x16x32_bf16 v[14:17], v[146:149], v[174:177], v[14:17]
	v_mfma_f32_16x16x32_bf16 v[54:57], v[146:149], v[182:185], v[54:57]
	v_mfma_f32_16x16x32_bf16 v[74:77], v[138:141], v[182:185], v[74:77]
	v_mfma_f32_16x16x32_bf16 v[106:109], v[138:141], v[190:193], v[106:109]
	v_mfma_f32_16x16x32_bf16 v[102:105], v[146:149], v[190:193], v[102:105]
	v_mfma_f32_16x16x32_bf16 v[118:121], v[146:149], v[206:209], v[118:121]
	v_mfma_f32_16x16x32_bf16 v[122:125], v[138:141], v[206:209], v[122:125]
	v_mfma_f32_16x16x32_bf16 v[114:117], v[154:157], v[206:209], v[114:117]
	v_mfma_f32_16x16x32_bf16 v[126:129], v[166:169], v[206:209], v[126:129]
	v_mfma_f32_16x16x32_bf16 v[110:113], v[166:169], v[190:193], v[110:113]
	v_mfma_f32_16x16x32_bf16 v[98:101], v[154:157], v[190:193], v[98:101]
	v_mfma_f32_16x16x32_bf16 v[50:53], v[154:157], v[182:185], v[50:53]
	v_mfma_f32_16x16x32_bf16 v[78:81], v[166:169], v[182:185], v[78:81]
	v_mfma_f32_16x16x32_bf16 v[18:21], v[166:169], v[174:177], v[18:21]
	v_mfma_f32_16x16x32_bf16 v[6:9], v[154:157], v[174:177], v[6:9]
	s_barrier
	s_setprio 0
	s_mov_b32 m0, s60
	s_add_i32 s78, s76, 0x80
	ds_read_b128 v[170:173], v132 offset:49152
	ds_read_b128 v[174:177], v132 offset:50176
	ds_read_b128 v[178:181], v132 offset:51200
	ds_read_b128 v[182:185], v132 offset:52224
	ds_read_b128 v[186:189], v132 offset:53248
	ds_read_b128 v[190:193], v132 offset:54272
	ds_read_b128 v[200:203], v132 offset:55296
	ds_read_b128 v[206:209], v132 offset:56320
	buffer_load_dwordx4 v0, s[40:43], s78 offen lds
	s_mov_b32 m0, s61
	s_add_i32 s76, s76, 0x160080
	buffer_load_dwordx4 v130, s[40:43], s78 offen lds
	s_mov_b32 m0, s66
	s_addk_i32 s77, 0x80
	buffer_load_dwordx4 v0, s[40:43], s76 offen lds
	s_mov_b32 m0, s67
	s_nop 0
	buffer_load_dwordx4 v130, s[40:43], s76 offen lds
	s_mov_b32 m0, s62
	s_nop 0
	buffer_load_dwordx4 v0, s[4:7], s77 offen lds
	s_waitcnt vmcnt(7)
	s_waitcnt lgkmcnt(0)
	s_setprio 1
	s_barrier
;     static __device__ __forceinline__ bool last_of_chain(const Unit& u) { return (u.pn >> 3) == 2; }
; #define PG8_STAGE(bufoff, gbase, voff) do { const int so_ = (int)(unsigned)((const char*)(gbase) - base_##voff); _Pragma("unroll") for (int _i = 0; _i < 2; ++_i) \
;         __builtin_amdgcn_raw_ptr_buffer_load_lds(rs_##voff, (PG8_LAS unsigned*)(lds + (bufoff) + ldsw + _i * 8192), 16, (int)(voff)[_i], so_, 0, 0); } while (0)
; #define PG8_LDA(dst, b, h) do { _Pragma("unroll") for (int m = 0; m < 4; ++m) _Pragma("unroll") for (int k = 0; k < 2; ++k) dst[m][k] = *(const PG8_LAS bf16x8*)(lds + PG8_SA(b, h) + aoff + m * 2048 + k * 1024); } while (0)
; #define PG8_MMA(ai, bj, At, Bt) do { __builtin_amdgcn_s_setprio(1); _Pragma("unroll") for (int m = 0; m < 4; ++m) _Pragma("unroll") for (int n = 0; n < 2; ++n) _Pragma("unroll") for (int k = 0; k < 2; ++k) \
;         acc[ai][bj][m][n] = __builtin_amdgcn_mfma_f32_16x16x32_bf16(Bt[n][k], At[m][k], acc[ai][bj][m][n], 0, 0, 0); __builtin_amdgcn_s_setprio(0); } while (0)
; #define PG8_WAIT_V(n) asm volatile("s_waitcnt vmcnt(" #n ")" ::: "memory")
; #define PG8_WAIT_L(n) asm volatile("s_waitcnt lgkmcnt(" #n ")" ::: "memory")
; #define PG8_BAR __builtin_amdgcn_s_barrier()
; #define PG8_SCHED __builtin_amdgcn_sched_barrier(0)
; template <class Epi, class Sched, bool ALIGN_EPI = false, bool SP2 = false>
; __device__ __forceinline__ void gemm_phase(PG8_LAS unsigned char* lds, const Gemm g, const Sched& S, const Epi& E, int tid_in) {
;     ...
;             PG8_LDA(At, 1, 1); PG8_STAGE(PG8_SB(1, 0), b3, voffB); PG8_STAGE(PG8_SB(1, 1), b3 + hstepB, voffB); PG8_STAGE(PG8_SA(1, 0), a3, voffA);
;             PG8_WAIT_V(8); PG8_WAIT_L(0); PG8_BAR; PG8_MMA(1, 0, At, B0); PG8_MMA(1, 1, At, B1); PG8_BAR; PG8_SCHED;
;     ...
;         bool zero_acc = true; if constexpr (Epi::CHAIN) zero_acc = Epi::last_of_chain(cur);
;         if (zero_acc) {
; #pragma unroll
;         for (int a = 0; a < 2; ++a)
; #pragma unroll
;             for (int b = 0; b < 2; ++b)
; #pragma unroll
;                 for (int m = 0; m < 4; ++m)
; #pragma unroll
;                     for (int n = 0; n < 2; ++n) acc[a][b][m][n] = (f32x4){0.f, 0.f, 0.f, 0.f};
;         }
;         cur = nxt; cA = nA; cB = nB; ++ui;
	v_mfma_f32_16x16x32_bf16 v[62:65], v[134:137], v[170:173], v[62:65]
	v_mfma_f32_16x16x32_bf16 v[46:49], v[142:145], v[170:173], v[46:49]
	v_mfma_f32_16x16x32_bf16 v[70:73], v[142:145], v[178:181], v[70:73]
	v_mfma_f32_16x16x32_bf16 v[82:85], v[134:137], v[178:181], v[82:85]
	v_mfma_f32_16x16x32_bf16 v[94:97], v[134:137], v[186:189], v[94:97]
	v_mfma_f32_16x16x32_bf16 v[90:93], v[142:145], v[186:189], v[90:93]
	v_mfma_f32_16x16x32_bf16 v[26:29], v[142:145], v[200:203], v[26:29]
	v_mfma_f32_16x16x32_bf16 v[38:41], v[134:137], v[200:203], v[38:41]
	v_mfma_f32_16x16x32_bf16 v[10:13], v[150:153], v[200:203], v[10:13]
	v_mfma_f32_16x16x32_bf16 v[2:5], v[158:161], v[200:203], v[2:5]
	v_mfma_f32_16x16x32_bf16 v[34:37], v[158:161], v[186:189], v[34:37]
	v_mfma_f32_16x16x32_bf16 v[58:61], v[150:153], v[186:189], v[58:61]
	v_mfma_f32_16x16x32_bf16 v[66:69], v[150:153], v[178:181], v[66:69]
	v_mfma_f32_16x16x32_bf16 v[86:89], v[158:161], v[178:181], v[86:89]
	v_mfma_f32_16x16x32_bf16 v[30:33], v[158:161], v[170:173], v[30:33]
	v_mfma_f32_16x16x32_bf16 v[42:45], v[150:153], v[170:173], v[42:45]
	v_mfma_f32_16x16x32_bf16 v[62:65], v[138:141], v[174:177], v[62:65]
	v_mfma_f32_16x16x32_bf16 v[46:49], v[146:149], v[174:177], v[46:49]
	v_mfma_f32_16x16x32_bf16 v[70:73], v[146:149], v[182:185], v[70:73]
	v_mfma_f32_16x16x32_bf16 v[82:85], v[138:141], v[182:185], v[82:85]
	v_mfma_f32_16x16x32_bf16 v[94:97], v[138:141], v[190:193], v[94:97]
	v_mfma_f32_16x16x32_bf16 v[90:93], v[146:149], v[190:193], v[90:93]
	v_mfma_f32_16x16x32_bf16 v[26:29], v[146:149], v[206:209], v[26:29]
	v_mfma_f32_16x16x32_bf16 v[38:41], v[138:141], v[206:209], v[38:41]
	v_mfma_f32_16x16x32_bf16 v[10:13], v[154:157], v[206:209], v[10:13]
	v_mfma_f32_16x16x32_bf16 v[2:5], v[166:169], v[206:209], v[2:5]
	v_mfma_f32_16x16x32_bf16 v[34:37], v[166:169], v[190:193], v[34:37]
	v_mfma_f32_16x16x32_bf16 v[58:61], v[154:157], v[190:193], v[58:61]
	v_mfma_f32_16x16x32_bf16 v[66:69], v[154:157], v[182:185], v[66:69]
	v_mfma_f32_16x16x32_bf16 v[86:89], v[166:169], v[182:185], v[86:89]
	v_mfma_f32_16x16x32_bf16 v[30:33], v[166:169], v[174:177], v[30:33]
	v_mfma_f32_16x16x32_bf16 v[42:45], v[154:157], v[174:177], v[42:45]
	s_barrier
	s_setprio 0
	s_add_i32 s39, s39, 2
	s_add_u32 s22, s22, 0x100
	s_addc_u32 s23, s23, 0
	s_cmpk_gt_u32 s39, 0x55
	s_cbranch_scc0 .LBB0_1584
	s_and_b64 vcc, exec, s[36:37]
	s_cbranch_vccnz .LBB0_1572
	v_mov_b32_e32 v2, 0
	s_mov_b32 s10, s73
	s_mov_b32 s25, s74
	s_mov_b64 s[12:13], s[20:21]
	s_mov_b64 s[14:15], s[16:17]
	s_mov_b32 s72, s75
	v_mov_b32_e32 v3, v2
	v_mov_b32_e32 v4, v2
	v_mov_b32_e32 v5, v2
	v_mov_b32_e32 v10, v2
	v_mov_b32_e32 v11, v2
	v_mov_b32_e32 v12, v2
	v_mov_b32_e32 v13, v2
	v_mov_b32_e32 v34, v2
	v_mov_b32_e32 v35, v2
	v_mov_b32_e32 v36, v2
	v_mov_b32_e32 v37, v2
	v_mov_b32_e32 v58, v2
	v_mov_b32_e32 v59, v2
	v_mov_b32_e32 v60, v2
	v_mov_b32_e32 v61, v2
	v_mov_b32_e32 v86, v2
	v_mov_b32_e32 v87, v2
	v_mov_b32_e32 v88, v2
	v_mov_b32_e32 v89, v2
	v_mov_b32_e32 v66, v2
	v_mov_b32_e32 v67, v2
	v_mov_b32_e32 v68, v2
	v_mov_b32_e32 v69, v2
	v_mov_b32_e32 v30, v2
	v_mov_b32_e32 v31, v2
	v_mov_b32_e32 v32, v2
	v_mov_b32_e32 v33, v2
	v_mov_b32_e32 v42, v2
	v_mov_b32_e32 v43, v2
	v_mov_b32_e32 v44, v2
	v_mov_b32_e32 v45, v2
	v_mov_b32_e32 v26, v2
	v_mov_b32_e32 v27, v2
	v_mov_b32_e32 v28, v2
	v_mov_b32_e32 v29, v2
	v_mov_b32_e32 v38, v2
	v_mov_b32_e32 v39, v2
	v_mov_b32_e32 v40, v2
	v_mov_b32_e32 v41, v2
	v_mov_b32_e32 v90, v2
	v_mov_b32_e32 v91, v2
	v_mov_b32_e32 v92, v2
	v_mov_b32_e32 v93, v2
	v_mov_b32_e32 v94, v2
	v_mov_b32_e32 v95, v2
	v_mov_b32_e32 v96, v2
	v_mov_b32_e32 v97, v2
	v_mov_b32_e32 v70, v2
	v_mov_b32_e32 v71, v2
	v_mov_b32_e32 v72, v2
	v_mov_b32_e32 v73, v2
	v_mov_b32_e32 v82, v2
	v_mov_b32_e32 v83, v2
	v_mov_b32_e32 v84, v2
	v_mov_b32_e32 v85, v2
	v_mov_b32_e32 v46, v2
	v_mov_b32_e32 v47, v2
	v_mov_b32_e32 v48, v2
	v_mov_b32_e32 v49, v2
	v_mov_b32_e32 v62, v2
	v_mov_b32_e32 v63, v2
	v_mov_b32_e32 v64, v2
	v_mov_b32_e32 v65, v2
	v_mov_b32_e32 v126, v2
	v_mov_b32_e32 v127, v2
	v_mov_b32_e32 v128, v2
	v_mov_b32_e32 v129, v2
	v_mov_b32_e32 v114, v2
	v_mov_b32_e32 v115, v2
	v_mov_b32_e32 v116, v2
	v_mov_b32_e32 v117, v2
	v_mov_b32_e32 v110, v2
	v_mov_b32_e32 v111, v2
	v_mov_b32_e32 v112, v2
	v_mov_b32_e32 v113, v2
	v_mov_b32_e32 v98, v2
	v_mov_b32_e32 v99, v2
	v_mov_b32_e32 v100, v2
	v_mov_b32_e32 v101, v2
	v_mov_b32_e32 v78, v2
	v_mov_b32_e32 v79, v2
	v_mov_b32_e32 v80, v2
	v_mov_b32_e32 v81, v2
	v_mov_b32_e32 v50, v2
	v_mov_b32_e32 v51, v2
	v_mov_b32_e32 v52, v2
	v_mov_b32_e32 v53, v2
	v_mov_b32_e32 v18, v2
	v_mov_b32_e32 v19, v2
	v_mov_b32_e32 v20, v2
	v_mov_b32_e32 v21, v2
	v_mov_b32_e32 v6, v2
	v_mov_b32_e32 v7, v2
	v_mov_b32_e32 v8, v2
	v_mov_b32_e32 v9, v2
	v_mov_b32_e32 v118, v2
	v_mov_b32_e32 v119, v2
	v_mov_b32_e32 v120, v2
	v_mov_b32_e32 v121, v2
	v_mov_b32_e32 v122, v2
	v_mov_b32_e32 v123, v2
	v_mov_b32_e32 v124, v2
	v_mov_b32_e32 v125, v2
	v_mov_b32_e32 v102, v2
	v_mov_b32_e32 v103, v2
	v_mov_b32_e32 v104, v2
	v_mov_b32_e32 v105, v2
	v_mov_b32_e32 v106, v2
	v_mov_b32_e32 v107, v2
	v_mov_b32_e32 v108, v2
	v_mov_b32_e32 v109, v2
	v_mov_b32_e32 v54, v2
	v_mov_b32_e32 v55, v2
	v_mov_b32_e32 v56, v2
	v_mov_b32_e32 v57, v2
	v_mov_b32_e32 v74, v2
	v_mov_b32_e32 v75, v2
	v_mov_b32_e32 v76, v2
	v_mov_b32_e32 v77, v2
	v_mov_b32_e32 v14, v2
	v_mov_b32_e32 v15, v2
	v_mov_b32_e32 v16, v2
	v_mov_b32_e32 v17, v2
	v_mov_b32_e32 v22, v2
	v_mov_b32_e32 v23, v2
	v_mov_b32_e32 v24, v2
	v_mov_b32_e32 v25, v2
	s_branch .LBB0_1572
